# LDS-read/MFMA software pipelining extended: first-tile and tail QK^T blocks of every attention loop, the small-block loops and the GLA output unit's MFMA sections (rolling fragment buffers in dead reg
# speedup vs baseline: 1.0082x; 1.0010x over previous
.LBB0_966:
	s_andn2_b64 vcc, exec, s[28:29]
	s_cbranch_vccnz .LBB0_957
	ds_read_b128 v[2:5], v235 offset:32768
	ds_read_b128 v[98:101], v229
	ds_read_b128 v[102:105], v229 offset:32
	ds_read_b128 v[106:109], v229 offset:64
	ds_read_b128 v[110:113], v229 offset:96
	ds_read_b128 v[82:85], v229 offset:128
	ds_read_b128 v[6:9], v235 offset:40960
	ds_read_b128 v[86:89], v229 offset:160
	ds_read_b128 v[90:93], v229 offset:192
	ds_read_b128 v[94:97], v229 offset:224
	s_add_i32 s2, s30, 63
	s_waitcnt lgkmcnt(5)
	v_mfma_f32_32x32x16_bf16 v[98:113], v[2:5], v[114:117], v[98:113]
	ds_read_b128 v[2:5], v236 offset:32768
	s_cmp_le_i32 s2, s31
	s_waitcnt lgkmcnt(1)
	v_mfma_f32_32x32x16_bf16 v[82:97], v[6:9], v[114:117], v[82:97]
	s_waitcnt lgkmcnt(0)
	v_mfma_f32_32x32x16_bf16 v[98:113], v[2:5], v[118:121], v[98:113]
	ds_read_b128 v[2:5], v236 offset:40960
	ds_read_b128 v[6:9], v237 offset:32768
	ds_read_b128 v[10:13], v237 offset:40960
	ds_read_b128 v[240:243], v238 offset:32768
	s_waitcnt lgkmcnt(3)
	v_mfma_f32_32x32x16_bf16 v[82:97], v[2:5], v[118:121], v[82:97]
	ds_read_b128 v[2:5], v238 offset:40960
	s_waitcnt lgkmcnt(3)
	v_mfma_f32_32x32x16_bf16 v[98:113], v[6:9], v[122:125], v[98:113]
	ds_read_b128 v[6:9], v235 offset:32896
	s_waitcnt lgkmcnt(3)
	v_mfma_f32_32x32x16_bf16 v[82:97], v[10:13], v[122:125], v[82:97]
	ds_read_b128 v[10:13], v235 offset:41088
	s_waitcnt lgkmcnt(3)
	v_mfma_f32_32x32x16_bf16 v[98:113], v[240:243], v[126:129], v[98:113]
	ds_read_b128 v[240:243], v236 offset:32896
	s_waitcnt lgkmcnt(3)
	v_mfma_f32_32x32x16_bf16 v[82:97], v[2:5], v[126:129], v[82:97]
	ds_read_b128 v[2:5], v236 offset:41088
	s_waitcnt lgkmcnt(3)
	v_mfma_f32_32x32x16_bf16 v[98:113], v[6:9], v[130:133], v[98:113]
	ds_read_b128 v[6:9], v237 offset:32896
	s_waitcnt lgkmcnt(3)
	v_mfma_f32_32x32x16_bf16 v[82:97], v[10:13], v[130:133], v[82:97]
	ds_read_b128 v[10:13], v237 offset:41088
	s_waitcnt lgkmcnt(3)
	v_mfma_f32_32x32x16_bf16 v[98:113], v[240:243], v[134:137], v[98:113]
	ds_read_b128 v[240:243], v238 offset:32896
	s_waitcnt lgkmcnt(3)
	v_mfma_f32_32x32x16_bf16 v[82:97], v[2:5], v[134:137], v[82:97]
	ds_read_b128 v[2:5], v238 offset:41088
	s_waitcnt lgkmcnt(3)
	v_mfma_f32_32x32x16_bf16 v[98:113], v[6:9], v[138:141], v[98:113]
	s_waitcnt lgkmcnt(2)
	v_mfma_f32_32x32x16_bf16 v[82:97], v[10:13], v[138:141], v[82:97]
	s_waitcnt lgkmcnt(1)
	v_mfma_f32_32x32x16_bf16 v[98:113], v[240:243], v[142:145], v[98:113]
	s_waitcnt lgkmcnt(0)
	v_mfma_f32_32x32x16_bf16 v[82:97], v[2:5], v[142:145], v[82:97]
	s_cbranch_scc1 .LBB0_969
	v_add_u32_e32 v0, 0x4000003b, v230
	v_cmp_gt_u32_e32 vcc, 2.0, v0
	v_add_u32_e32 v0, 27, v230
	s_nop 4
	v_cndmask_b32_e32 v98, v205, v98, vcc
	v_cmp_lt_u32_e32 vcc, s71, v0
	v_add_u32_e32 v0, 58, v230
	s_nop 0
	v_cndmask_b32_e32 v82, v205, v82, vcc
	v_cmp_lt_u32_e32 vcc, s71, v0
	v_add_u32_e32 v0, 26, v230
	s_nop 0
	v_cndmask_b32_e32 v99, v205, v99, vcc
	v_cmp_lt_u32_e32 vcc, s71, v0
	v_add_u32_e32 v0, 57, v230
	s_nop 0
	v_cndmask_b32_e32 v83, v205, v83, vcc
	v_cmp_lt_u32_e32 vcc, s71, v0
	v_add_u32_e32 v0, 25, v230
	s_nop 0
	v_cndmask_b32_e32 v100, v205, v100, vcc
	v_cmp_lt_u32_e32 vcc, s71, v0
	v_add_u32_e32 v0, 56, v230
	s_nop 0
	v_cndmask_b32_e32 v84, v205, v84, vcc
	v_cmp_lt_u32_e32 vcc, s71, v0
	v_add_u32_e32 v0, 24, v230
	s_nop 0
	v_cndmask_b32_e32 v101, v205, v101, vcc
	v_cmp_lt_u32_e32 vcc, s71, v0
	v_add_u32_e32 v0, 51, v230
	s_nop 0
	v_cndmask_b32_e32 v85, v205, v85, vcc
	v_cmp_lt_u32_e32 vcc, s71, v0
	v_add_u32_e32 v0, 19, v230
	s_nop 0
	v_cndmask_b32_e32 v102, v205, v102, vcc
	v_cmp_lt_u32_e32 vcc, s71, v0
	v_add_u32_e32 v0, 50, v230
	s_nop 0
	v_cndmask_b32_e32 v86, v205, v86, vcc
	v_cmp_lt_u32_e32 vcc, s71, v0
	v_add_u32_e32 v0, 18, v230
	s_nop 0
	v_cndmask_b32_e32 v103, v205, v103, vcc
	v_cmp_lt_u32_e32 vcc, s71, v0
	v_add_u32_e32 v0, 49, v230
	s_nop 0
	v_cndmask_b32_e32 v87, v205, v87, vcc
	v_cmp_lt_u32_e32 vcc, s71, v0
	v_add_u32_e32 v0, 17, v230
	s_nop 0
	v_cndmask_b32_e32 v104, v205, v104, vcc
	v_cmp_lt_u32_e32 vcc, s71, v0
	v_add_u32_e32 v0, 48, v230
	s_nop 0
	v_cndmask_b32_e32 v88, v205, v88, vcc
	v_cmp_lt_u32_e32 vcc, s71, v0
	v_add_u32_e32 v0, 16, v230
	s_nop 0
	v_cndmask_b32_e32 v105, v205, v105, vcc
	v_cmp_lt_u32_e32 vcc, s71, v0
	v_add_u32_e32 v0, 43, v230
	s_nop 0
	v_cndmask_b32_e32 v89, v205, v89, vcc
	v_cmp_lt_u32_e32 vcc, s71, v0
	v_add_u32_e32 v0, 11, v230
	s_nop 0
	v_cndmask_b32_e32 v106, v205, v106, vcc
	v_cmp_lt_u32_e32 vcc, s71, v0
	v_add_u32_e32 v0, 42, v230
	s_nop 0
	v_cndmask_b32_e32 v90, v205, v90, vcc
	v_cmp_lt_u32_e32 vcc, s71, v0
	v_add_u32_e32 v0, 10, v230
	s_nop 0
	v_cndmask_b32_e32 v107, v205, v107, vcc
	v_cmp_lt_u32_e32 vcc, s71, v0
	v_add_u32_e32 v0, 41, v230
	s_nop 0
	v_cndmask_b32_e32 v91, v205, v91, vcc
	v_cmp_lt_u32_e32 vcc, s71, v0
	v_add_u32_e32 v0, 9, v230
	s_nop 0
	v_cndmask_b32_e32 v108, v205, v108, vcc
	v_cmp_lt_u32_e32 vcc, s71, v0
	v_add_u32_e32 v0, 40, v230
	s_nop 0
	v_cndmask_b32_e32 v92, v205, v92, vcc
	v_cmp_lt_u32_e32 vcc, s71, v0
	v_add_u32_e32 v0, 8, v230
	s_nop 0
	v_cndmask_b32_e32 v109, v205, v109, vcc
	v_cmp_lt_u32_e32 vcc, s71, v0
	v_add_u32_e32 v0, 35, v230
	s_nop 0
	v_cndmask_b32_e32 v93, v205, v93, vcc
	v_cmp_lt_u32_e32 vcc, s71, v0
	v_add_u32_e32 v0, 3, v230
	s_nop 0
	v_cndmask_b32_e32 v110, v205, v110, vcc
	v_cmp_lt_u32_e32 vcc, s71, v0
	v_add_u32_e32 v0, 34, v230
	s_nop 0
	v_cndmask_b32_e32 v94, v205, v94, vcc
	v_cmp_lt_u32_e32 vcc, s71, v0
	v_add_u32_e32 v0, 2, v230
	s_nop 0
	v_cndmask_b32_e32 v111, v205, v111, vcc
	v_cmp_lt_u32_e32 vcc, s71, v0
	v_add_u32_e32 v0, 33, v230
	s_nop 0
	v_cndmask_b32_e32 v95, v205, v95, vcc
	v_cmp_lt_u32_e32 vcc, s71, v0
	v_add_u32_e32 v0, 1, v230
	s_nop 0
	v_cndmask_b32_e32 v112, v205, v112, vcc
	v_cmp_lt_u32_e32 vcc, s71, v0
	v_add_u32_e32 v0, 32, v230
	s_nop 0
	v_cndmask_b32_e32 v96, v205, v96, vcc
	v_cmp_lt_u32_e32 vcc, s71, v0
	s_nop 1
	v_cndmask_b32_e32 v113, v205, v113, vcc
	v_cmp_lt_u32_e32 vcc, s71, v230
	s_nop 1
	v_cndmask_b32_e32 v97, v205, v97, vcc

.LBB0_1471:
	s_ashr_i32 s2, s7, 1
	s_and_b32 s28, s2, 0xffffffe0
	s_cmp_lt_i32 s28, s97
	s_cselect_b64 s[30:31], -1, 0
	s_lshl_b32 s34, s95, 15
	s_add_i32 s2, s34, 0
	v_bfe_u32 v49, v210, 5, 1
	s_add_i32 s2, s2, 0x10800
	v_and_b32_e32 v211, 31, v210
	v_lshl_add_u32 v221, v49, 4, s2
	s_cmp_ge_i32 s28, s97
	v_lshlrev_b32_e32 v198, 4, v49
	s_cbranch_scc1 .LBB0_1473
	v_lshlrev_b32_e32 v11, 4, v211
	v_lshlrev_b32_e32 v10, 8, v211
	v_bitop3_b32 v2, v198, v11, s44 bitop3:0x78
	v_add3_u32 v12, 0, v2, v10
	v_lshl_add_u32 v1, s6, 2, v221
	ds_read_b128 v[2:5], v12 offset:32768
	ds_read_b128 v[32:35], v1
	ds_read_b128 v[36:39], v1 offset:32
	ds_read_b128 v[40:43], v1 offset:64
	ds_read_b128 v[44:47], v1 offset:96
	ds_read_b128 v[16:19], v1 offset:128
	ds_read_b128 v[6:9], v12 offset:40960
	ds_read_b128 v[20:23], v1 offset:160
	ds_read_b128 v[24:27], v1 offset:192
	ds_read_b128 v[28:31], v1 offset:224
	v_and_b32_e32 v1, 0x70, v11
	s_waitcnt lgkmcnt(5)
	v_mfma_f32_32x32x16_bf16 v[32:47], v[2:5], v[172:175], v[32:47]
	v_bitop3_b32 v2, v198, v1, 32 bitop3:0x36
	v_add3_u32 v11, 0, v2, v10
	ds_read_b128 v[2:5], v11 offset:32768
	s_waitcnt lgkmcnt(1)
	v_mfma_f32_32x32x16_bf16 v[16:31], v[6:9], v[172:175], v[16:31]
	v_bitop3_b32 v6, v198, v1, 64 bitop3:0x36
	v_add3_u32 v6, 0, v6, v10
	v_bitop3_b32 v1, v198, v1, s45 bitop3:0x36
	v_add3_u32 v1, 0, v1, v10
	s_waitcnt lgkmcnt(0)
	v_mfma_f32_32x32x16_bf16 v[32:47], v[2:5], v[168:171], v[32:47]
	ds_read_b128 v[2:5], v11 offset:40960
	ds_read_b128 v[50:53], v6 offset:32768
	ds_read_b128 v[54:57], v6 offset:40960
	ds_read_b128 v[58:61], v1 offset:32768
	s_waitcnt lgkmcnt(3)
	v_mfma_f32_32x32x16_bf16 v[16:31], v[2:5], v[168:171], v[16:31]
	ds_read_b128 v[2:5], v1 offset:40960
	s_waitcnt lgkmcnt(3)
	v_mfma_f32_32x32x16_bf16 v[32:47], v[50:53], v[164:167], v[32:47]
	ds_read_b128 v[50:53], v12 offset:32896
	s_waitcnt lgkmcnt(3)
	v_mfma_f32_32x32x16_bf16 v[16:31], v[54:57], v[164:167], v[16:31]
	ds_read_b128 v[54:57], v12 offset:41088
	s_waitcnt lgkmcnt(3)
	v_mfma_f32_32x32x16_bf16 v[32:47], v[58:61], v[160:163], v[32:47]
	ds_read_b128 v[58:61], v11 offset:32896
	s_waitcnt lgkmcnt(3)
	v_mfma_f32_32x32x16_bf16 v[16:31], v[2:5], v[160:163], v[16:31]
	ds_read_b128 v[2:5], v11 offset:41088
	s_waitcnt lgkmcnt(3)
	v_mfma_f32_32x32x16_bf16 v[32:47], v[50:53], v[156:159], v[32:47]
	ds_read_b128 v[50:53], v6 offset:32896
	s_waitcnt lgkmcnt(3)
	v_mfma_f32_32x32x16_bf16 v[16:31], v[54:57], v[156:159], v[16:31]
	ds_read_b128 v[54:57], v6 offset:41088
	s_waitcnt lgkmcnt(3)
	v_mfma_f32_32x32x16_bf16 v[32:47], v[58:61], v[152:155], v[32:47]
	ds_read_b128 v[58:61], v1 offset:32896
	s_waitcnt lgkmcnt(3)
	v_mfma_f32_32x32x16_bf16 v[16:31], v[2:5], v[152:155], v[16:31]
	ds_read_b128 v[2:5], v1 offset:41088
	s_waitcnt lgkmcnt(3)
	v_mfma_f32_32x32x16_bf16 v[32:47], v[50:53], v[148:151], v[32:47]
	s_waitcnt lgkmcnt(2)
	v_mfma_f32_32x32x16_bf16 v[16:31], v[54:57], v[148:151], v[16:31]
	s_waitcnt lgkmcnt(1)
	v_mfma_f32_32x32x16_bf16 v[32:47], v[58:61], v[144:147], v[32:47]
	s_waitcnt lgkmcnt(0)
	v_mfma_f32_32x32x16_bf16 v[16:31], v[2:5], v[144:147], v[16:31]
	s_branch .LBB0_1474

.LBB0_1508:
	s_bitcmp0_b32 s37, 0
	s_cselect_b64 s[4:5], -1, 0
	v_cndmask_b32_e64 v1, 0, 1, s[30:31]
	s_and_b64 vcc, exec, s[4:5]
	v_cmp_ne_u32_e64 s[2:3], 1, v1
	s_cbranch_vccz .LBB0_1513
	s_and_b64 vcc, exec, s[2:3]
	s_cbranch_vccnz .LBB0_1511
	v_lshl_add_u32 v1, s29, 8, v221
	v_add_u32_e32 v2, 0xffffff00, v1
	v_add_u32_e32 v6, 0xffffff40, v1
	v_subrev_u32_e32 v13, 64, v1
	v_add_u32_e32 v3, 0xffffff80, v1
	ds_read_b128 v[80:83], v2
	ds_read_b128 v[96:99], v3
	ds_read_b128 v[88:91], v6
	ds_read_b128 v[104:107], v13
	v_add_u32_e32 v6, 0xffffff60, v1
	v_add_u32_e32 v2, 0xffffff20, v1
	v_lshlrev_b32_e32 v11, 4, v211
	ds_read_b128 v[92:95], v6
	v_add_u32_e32 v6, 0xffffffa0, v1
	v_subrev_u32_e32 v1, 32, v1
	ds_read_b128 v[84:87], v2
	ds_read_b128 v[108:111], v1
	v_lshlrev_b32_e32 v10, 8, v211
	v_bitop3_b32 v2, v198, v11, s44 bitop3:0x78
	v_add3_u32 v12, 0, v2, v10
	ds_read_b128 v[2:5], v12 offset:49152
	v_and_b32_e32 v1, 0x70, v11
	s_waitcnt lgkmcnt(0)
	v_mfma_f32_32x32x16_bf16 v[80:95], v[2:5], v[172:175], v[80:95]
	v_bitop3_b32 v2, v198, v1, 32 bitop3:0x36
	v_add3_u32 v11, 0, v2, v10
	ds_read_b128 v[100:103], v6
	ds_read_b128 v[2:5], v11 offset:49152
	ds_read_b128 v[6:9], v12 offset:57344
	s_waitcnt lgkmcnt(1)
	v_mfma_f32_32x32x16_bf16 v[80:95], v[2:5], v[168:171], v[80:95]
	ds_read_b128 v[2:5], v11 offset:57344
	s_waitcnt lgkmcnt(1)
	v_mfma_f32_32x32x16_bf16 v[96:111], v[6:9], v[172:175], v[96:111]
	v_bitop3_b32 v6, v198, v1, 64 bitop3:0x36
	v_add3_u32 v6, 0, v6, v10
	v_bitop3_b32 v1, v198, v1, s45 bitop3:0x36
	v_add3_u32 v1, 0, v1, v10
	s_waitcnt lgkmcnt(0)
	v_mfma_f32_32x32x16_bf16 v[96:111], v[2:5], v[168:171], v[96:111]
	ds_read_b128 v[2:5], v6 offset:49152
	ds_read_b128 v[112:115], v6 offset:57344
	ds_read_b128 v[116:119], v1 offset:49152
	ds_read_b128 v[120:123], v1 offset:57344
	s_waitcnt lgkmcnt(3)
	v_mfma_f32_32x32x16_bf16 v[80:95], v[2:5], v[164:167], v[80:95]
	ds_read_b128 v[2:5], v12 offset:49280
	s_waitcnt lgkmcnt(3)
	v_mfma_f32_32x32x16_bf16 v[96:111], v[112:115], v[164:167], v[96:111]
	ds_read_b128 v[112:115], v12 offset:57472
	s_waitcnt lgkmcnt(3)
	v_mfma_f32_32x32x16_bf16 v[80:95], v[116:119], v[160:163], v[80:95]
	ds_read_b128 v[116:119], v11 offset:49280
	s_waitcnt lgkmcnt(3)
	v_mfma_f32_32x32x16_bf16 v[96:111], v[120:123], v[160:163], v[96:111]
	ds_read_b128 v[120:123], v11 offset:57472
	s_waitcnt lgkmcnt(3)
	v_mfma_f32_32x32x16_bf16 v[80:95], v[2:5], v[156:159], v[80:95]
	ds_read_b128 v[2:5], v6 offset:49280
	s_waitcnt lgkmcnt(3)
	v_mfma_f32_32x32x16_bf16 v[96:111], v[112:115], v[156:159], v[96:111]
	ds_read_b128 v[112:115], v6 offset:57472
	s_waitcnt lgkmcnt(3)
	v_mfma_f32_32x32x16_bf16 v[80:95], v[116:119], v[152:155], v[80:95]
	ds_read_b128 v[116:119], v1 offset:49280
	s_waitcnt lgkmcnt(3)
	v_mfma_f32_32x32x16_bf16 v[96:111], v[120:123], v[152:155], v[96:111]
	ds_read_b128 v[120:123], v1 offset:57472
	s_waitcnt lgkmcnt(3)
	v_mfma_f32_32x32x16_bf16 v[80:95], v[2:5], v[148:151], v[80:95]
	s_waitcnt lgkmcnt(2)
	v_mfma_f32_32x32x16_bf16 v[96:111], v[112:115], v[148:151], v[96:111]
	s_waitcnt lgkmcnt(1)
	v_mfma_f32_32x32x16_bf16 v[80:95], v[116:119], v[144:147], v[80:95]
	s_waitcnt lgkmcnt(0)
	v_mfma_f32_32x32x16_bf16 v[96:111], v[120:123], v[144:147], v[96:111]
	s_branch .LBB0_1512

.LBB0_2525:
	s_andn2_b64 vcc, exec, s[22:23]
	s_cbranch_vccnz .LBB0_2516
	ds_read_b128 v[2:5], v235 offset:32768
	ds_read_b128 v[98:101], v229
	ds_read_b128 v[102:105], v229 offset:32
	ds_read_b128 v[106:109], v229 offset:64
	ds_read_b128 v[110:113], v229 offset:96
	ds_read_b128 v[82:85], v229 offset:128
	ds_read_b128 v[6:9], v235 offset:40960
	ds_read_b128 v[86:89], v229 offset:160
	ds_read_b128 v[90:93], v229 offset:192
	ds_read_b128 v[94:97], v229 offset:224
	s_add_i32 s20, s26, 63
	s_waitcnt lgkmcnt(5)
	v_mfma_f32_32x32x16_bf16 v[98:113], v[2:5], v[114:117], v[98:113]
	ds_read_b128 v[2:5], v236 offset:32768
	s_cmp_le_i32 s20, s27
	s_waitcnt lgkmcnt(1)
	v_mfma_f32_32x32x16_bf16 v[82:97], v[6:9], v[114:117], v[82:97]
	s_waitcnt lgkmcnt(0)
	v_mfma_f32_32x32x16_bf16 v[98:113], v[2:5], v[118:121], v[98:113]
	ds_read_b128 v[2:5], v236 offset:40960
	ds_read_b128 v[6:9], v237 offset:32768
	ds_read_b128 v[10:13], v237 offset:40960
	ds_read_b128 v[240:243], v238 offset:32768
	s_waitcnt lgkmcnt(3)
	v_mfma_f32_32x32x16_bf16 v[82:97], v[2:5], v[118:121], v[82:97]
	ds_read_b128 v[2:5], v238 offset:40960
	s_waitcnt lgkmcnt(3)
	v_mfma_f32_32x32x16_bf16 v[98:113], v[6:9], v[122:125], v[98:113]
	ds_read_b128 v[6:9], v235 offset:32896
	s_waitcnt lgkmcnt(3)
	v_mfma_f32_32x32x16_bf16 v[82:97], v[10:13], v[122:125], v[82:97]
	ds_read_b128 v[10:13], v235 offset:41088
	s_waitcnt lgkmcnt(3)
	v_mfma_f32_32x32x16_bf16 v[98:113], v[240:243], v[126:129], v[98:113]
	ds_read_b128 v[240:243], v236 offset:32896
	s_waitcnt lgkmcnt(3)
	v_mfma_f32_32x32x16_bf16 v[82:97], v[2:5], v[126:129], v[82:97]
	ds_read_b128 v[2:5], v236 offset:41088
	s_waitcnt lgkmcnt(3)
	v_mfma_f32_32x32x16_bf16 v[98:113], v[6:9], v[130:133], v[98:113]
	ds_read_b128 v[6:9], v237 offset:32896
	s_waitcnt lgkmcnt(3)
	v_mfma_f32_32x32x16_bf16 v[82:97], v[10:13], v[130:133], v[82:97]
	ds_read_b128 v[10:13], v237 offset:41088
	s_waitcnt lgkmcnt(3)
	v_mfma_f32_32x32x16_bf16 v[98:113], v[240:243], v[134:137], v[98:113]
	ds_read_b128 v[240:243], v238 offset:32896
	s_waitcnt lgkmcnt(3)
	v_mfma_f32_32x32x16_bf16 v[82:97], v[2:5], v[134:137], v[82:97]
	ds_read_b128 v[2:5], v238 offset:41088
	s_waitcnt lgkmcnt(3)
	v_mfma_f32_32x32x16_bf16 v[98:113], v[6:9], v[138:141], v[98:113]
	s_waitcnt lgkmcnt(2)
	v_mfma_f32_32x32x16_bf16 v[82:97], v[10:13], v[138:141], v[82:97]
	s_waitcnt lgkmcnt(1)
	v_mfma_f32_32x32x16_bf16 v[98:113], v[240:243], v[142:145], v[98:113]
	s_waitcnt lgkmcnt(0)
	v_mfma_f32_32x32x16_bf16 v[82:97], v[2:5], v[142:145], v[82:97]
	s_cbranch_scc1 .LBB0_2528
	v_add_u32_e32 v0, 0x4000003b, v230
	v_cmp_gt_u32_e32 vcc, 2.0, v0
	v_add_u32_e32 v0, 27, v230
	s_nop 4
	v_cndmask_b32_e32 v98, v205, v98, vcc
	v_cmp_lt_u32_e32 vcc, s82, v0
	v_add_u32_e32 v0, 58, v230
	s_nop 0
	v_cndmask_b32_e32 v82, v205, v82, vcc
	v_cmp_lt_u32_e32 vcc, s82, v0
	v_add_u32_e32 v0, 26, v230
	s_nop 0
	v_cndmask_b32_e32 v99, v205, v99, vcc
	v_cmp_lt_u32_e32 vcc, s82, v0
	v_add_u32_e32 v0, 57, v230
	s_nop 0
	v_cndmask_b32_e32 v83, v205, v83, vcc
	v_cmp_lt_u32_e32 vcc, s82, v0
	v_add_u32_e32 v0, 25, v230
	s_nop 0
	v_cndmask_b32_e32 v100, v205, v100, vcc
	v_cmp_lt_u32_e32 vcc, s82, v0
	v_add_u32_e32 v0, 56, v230
	s_nop 0
	v_cndmask_b32_e32 v84, v205, v84, vcc
	v_cmp_lt_u32_e32 vcc, s82, v0
	v_add_u32_e32 v0, 24, v230
	s_nop 0
	v_cndmask_b32_e32 v101, v205, v101, vcc
	v_cmp_lt_u32_e32 vcc, s82, v0
	v_add_u32_e32 v0, 51, v230
	s_nop 0
	v_cndmask_b32_e32 v85, v205, v85, vcc
	v_cmp_lt_u32_e32 vcc, s82, v0
	v_add_u32_e32 v0, 19, v230
	s_nop 0
	v_cndmask_b32_e32 v102, v205, v102, vcc
	v_cmp_lt_u32_e32 vcc, s82, v0
	v_add_u32_e32 v0, 50, v230
	s_nop 0
	v_cndmask_b32_e32 v86, v205, v86, vcc
	v_cmp_lt_u32_e32 vcc, s82, v0
	v_add_u32_e32 v0, 18, v230
	s_nop 0
	v_cndmask_b32_e32 v103, v205, v103, vcc
	v_cmp_lt_u32_e32 vcc, s82, v0
	v_add_u32_e32 v0, 49, v230
	s_nop 0
	v_cndmask_b32_e32 v87, v205, v87, vcc
	v_cmp_lt_u32_e32 vcc, s82, v0
	v_add_u32_e32 v0, 17, v230
	s_nop 0
	v_cndmask_b32_e32 v104, v205, v104, vcc
	v_cmp_lt_u32_e32 vcc, s82, v0
	v_add_u32_e32 v0, 48, v230
	s_nop 0
	v_cndmask_b32_e32 v88, v205, v88, vcc
	v_cmp_lt_u32_e32 vcc, s82, v0
	v_add_u32_e32 v0, 16, v230
	s_nop 0
	v_cndmask_b32_e32 v105, v205, v105, vcc
	v_cmp_lt_u32_e32 vcc, s82, v0
	v_add_u32_e32 v0, 43, v230
	s_nop 0
	v_cndmask_b32_e32 v89, v205, v89, vcc
	v_cmp_lt_u32_e32 vcc, s82, v0
	v_add_u32_e32 v0, 11, v230
	s_nop 0
	v_cndmask_b32_e32 v106, v205, v106, vcc
	v_cmp_lt_u32_e32 vcc, s82, v0
	v_add_u32_e32 v0, 42, v230
	s_nop 0
	v_cndmask_b32_e32 v90, v205, v90, vcc
	v_cmp_lt_u32_e32 vcc, s82, v0
	v_add_u32_e32 v0, 10, v230
	s_nop 0
	v_cndmask_b32_e32 v107, v205, v107, vcc
	v_cmp_lt_u32_e32 vcc, s82, v0
	v_add_u32_e32 v0, 41, v230
	s_nop 0
	v_cndmask_b32_e32 v91, v205, v91, vcc
	v_cmp_lt_u32_e32 vcc, s82, v0
	v_add_u32_e32 v0, 9, v230
	s_nop 0
	v_cndmask_b32_e32 v108, v205, v108, vcc
	v_cmp_lt_u32_e32 vcc, s82, v0
	v_add_u32_e32 v0, 40, v230
	s_nop 0
	v_cndmask_b32_e32 v92, v205, v92, vcc
	v_cmp_lt_u32_e32 vcc, s82, v0
	v_add_u32_e32 v0, 8, v230
	s_nop 0
	v_cndmask_b32_e32 v109, v205, v109, vcc
	v_cmp_lt_u32_e32 vcc, s82, v0
	v_add_u32_e32 v0, 35, v230
	s_nop 0
	v_cndmask_b32_e32 v93, v205, v93, vcc
	v_cmp_lt_u32_e32 vcc, s82, v0
	v_add_u32_e32 v0, 3, v230
	s_nop 0
	v_cndmask_b32_e32 v110, v205, v110, vcc
	v_cmp_lt_u32_e32 vcc, s82, v0
	v_add_u32_e32 v0, 34, v230
	s_nop 0
	v_cndmask_b32_e32 v94, v205, v94, vcc
	v_cmp_lt_u32_e32 vcc, s82, v0
	v_add_u32_e32 v0, 2, v230
	s_nop 0
	v_cndmask_b32_e32 v111, v205, v111, vcc
	v_cmp_lt_u32_e32 vcc, s82, v0
	v_add_u32_e32 v0, 33, v230
	s_nop 0
	v_cndmask_b32_e32 v95, v205, v95, vcc
	v_cmp_lt_u32_e32 vcc, s82, v0
	v_add_u32_e32 v0, 1, v230
	s_nop 0
	v_cndmask_b32_e32 v112, v205, v112, vcc
	v_cmp_lt_u32_e32 vcc, s82, v0
	v_add_u32_e32 v0, 32, v230
	s_nop 0
	v_cndmask_b32_e32 v96, v205, v96, vcc
	v_cmp_lt_u32_e32 vcc, s82, v0
	s_nop 1
	v_cndmask_b32_e32 v113, v205, v113, vcc
	v_cmp_lt_u32_e32 vcc, s82, v230
	s_nop 1
	v_cndmask_b32_e32 v97, v205, v97, vcc

.LBB0_2843:
	s_ashr_i32 s23, s39, 1
	s_and_b32 s74, s23, 0xffffffe0
	s_cmpk_lt_i32 s74, 0x100
	s_cselect_b64 s[20:21], -1, 0
	s_lshl_b32 s40, s6, 15
	s_add_i32 s27, s40, 0
	v_bfe_u32 v49, v210, 5, 1
	s_add_i32 s27, s27, 0x10800
	v_and_b32_e32 v211, 31, v210
	v_lshl_add_u32 v221, v49, 4, s27
	s_cmpk_gt_i32 s74, 0xff
	v_lshlrev_b32_e32 v198, 4, v49
	s_cbranch_scc1 .LBB0_2845
	v_lshlrev_b32_e32 v11, 4, v211
	v_lshlrev_b32_e32 v10, 8, v211
	v_bitop3_b32 v2, v198, v11, s5 bitop3:0x78
	v_add3_u32 v12, 0, v2, v10
	v_lshl_add_u32 v1, s38, 2, v221
	ds_read_b128 v[2:5], v12 offset:32768
	ds_read_b128 v[32:35], v1
	ds_read_b128 v[36:39], v1 offset:32
	ds_read_b128 v[40:43], v1 offset:64
	ds_read_b128 v[44:47], v1 offset:96
	ds_read_b128 v[16:19], v1 offset:128
	ds_read_b128 v[6:9], v12 offset:40960
	ds_read_b128 v[20:23], v1 offset:160
	ds_read_b128 v[24:27], v1 offset:192
	ds_read_b128 v[28:31], v1 offset:224
	v_and_b32_e32 v1, 0x70, v11
	s_waitcnt vmcnt(7) lgkmcnt(5)
	v_mfma_f32_32x32x16_bf16 v[32:47], v[2:5], v[172:175], v[32:47]
	v_bitop3_b32 v2, v198, v1, 32 bitop3:0x36
	v_add3_u32 v11, 0, v2, v10
	ds_read_b128 v[2:5], v11 offset:32768
	s_waitcnt lgkmcnt(1)
	v_mfma_f32_32x32x16_bf16 v[16:31], v[6:9], v[172:175], v[16:31]
	v_bitop3_b32 v6, v198, v1, 64 bitop3:0x36
	v_add3_u32 v6, 0, v6, v10
	v_bitop3_b32 v1, v198, v1, s93 bitop3:0x36
	v_add3_u32 v1, 0, v1, v10
	s_waitcnt vmcnt(6) lgkmcnt(0)
	v_mfma_f32_32x32x16_bf16 v[32:47], v[2:5], v[168:171], v[32:47]
	ds_read_b128 v[2:5], v11 offset:40960
	ds_read_b128 v[50:53], v6 offset:32768
	ds_read_b128 v[54:57], v6 offset:40960
	ds_read_b128 v[58:61], v1 offset:32768
	s_waitcnt lgkmcnt(3)
	v_mfma_f32_32x32x16_bf16 v[16:31], v[2:5], v[168:171], v[16:31]
	ds_read_b128 v[2:5], v1 offset:40960
	s_waitcnt vmcnt(5) lgkmcnt(3)
	v_mfma_f32_32x32x16_bf16 v[32:47], v[50:53], v[164:167], v[32:47]
	ds_read_b128 v[50:53], v12 offset:32896
	s_waitcnt lgkmcnt(3)
	v_mfma_f32_32x32x16_bf16 v[16:31], v[54:57], v[164:167], v[16:31]
	ds_read_b128 v[54:57], v12 offset:41088
	s_waitcnt vmcnt(4) lgkmcnt(3)
	v_mfma_f32_32x32x16_bf16 v[32:47], v[58:61], v[160:163], v[32:47]
	ds_read_b128 v[58:61], v11 offset:32896
	s_waitcnt lgkmcnt(3)
	v_mfma_f32_32x32x16_bf16 v[16:31], v[2:5], v[160:163], v[16:31]
	ds_read_b128 v[2:5], v11 offset:41088
	s_waitcnt vmcnt(3) lgkmcnt(3)
	v_mfma_f32_32x32x16_bf16 v[32:47], v[50:53], v[156:159], v[32:47]
	ds_read_b128 v[50:53], v6 offset:32896
	s_waitcnt lgkmcnt(3)
	v_mfma_f32_32x32x16_bf16 v[16:31], v[54:57], v[156:159], v[16:31]
	ds_read_b128 v[54:57], v6 offset:41088
	s_waitcnt vmcnt(2) lgkmcnt(3)
	v_mfma_f32_32x32x16_bf16 v[32:47], v[58:61], v[152:155], v[32:47]
	ds_read_b128 v[58:61], v1 offset:32896
	s_waitcnt lgkmcnt(3)
	v_mfma_f32_32x32x16_bf16 v[16:31], v[2:5], v[152:155], v[16:31]
	ds_read_b128 v[2:5], v1 offset:41088
	s_waitcnt vmcnt(1) lgkmcnt(3)
	v_mfma_f32_32x32x16_bf16 v[32:47], v[50:53], v[148:151], v[32:47]
	s_waitcnt lgkmcnt(2)
	v_mfma_f32_32x32x16_bf16 v[16:31], v[54:57], v[148:151], v[16:31]
	s_waitcnt vmcnt(0) lgkmcnt(1)
	v_mfma_f32_32x32x16_bf16 v[32:47], v[58:61], v[144:147], v[32:47]
	s_waitcnt lgkmcnt(0)
	v_mfma_f32_32x32x16_bf16 v[16:31], v[2:5], v[144:147], v[16:31]
	s_branch .LBB0_2846

.LBB0_2880:
	s_bitcmp0_b32 s28, 0
	s_cselect_b64 s[0:1], -1, 0
	v_cndmask_b32_e64 v1, 0, 1, s[20:21]
	s_and_b64 vcc, exec, s[0:1]
	v_cmp_ne_u32_e64 s[36:37], 1, v1
	s_cbranch_vccz .LBB0_2885
	s_and_b64 vcc, exec, s[36:37]
	s_cbranch_vccnz .LBB0_2883
	v_lshl_add_u32 v1, s22, 8, v221
	v_add_u32_e32 v2, 0xffffff00, v1
	v_add_u32_e32 v6, 0xffffff40, v1
	v_subrev_u32_e32 v13, 64, v1
	v_add_u32_e32 v3, 0xffffff80, v1
	ds_read_b128 v[80:83], v2
	ds_read_b128 v[96:99], v3
	ds_read_b128 v[88:91], v6
	ds_read_b128 v[104:107], v13
	v_add_u32_e32 v6, 0xffffff60, v1
	v_add_u32_e32 v2, 0xffffff20, v1
	v_lshlrev_b32_e32 v11, 4, v211
	ds_read_b128 v[92:95], v6
	v_add_u32_e32 v6, 0xffffffa0, v1
	v_subrev_u32_e32 v1, 32, v1
	ds_read_b128 v[84:87], v2
	ds_read_b128 v[108:111], v1
	v_lshlrev_b32_e32 v10, 8, v211
	v_bitop3_b32 v2, v198, v11, s5 bitop3:0x78
	v_add3_u32 v12, 0, v2, v10
	ds_read_b128 v[2:5], v12 offset:49152
	v_and_b32_e32 v1, 0x70, v11
	s_waitcnt vmcnt(7) lgkmcnt(0)
	v_mfma_f32_32x32x16_bf16 v[80:95], v[2:5], v[172:175], v[80:95]
	v_bitop3_b32 v2, v198, v1, 32 bitop3:0x36
	v_add3_u32 v11, 0, v2, v10
	ds_read_b128 v[100:103], v6
	ds_read_b128 v[2:5], v11 offset:49152
	ds_read_b128 v[6:9], v12 offset:57344
	s_waitcnt vmcnt(6) lgkmcnt(1)
	v_mfma_f32_32x32x16_bf16 v[80:95], v[2:5], v[168:171], v[80:95]
	ds_read_b128 v[2:5], v11 offset:57344
	s_waitcnt lgkmcnt(1)
	v_mfma_f32_32x32x16_bf16 v[96:111], v[6:9], v[172:175], v[96:111]
	v_bitop3_b32 v6, v198, v1, 64 bitop3:0x36
	v_add3_u32 v6, 0, v6, v10
	v_bitop3_b32 v1, v198, v1, s93 bitop3:0x36
	v_add3_u32 v1, 0, v1, v10
	s_waitcnt lgkmcnt(0)
	v_mfma_f32_32x32x16_bf16 v[96:111], v[2:5], v[168:171], v[96:111]
	ds_read_b128 v[2:5], v6 offset:49152
	ds_read_b128 v[112:115], v6 offset:57344
	ds_read_b128 v[116:119], v1 offset:49152
	ds_read_b128 v[120:123], v1 offset:57344
	s_waitcnt vmcnt(5) lgkmcnt(3)
	v_mfma_f32_32x32x16_bf16 v[80:95], v[2:5], v[164:167], v[80:95]
	ds_read_b128 v[2:5], v12 offset:49280
	s_waitcnt lgkmcnt(3)
	v_mfma_f32_32x32x16_bf16 v[96:111], v[112:115], v[164:167], v[96:111]
	ds_read_b128 v[112:115], v12 offset:57472
	s_waitcnt vmcnt(4) lgkmcnt(3)
	v_mfma_f32_32x32x16_bf16 v[80:95], v[116:119], v[160:163], v[80:95]
	ds_read_b128 v[116:119], v11 offset:49280
	s_waitcnt lgkmcnt(3)
	v_mfma_f32_32x32x16_bf16 v[96:111], v[120:123], v[160:163], v[96:111]
	ds_read_b128 v[120:123], v11 offset:57472
	s_waitcnt vmcnt(3) lgkmcnt(3)
	v_mfma_f32_32x32x16_bf16 v[80:95], v[2:5], v[156:159], v[80:95]
	ds_read_b128 v[2:5], v6 offset:49280
	s_waitcnt lgkmcnt(3)
	v_mfma_f32_32x32x16_bf16 v[96:111], v[112:115], v[156:159], v[96:111]
	ds_read_b128 v[112:115], v6 offset:57472
	s_waitcnt vmcnt(2) lgkmcnt(3)
	v_mfma_f32_32x32x16_bf16 v[80:95], v[116:119], v[152:155], v[80:95]
	ds_read_b128 v[116:119], v1 offset:49280
	s_waitcnt lgkmcnt(3)
	v_mfma_f32_32x32x16_bf16 v[96:111], v[120:123], v[152:155], v[96:111]
	ds_read_b128 v[120:123], v1 offset:57472
	s_waitcnt vmcnt(1) lgkmcnt(3)
	v_mfma_f32_32x32x16_bf16 v[80:95], v[2:5], v[148:151], v[80:95]
	s_waitcnt lgkmcnt(2)
	v_mfma_f32_32x32x16_bf16 v[96:111], v[112:115], v[148:151], v[96:111]
	s_waitcnt vmcnt(0) lgkmcnt(1)
	v_mfma_f32_32x32x16_bf16 v[80:95], v[116:119], v[144:147], v[80:95]
	s_waitcnt lgkmcnt(0)
	v_mfma_f32_32x32x16_bf16 v[96:111], v[120:123], v[144:147], v[96:111]
	s_branch .LBB0_2884

.LBB0_4545:
	s_ashr_i32 s23, s39, 1
	s_and_b32 s76, s23, 0xffffffe0
	s_cmpk_lt_i32 s76, 0x100
	s_cselect_b64 s[20:21], -1, 0
	s_lshl_b32 s40, s4, 15
	s_add_i32 s27, s40, 0
	v_bfe_u32 v49, v210, 5, 1
	s_add_i32 s27, s27, 0x10800
	v_and_b32_e32 v211, 31, v210
	v_lshl_add_u32 v221, v49, 4, s27
	s_cmpk_gt_i32 s76, 0xff
	v_lshlrev_b32_e32 v198, 4, v49
	s_cbranch_scc1 .LBB0_4547
	v_lshlrev_b32_e32 v11, 4, v211
	v_lshlrev_b32_e32 v10, 8, v211
	v_bitop3_b32 v2, v198, v11, s3 bitop3:0x78
	v_add3_u32 v12, 0, v2, v10
	v_lshl_add_u32 v1, s38, 2, v221
	ds_read_b128 v[2:5], v12 offset:32768
	ds_read_b128 v[32:35], v1
	ds_read_b128 v[36:39], v1 offset:32
	ds_read_b128 v[40:43], v1 offset:64
	ds_read_b128 v[44:47], v1 offset:96
	ds_read_b128 v[16:19], v1 offset:128
	ds_read_b128 v[6:9], v12 offset:40960
	ds_read_b128 v[20:23], v1 offset:160
	ds_read_b128 v[24:27], v1 offset:192
	ds_read_b128 v[28:31], v1 offset:224
	v_and_b32_e32 v1, 0x70, v11
	s_waitcnt vmcnt(7) lgkmcnt(5)
	v_mfma_f32_32x32x16_bf16 v[32:47], v[2:5], v[172:175], v[32:47]
	v_bitop3_b32 v2, v198, v1, 32 bitop3:0x36
	v_add3_u32 v11, 0, v2, v10
	ds_read_b128 v[2:5], v11 offset:32768
	s_waitcnt lgkmcnt(1)
	v_mfma_f32_32x32x16_bf16 v[16:31], v[6:9], v[172:175], v[16:31]
	v_bitop3_b32 v6, v198, v1, 64 bitop3:0x36
	v_add3_u32 v6, 0, v6, v10
	v_bitop3_b32 v1, v198, v1, s96 bitop3:0x36
	v_add3_u32 v1, 0, v1, v10
	s_waitcnt vmcnt(6) lgkmcnt(0)
	v_mfma_f32_32x32x16_bf16 v[32:47], v[2:5], v[168:171], v[32:47]
	ds_read_b128 v[2:5], v11 offset:40960
	ds_read_b128 v[50:53], v6 offset:32768
	ds_read_b128 v[54:57], v6 offset:40960
	ds_read_b128 v[58:61], v1 offset:32768
	s_waitcnt lgkmcnt(3)
	v_mfma_f32_32x32x16_bf16 v[16:31], v[2:5], v[168:171], v[16:31]
	ds_read_b128 v[2:5], v1 offset:40960
	s_waitcnt vmcnt(5) lgkmcnt(3)
	v_mfma_f32_32x32x16_bf16 v[32:47], v[50:53], v[164:167], v[32:47]
	ds_read_b128 v[50:53], v12 offset:32896
	s_waitcnt lgkmcnt(3)
	v_mfma_f32_32x32x16_bf16 v[16:31], v[54:57], v[164:167], v[16:31]
	ds_read_b128 v[54:57], v12 offset:41088
	s_waitcnt vmcnt(4) lgkmcnt(3)
	v_mfma_f32_32x32x16_bf16 v[32:47], v[58:61], v[160:163], v[32:47]
	ds_read_b128 v[58:61], v11 offset:32896
	s_waitcnt lgkmcnt(3)
	v_mfma_f32_32x32x16_bf16 v[16:31], v[2:5], v[160:163], v[16:31]
	ds_read_b128 v[2:5], v11 offset:41088
	s_waitcnt vmcnt(3) lgkmcnt(3)
	v_mfma_f32_32x32x16_bf16 v[32:47], v[50:53], v[156:159], v[32:47]
	ds_read_b128 v[50:53], v6 offset:32896
	s_waitcnt lgkmcnt(3)
	v_mfma_f32_32x32x16_bf16 v[16:31], v[54:57], v[156:159], v[16:31]
	ds_read_b128 v[54:57], v6 offset:41088
	s_waitcnt vmcnt(2) lgkmcnt(3)
	v_mfma_f32_32x32x16_bf16 v[32:47], v[58:61], v[152:155], v[32:47]
	ds_read_b128 v[58:61], v1 offset:32896
	s_waitcnt lgkmcnt(3)
	v_mfma_f32_32x32x16_bf16 v[16:31], v[2:5], v[152:155], v[16:31]
	ds_read_b128 v[2:5], v1 offset:41088
	s_waitcnt vmcnt(1) lgkmcnt(3)
	v_mfma_f32_32x32x16_bf16 v[32:47], v[50:53], v[148:151], v[32:47]
	s_waitcnt lgkmcnt(2)
	v_mfma_f32_32x32x16_bf16 v[16:31], v[54:57], v[148:151], v[16:31]
	s_waitcnt vmcnt(0) lgkmcnt(1)
	v_mfma_f32_32x32x16_bf16 v[32:47], v[58:61], v[144:147], v[32:47]
	s_waitcnt lgkmcnt(0)
	v_mfma_f32_32x32x16_bf16 v[16:31], v[2:5], v[144:147], v[16:31]
	s_branch .LBB0_4548

.LBB0_4582:
	s_bitcmp0_b32 s28, 0
	s_cselect_b64 s[0:1], -1, 0
	v_cndmask_b32_e64 v1, 0, 1, s[20:21]
	s_and_b64 vcc, exec, s[0:1]
	v_cmp_ne_u32_e64 s[36:37], 1, v1
	s_cbranch_vccz .LBB0_4587
	s_and_b64 vcc, exec, s[36:37]
	s_cbranch_vccnz .LBB0_4585
	v_lshl_add_u32 v1, s22, 8, v221
	v_add_u32_e32 v2, 0xffffff00, v1
	v_add_u32_e32 v6, 0xffffff40, v1
	v_subrev_u32_e32 v13, 64, v1
	v_add_u32_e32 v3, 0xffffff80, v1
	ds_read_b128 v[80:83], v2
	ds_read_b128 v[96:99], v3
	ds_read_b128 v[88:91], v6
	ds_read_b128 v[104:107], v13
	v_add_u32_e32 v6, 0xffffff60, v1
	v_add_u32_e32 v2, 0xffffff20, v1
	v_lshlrev_b32_e32 v11, 4, v211
	ds_read_b128 v[92:95], v6
	v_add_u32_e32 v6, 0xffffffa0, v1
	v_subrev_u32_e32 v1, 32, v1
	ds_read_b128 v[84:87], v2
	ds_read_b128 v[108:111], v1
	v_lshlrev_b32_e32 v10, 8, v211
	v_bitop3_b32 v2, v198, v11, s3 bitop3:0x78
	v_add3_u32 v12, 0, v2, v10
	ds_read_b128 v[2:5], v12 offset:49152
	v_and_b32_e32 v1, 0x70, v11
	s_waitcnt vmcnt(7) lgkmcnt(0)
	v_mfma_f32_32x32x16_bf16 v[80:95], v[2:5], v[172:175], v[80:95]
	v_bitop3_b32 v2, v198, v1, 32 bitop3:0x36
	v_add3_u32 v11, 0, v2, v10
	ds_read_b128 v[100:103], v6
	ds_read_b128 v[2:5], v11 offset:49152
	ds_read_b128 v[6:9], v12 offset:57344
	s_waitcnt vmcnt(6) lgkmcnt(1)
	v_mfma_f32_32x32x16_bf16 v[80:95], v[2:5], v[168:171], v[80:95]
	ds_read_b128 v[2:5], v11 offset:57344
	s_waitcnt lgkmcnt(1)
	v_mfma_f32_32x32x16_bf16 v[96:111], v[6:9], v[172:175], v[96:111]
	v_bitop3_b32 v6, v198, v1, 64 bitop3:0x36
	v_add3_u32 v6, 0, v6, v10
	v_bitop3_b32 v1, v198, v1, s96 bitop3:0x36
	v_add3_u32 v1, 0, v1, v10
	s_waitcnt lgkmcnt(0)
	v_mfma_f32_32x32x16_bf16 v[96:111], v[2:5], v[168:171], v[96:111]
	ds_read_b128 v[2:5], v6 offset:49152
	ds_read_b128 v[112:115], v6 offset:57344
	ds_read_b128 v[116:119], v1 offset:49152
	ds_read_b128 v[120:123], v1 offset:57344
	s_waitcnt vmcnt(5) lgkmcnt(3)
	v_mfma_f32_32x32x16_bf16 v[80:95], v[2:5], v[164:167], v[80:95]
	ds_read_b128 v[2:5], v12 offset:49280
	s_waitcnt lgkmcnt(3)
	v_mfma_f32_32x32x16_bf16 v[96:111], v[112:115], v[164:167], v[96:111]
	ds_read_b128 v[112:115], v12 offset:57472
	s_waitcnt vmcnt(4) lgkmcnt(3)
	v_mfma_f32_32x32x16_bf16 v[80:95], v[116:119], v[160:163], v[80:95]
	ds_read_b128 v[116:119], v11 offset:49280
	s_waitcnt lgkmcnt(3)
	v_mfma_f32_32x32x16_bf16 v[96:111], v[120:123], v[160:163], v[96:111]
	ds_read_b128 v[120:123], v11 offset:57472
	s_waitcnt vmcnt(3) lgkmcnt(3)
	v_mfma_f32_32x32x16_bf16 v[80:95], v[2:5], v[156:159], v[80:95]
	ds_read_b128 v[2:5], v6 offset:49280
	s_waitcnt lgkmcnt(3)
	v_mfma_f32_32x32x16_bf16 v[96:111], v[112:115], v[156:159], v[96:111]
	ds_read_b128 v[112:115], v6 offset:57472
	s_waitcnt vmcnt(2) lgkmcnt(3)
	v_mfma_f32_32x32x16_bf16 v[80:95], v[116:119], v[152:155], v[80:95]
	ds_read_b128 v[116:119], v1 offset:49280
	s_waitcnt lgkmcnt(3)
	v_mfma_f32_32x32x16_bf16 v[96:111], v[120:123], v[152:155], v[96:111]
	ds_read_b128 v[120:123], v1 offset:57472
	s_waitcnt vmcnt(1) lgkmcnt(3)
	v_mfma_f32_32x32x16_bf16 v[80:95], v[2:5], v[148:151], v[80:95]
	s_waitcnt lgkmcnt(2)
	v_mfma_f32_32x32x16_bf16 v[96:111], v[112:115], v[148:151], v[96:111]
	s_waitcnt vmcnt(0) lgkmcnt(1)
	v_mfma_f32_32x32x16_bf16 v[80:95], v[116:119], v[144:147], v[80:95]
	s_waitcnt lgkmcnt(0)
	v_mfma_f32_32x32x16_bf16 v[96:111], v[120:123], v[144:147], v[96:111]
	s_branch .LBB0_4586

.LBB0_4809:
	s_or_b64 exec, exec, s[0:1]
	v_mul_lo_u32 v24, v79, s59
	v_lshlrev_b32_e32 v25, 2, v48
	v_add3_u32 v28, 0, v24, v25
	s_waitcnt lgkmcnt(0)
	s_barrier
	ds_read_b32 v24, v28
	s_movk_i32 s0, 0x2ff
	v_cmp_lt_i32_e32 vcc, s0, v54
	v_mov_b32_e32 v25, 0
	v_lshl_add_u32 v27, v48, 2, 0
	v_mov_b32_e32 v26, 0
	s_and_saveexec_b64 s[0:1], vcc
	ds_read_b32 v26, v27 offset:53248
	s_or_b64 exec, exec, s[0:1]
	s_waitcnt vmcnt(16)
	ds_read_b32 v29, v28 offset:4
	s_and_saveexec_b64 s[0:1], vcc
	ds_read_b32 v25, v27 offset:53252
	s_or_b64 exec, exec, s[0:1]
	s_waitcnt vmcnt(10)
	ds_read_b32 v30, v28 offset:8
	s_waitcnt vmcnt(8)
	v_mov_b32_e32 v32, 0
	v_mov_b32_e32 v31, 0
	s_and_saveexec_b64 s[0:1], vcc
	ds_read_b32 v31, v27 offset:53256
	s_or_b64 exec, exec, s[0:1]
	s_waitcnt vmcnt(7)
	ds_read_b32 v33, v28 offset:12
	s_and_saveexec_b64 s[0:1], vcc
	ds_read_b32 v32, v27 offset:53260
	s_or_b64 exec, exec, s[0:1]
	s_waitcnt vmcnt(6)
	ds_read_b32 v34, v28 offset:16
	s_waitcnt vmcnt(4)
	v_mov_b32_e32 v36, 0
	v_mov_b32_e32 v35, 0
	s_and_saveexec_b64 s[0:1], vcc
	ds_read_b32 v35, v27 offset:53264
	s_or_b64 exec, exec, s[0:1]
	s_waitcnt vmcnt(3)
	ds_read_b32 v37, v28 offset:20
	s_and_saveexec_b64 s[0:1], vcc
	ds_read_b32 v36, v27 offset:53268
	s_or_b64 exec, exec, s[0:1]
	s_waitcnt vmcnt(1)
	ds_read_b32 v39, v28 offset:24
	v_mov_b32_e32 v38, 0
	s_waitcnt vmcnt(0)
	v_mov_b32_e32 v40, 0
	s_and_saveexec_b64 s[0:1], vcc
	ds_read_b32 v40, v27 offset:53272
	s_or_b64 exec, exec, s[0:1]
	ds_read_b32 v28, v28 offset:28
	s_and_saveexec_b64 s[0:1], vcc
	ds_read_b32 v38, v27 offset:53276
	s_or_b64 exec, exec, s[0:1]
	s_waitcnt lgkmcnt(6)
	v_add_f32_e32 v25, v29, v25
	v_add_f32_e32 v24, v24, v26
	v_mul_f32_e32 v24, 0x3fb8aa3b, v24
	v_mul_f32_e32 v25, 0x3fb8aa3b, v25
	v_exp_f32_e32 v24, v24
	v_exp_f32_e32 v25, v25
	s_waitcnt lgkmcnt(0)
	v_add_f32_e32 v26, v28, v38
	v_lshlrev_b32_e32 v28, 16, v20
	v_and_b32_e32 v20, 0xffff0000, v20
	v_mul_f32_e32 v28, 0x3d93cd3a, v28
	v_mul_f32_e32 v20, 0x3d93cd3a, v20
	v_mul_f32_e32 v28, v28, v24
	v_mul_f32_e32 v20, v20, v25
	v_rcp_f32_e32 v24, v24
	v_rcp_f32_e32 v25, v25
	v_cvt_pk_bf16_f32 v20, v28, v20
	v_lshlrev_b32_e32 v28, 16, v16
	v_and_b32_e32 v16, 0xffff0000, v16
	v_add_f32_e32 v32, v33, v32
	v_add_f32_e32 v30, v30, v31
	v_mul_f32_e32 v24, v24, v28
	v_mul_f32_e32 v16, v25, v16
	v_cvt_pk_bf16_f32 v16, v24, v16
	v_mul_f32_e32 v24, 0x3fb8aa3b, v30
	v_mul_f32_e32 v25, 0x3fb8aa3b, v32
	v_exp_f32_e32 v24, v24
	v_exp_f32_e32 v25, v25
	v_lshlrev_b32_e32 v28, 16, v21
	v_and_b32_e32 v21, 0xffff0000, v21
	v_mul_f32_e32 v28, 0x3d93cd3a, v28
	v_mul_f32_e32 v21, 0x3d93cd3a, v21
	v_mul_f32_e32 v28, v28, v24
	v_mul_f32_e32 v21, v21, v25
	v_rcp_f32_e32 v24, v24
	v_rcp_f32_e32 v25, v25
	v_cvt_pk_bf16_f32 v21, v28, v21
	v_lshlrev_b32_e32 v28, 16, v17
	v_and_b32_e32 v17, 0xffff0000, v17
	v_add_f32_e32 v36, v37, v36
	v_add_f32_e32 v34, v34, v35
	v_mul_f32_e32 v24, v24, v28
	v_mul_f32_e32 v17, v25, v17
	v_cvt_pk_bf16_f32 v17, v24, v17
	v_mul_f32_e32 v24, 0x3fb8aa3b, v34
	v_mul_f32_e32 v25, 0x3fb8aa3b, v36
	v_exp_f32_e32 v24, v24
	v_exp_f32_e32 v25, v25
	v_lshlrev_b32_e32 v28, 16, v22
	v_and_b32_e32 v22, 0xffff0000, v22
	v_mul_f32_e32 v28, 0x3d93cd3a, v28
	v_mul_f32_e32 v22, 0x3d93cd3a, v22
	v_mul_f32_e32 v28, v28, v24
	v_mul_f32_e32 v22, v22, v25
	v_rcp_f32_e32 v24, v24
	v_rcp_f32_e32 v25, v25
	v_cvt_pk_bf16_f32 v22, v28, v22
	v_lshlrev_b32_e32 v28, 16, v18
	v_and_b32_e32 v18, 0xffff0000, v18
	v_add_f32_e32 v27, v39, v40
	v_mul_f32_e32 v24, v24, v28
	v_mul_f32_e32 v18, v25, v18
	v_cvt_pk_bf16_f32 v18, v24, v18
	v_mul_f32_e32 v24, 0x3fb8aa3b, v27
	v_mul_f32_e32 v25, 0x3fb8aa3b, v26
	v_exp_f32_e32 v24, v24
	v_exp_f32_e32 v25, v25
	v_lshlrev_b32_e32 v26, 16, v23
	v_and_b32_e32 v23, 0xffff0000, v23
	v_mul_f32_e32 v26, 0x3d93cd3a, v26
	v_mul_f32_e32 v23, 0x3d93cd3a, v23
	v_mul_f32_e32 v26, v26, v24
	v_mul_f32_e32 v23, v23, v25
	v_rcp_f32_e32 v24, v24
	v_rcp_f32_e32 v25, v25
	v_cvt_pk_bf16_f32 v23, v26, v23
	v_lshlrev_b32_e32 v26, 16, v19
	v_and_b32_e32 v19, 0xffff0000, v19
	v_mul_f32_e32 v24, v24, v26
	v_mul_f32_e32 v19, v25, v19
	v_cvt_pk_bf16_f32 v19, v24, v19
	v_mul_lo_u32 v24, v79, s60
	v_lshlrev_b32_e32 v25, 1, v48
	v_add3_u32 v58, 0, v24, v25
	ds_write_b128 v58, v[20:23] offset:54272
	v_add3_u32 v20, s61, v24, v25
	ds_write_b128 v20, v[16:19]
	v_mul_lo_u32 v16, v80, s59
	v_lshlrev_b32_e32 v17, 2, v50
	v_add3_u32 v20, 0, v16, v17
	ds_read_b32 v16, v20
	s_movk_i32 s0, 0xff
	v_cmp_lt_i32_e32 vcc, s0, v54
	v_mov_b32_e32 v17, 0
	v_lshl_add_u32 v19, v50, 2, 0
	v_mov_b32_e32 v18, 0
	s_and_saveexec_b64 s[0:1], vcc
	ds_read_b32 v18, v19 offset:53248
	s_or_b64 exec, exec, s[0:1]
	ds_read_b32 v21, v20 offset:4
	s_and_saveexec_b64 s[0:1], vcc
	ds_read_b32 v17, v19 offset:53252
	s_or_b64 exec, exec, s[0:1]
	ds_read_b32 v22, v20 offset:8
	v_mov_b32_e32 v24, 0
	v_mov_b32_e32 v23, 0
	s_and_saveexec_b64 s[0:1], vcc
	ds_read_b32 v23, v19 offset:53256
	s_or_b64 exec, exec, s[0:1]
	ds_read_b32 v25, v20 offset:12
	s_and_saveexec_b64 s[0:1], vcc
	ds_read_b32 v24, v19 offset:53260
	s_or_b64 exec, exec, s[0:1]
	ds_read_b32 v26, v20 offset:16
	v_mov_b32_e32 v28, 0
	v_mov_b32_e32 v27, 0
	s_and_saveexec_b64 s[0:1], vcc
	ds_read_b32 v27, v19 offset:53264
	s_or_b64 exec, exec, s[0:1]
	ds_read_b32 v29, v20 offset:20
	s_and_saveexec_b64 s[0:1], vcc
	ds_read_b32 v28, v19 offset:53268
	s_or_b64 exec, exec, s[0:1]
	ds_read_b32 v31, v20 offset:24
	v_mov_b32_e32 v30, 0
	v_mov_b32_e32 v32, 0
	s_and_saveexec_b64 s[0:1], vcc
	ds_read_b32 v32, v19 offset:53272
	s_or_b64 exec, exec, s[0:1]
	ds_read_b32 v20, v20 offset:28
	s_and_saveexec_b64 s[0:1], vcc
	ds_read_b32 v30, v19 offset:53276
	s_or_b64 exec, exec, s[0:1]
	s_waitcnt lgkmcnt(6)
	v_add_f32_e32 v17, v21, v17
	v_add_f32_e32 v16, v16, v18
	v_mul_f32_e32 v16, 0x3fb8aa3b, v16
	v_mul_f32_e32 v17, 0x3fb8aa3b, v17
	v_exp_f32_e32 v16, v16
	v_exp_f32_e32 v17, v17
	s_waitcnt lgkmcnt(0)
	v_add_f32_e32 v18, v20, v30
	v_lshlrev_b32_e32 v20, 16, v12
	v_and_b32_e32 v12, 0xffff0000, v12
	v_mul_f32_e32 v20, 0x3d93cd3a, v20
	v_mul_f32_e32 v12, 0x3d93cd3a, v12
	v_mul_f32_e32 v20, v20, v16
	v_mul_f32_e32 v12, v12, v17
	v_rcp_f32_e32 v16, v16
	v_rcp_f32_e32 v17, v17
	v_cvt_pk_bf16_f32 v12, v20, v12
	v_lshlrev_b32_e32 v20, 16, v8
	v_and_b32_e32 v8, 0xffff0000, v8
	v_add_f32_e32 v24, v25, v24
	v_add_f32_e32 v22, v22, v23
	v_mul_f32_e32 v16, v16, v20
	v_mul_f32_e32 v8, v17, v8
	v_cvt_pk_bf16_f32 v8, v16, v8
	v_mul_f32_e32 v16, 0x3fb8aa3b, v22
	v_mul_f32_e32 v17, 0x3fb8aa3b, v24
	v_exp_f32_e32 v16, v16
	v_exp_f32_e32 v17, v17
	v_lshlrev_b32_e32 v20, 16, v13
	v_and_b32_e32 v13, 0xffff0000, v13
	v_mul_f32_e32 v20, 0x3d93cd3a, v20
	v_mul_f32_e32 v13, 0x3d93cd3a, v13
	v_mul_f32_e32 v20, v20, v16
	v_mul_f32_e32 v13, v13, v17
	v_rcp_f32_e32 v16, v16
	v_rcp_f32_e32 v17, v17
	v_cvt_pk_bf16_f32 v13, v20, v13
	v_lshlrev_b32_e32 v20, 16, v9
	v_and_b32_e32 v9, 0xffff0000, v9
	v_add_f32_e32 v28, v29, v28
	v_add_f32_e32 v26, v26, v27
	v_mul_f32_e32 v16, v16, v20
	v_mul_f32_e32 v9, v17, v9
	v_cvt_pk_bf16_f32 v9, v16, v9
	v_mul_f32_e32 v16, 0x3fb8aa3b, v26
	v_mul_f32_e32 v17, 0x3fb8aa3b, v28
	v_exp_f32_e32 v16, v16
	v_exp_f32_e32 v17, v17
	v_lshlrev_b32_e32 v20, 16, v14
	v_and_b32_e32 v14, 0xffff0000, v14
	v_mul_f32_e32 v20, 0x3d93cd3a, v20
	v_mul_f32_e32 v14, 0x3d93cd3a, v14
	v_mul_f32_e32 v20, v20, v16
	v_mul_f32_e32 v14, v14, v17
	v_rcp_f32_e32 v16, v16
	v_rcp_f32_e32 v17, v17
	v_cvt_pk_bf16_f32 v14, v20, v14
	v_lshlrev_b32_e32 v20, 16, v10
	v_and_b32_e32 v10, 0xffff0000, v10
	v_add_f32_e32 v19, v31, v32
	v_mul_f32_e32 v16, v16, v20
	v_mul_f32_e32 v10, v17, v10
	v_cvt_pk_bf16_f32 v10, v16, v10
	v_mul_f32_e32 v16, 0x3fb8aa3b, v19
	v_mul_f32_e32 v17, 0x3fb8aa3b, v18
	v_exp_f32_e32 v16, v16
	v_exp_f32_e32 v17, v17
	v_lshlrev_b32_e32 v18, 16, v15
	v_and_b32_e32 v15, 0xffff0000, v15
	v_mul_f32_e32 v18, 0x3d93cd3a, v18
	v_mul_f32_e32 v15, 0x3d93cd3a, v15
	v_mul_f32_e32 v18, v18, v16
	v_mul_f32_e32 v15, v15, v17
	v_rcp_f32_e32 v16, v16
	v_rcp_f32_e32 v17, v17
	v_cvt_pk_bf16_f32 v15, v18, v15
	v_lshlrev_b32_e32 v18, 16, v11
	v_and_b32_e32 v11, 0xffff0000, v11
	v_mul_f32_e32 v16, v16, v18
	v_mul_f32_e32 v11, v17, v11
	v_cvt_pk_bf16_f32 v11, v16, v11
	v_mul_lo_u32 v16, v80, s60
	v_lshlrev_b32_e32 v17, 1, v50
	v_add3_u32 v84, 0, v16, v17
	ds_write_b128 v84, v[12:15] offset:54272
	v_add3_u32 v12, s61, v16, v17
	ds_write_b128 v12, v[8:11]
	v_mul_lo_u32 v8, v81, s59
	v_lshlrev_b32_e32 v9, 2, v52
	v_add3_u32 v12, 0, v8, v9
	ds_read_b32 v8, v12
	s_movk_i32 s0, 0xfeff
	v_cmp_lt_i32_e32 vcc, s0, v54
	v_mov_b32_e32 v9, 0
	v_lshl_add_u32 v11, v52, 2, 0
	v_mov_b32_e32 v10, 0
	s_and_saveexec_b64 s[0:1], vcc
	ds_read_b32 v10, v11 offset:53248
	s_or_b64 exec, exec, s[0:1]
	ds_read_b32 v13, v12 offset:4
	s_and_saveexec_b64 s[0:1], vcc
	ds_read_b32 v9, v11 offset:53252
	s_or_b64 exec, exec, s[0:1]
	ds_read_b32 v14, v12 offset:8
	v_mov_b32_e32 v16, 0
	v_mov_b32_e32 v15, 0
	s_and_saveexec_b64 s[0:1], vcc
	ds_read_b32 v15, v11 offset:53256
	s_or_b64 exec, exec, s[0:1]
	ds_read_b32 v17, v12 offset:12
	s_and_saveexec_b64 s[0:1], vcc
	ds_read_b32 v16, v11 offset:53260
	s_or_b64 exec, exec, s[0:1]
	ds_read_b32 v18, v12 offset:16
	v_mov_b32_e32 v20, 0
	v_mov_b32_e32 v19, 0
	s_and_saveexec_b64 s[0:1], vcc
	ds_read_b32 v19, v11 offset:53264
	s_or_b64 exec, exec, s[0:1]
	ds_read_b32 v21, v12 offset:20
	s_and_saveexec_b64 s[0:1], vcc
	ds_read_b32 v20, v11 offset:53268
	s_or_b64 exec, exec, s[0:1]
	ds_read_b32 v23, v12 offset:24
	v_mov_b32_e32 v22, 0
	v_mov_b32_e32 v24, 0
	s_and_saveexec_b64 s[0:1], vcc
	ds_read_b32 v24, v11 offset:53272
	s_or_b64 exec, exec, s[0:1]
	ds_read_b32 v12, v12 offset:28
	s_and_saveexec_b64 s[0:1], vcc
	ds_read_b32 v22, v11 offset:53276
	s_or_b64 exec, exec, s[0:1]
	s_waitcnt lgkmcnt(6)
	v_add_f32_e32 v9, v13, v9
	v_add_f32_e32 v8, v8, v10
	v_mul_f32_e32 v8, 0x3fb8aa3b, v8
	v_mul_f32_e32 v9, 0x3fb8aa3b, v9
	v_exp_f32_e32 v8, v8
	v_exp_f32_e32 v9, v9
	s_waitcnt lgkmcnt(0)
	v_add_f32_e32 v10, v12, v22
	v_lshlrev_b32_e32 v12, 16, v4
	v_and_b32_e32 v4, 0xffff0000, v4
	v_mul_f32_e32 v12, 0x3d93cd3a, v12
	v_mul_f32_e32 v4, 0x3d93cd3a, v4
	v_mul_f32_e32 v12, v12, v8
	v_mul_f32_e32 v4, v4, v9
	v_rcp_f32_e32 v8, v8
	v_rcp_f32_e32 v9, v9
	v_cvt_pk_bf16_f32 v4, v12, v4
	v_lshlrev_b32_e32 v12, 16, v0
	v_and_b32_e32 v0, 0xffff0000, v0
	v_add_f32_e32 v16, v17, v16
	v_add_f32_e32 v14, v14, v15
	v_mul_f32_e32 v8, v8, v12
	v_mul_f32_e32 v0, v9, v0
	v_cvt_pk_bf16_f32 v0, v8, v0
	v_mul_f32_e32 v8, 0x3fb8aa3b, v14
	v_mul_f32_e32 v9, 0x3fb8aa3b, v16
	v_exp_f32_e32 v8, v8
	v_exp_f32_e32 v9, v9
	v_lshlrev_b32_e32 v12, 16, v5
	v_and_b32_e32 v5, 0xffff0000, v5
	v_mul_f32_e32 v12, 0x3d93cd3a, v12
	v_mul_f32_e32 v5, 0x3d93cd3a, v5
	v_mul_f32_e32 v12, v12, v8
	v_mul_f32_e32 v5, v5, v9
	v_rcp_f32_e32 v8, v8
	v_rcp_f32_e32 v9, v9
	v_cvt_pk_bf16_f32 v5, v12, v5
	v_lshlrev_b32_e32 v12, 16, v1
	v_and_b32_e32 v1, 0xffff0000, v1
	v_add_f32_e32 v20, v21, v20
	v_add_f32_e32 v18, v18, v19
	v_mul_f32_e32 v8, v8, v12
	v_mul_f32_e32 v1, v9, v1
	v_cvt_pk_bf16_f32 v1, v8, v1
	v_mul_f32_e32 v8, 0x3fb8aa3b, v18
	v_mul_f32_e32 v9, 0x3fb8aa3b, v20
	v_exp_f32_e32 v8, v8
	v_exp_f32_e32 v9, v9
	v_lshlrev_b32_e32 v12, 16, v6
	v_and_b32_e32 v6, 0xffff0000, v6
	v_mul_f32_e32 v12, 0x3d93cd3a, v12
	v_mul_f32_e32 v6, 0x3d93cd3a, v6
	v_mul_f32_e32 v12, v12, v8
	v_mul_f32_e32 v6, v6, v9
	v_rcp_f32_e32 v8, v8
	v_rcp_f32_e32 v9, v9
	v_cvt_pk_bf16_f32 v6, v12, v6
	v_lshlrev_b32_e32 v12, 16, v2
	v_and_b32_e32 v2, 0xffff0000, v2
	v_add_f32_e32 v11, v23, v24
	v_mul_f32_e32 v8, v8, v12
	v_mul_f32_e32 v2, v9, v2
	v_cvt_pk_bf16_f32 v2, v8, v2
	v_mul_f32_e32 v8, 0x3fb8aa3b, v11
	v_mul_f32_e32 v9, 0x3fb8aa3b, v10
	v_exp_f32_e32 v8, v8
	v_exp_f32_e32 v9, v9
	v_lshlrev_b32_e32 v10, 16, v7
	v_and_b32_e32 v7, 0xffff0000, v7
	v_mul_f32_e32 v10, 0x3d93cd3a, v10
	v_mul_f32_e32 v7, 0x3d93cd3a, v7
	v_mul_f32_e32 v10, v10, v8
	v_mul_f32_e32 v7, v7, v9
	v_rcp_f32_e32 v8, v8
	v_rcp_f32_e32 v9, v9
	v_cvt_pk_bf16_f32 v7, v10, v7
	v_lshlrev_b32_e32 v10, 16, v3
	v_and_b32_e32 v3, 0xffff0000, v3
	s_lshl_b32 s0, s3, 2
	v_mul_f32_e32 v8, v8, v10
	v_mul_f32_e32 v3, v9, v3
	s_add_i32 s0, s0, s2
	v_cvt_pk_bf16_f32 v3, v8, v3
	v_mul_lo_u32 v8, v81, s60
	v_lshlrev_b32_e32 v9, 1, v52
	s_mul_hi_i32 s1, s0, 0x24000
	s_mul_i32 s0, s0, 0x24000
	v_add3_u32 v87, 0, v8, v9
	s_add_u32 s22, s46, s0
	ds_write_b128 v87, v[4:7] offset:54272
	v_add3_u32 v4, s61, v8, v9
	s_addc_u32 s23, s47, s1
	ds_write_b128 v4, v[0:3]
	v_mov_b64_e32 v[0:1], s[22:23]
	v_mad_i64_i32 v[2:3], s[0:1], v79, s54, v[0:1]
	v_mad_i64_i32 v[4:5], s[0:1], v80, s54, v[0:1]
	v_lshl_add_u64 v[2:3], v[48:49], 1, v[2:3]
	v_lshl_add_u64 v[4:5], v[50:51], 1, v[4:5]
	s_waitcnt lgkmcnt(0)
	s_barrier
	global_load_dwordx4 v[16:19], v[2:3], off
	global_load_dwordx4 v[20:23], v[4:5], off
	v_add_u32_e32 v4, 0x600, v54
	v_mul_hi_i32 v5, v4, s48
	v_lshrrev_b32_e32 v6, 31, v5
	v_ashrrev_i32_e32 v5, 2, v5
	v_add_u32_e32 v93, v5, v6
	v_mul_lo_u32 v5, v93, 24
	v_sub_u32_e32 v4, v4, v5
	v_mad_i64_i32 v[2:3], s[0:1], v81, s54, v[0:1]
	v_lshlrev_b32_e32 v64, 3, v4
	v_lshl_add_u64 v[2:3], v[52:53], 1, v[2:3]
	v_mad_i64_i32 v[4:5], s[0:1], v93, s54, v[0:1]
	v_ashrrev_i32_e32 v65, 31, v64
	v_lshl_add_u64 v[4:5], v[64:65], 1, v[4:5]
	global_load_dwordx4 v[28:31], v[2:3], off
	global_load_dwordx4 v[24:27], v[4:5], off
	v_add_u32_e32 v2, 0x800, v54
	v_mul_hi_i32 v3, v2, s48
	v_lshrrev_b32_e32 v4, 31, v3
	v_ashrrev_i32_e32 v3, 2, v3
	v_add_u32_e32 v94, v3, v4
	v_add_u32_e32 v4, 0xa00, v54
	v_mul_hi_i32 v5, v4, s48
	v_lshrrev_b32_e32 v6, 31, v5
	v_ashrrev_i32_e32 v5, 2, v5
	v_add_u32_e32 v95, v5, v6
	v_mul_lo_u32 v3, v94, 24
	v_mul_lo_u32 v5, v95, 24
	v_sub_u32_e32 v2, v2, v3
	v_sub_u32_e32 v4, v4, v5
	v_lshlrev_b32_e32 v66, 3, v2
	v_lshlrev_b32_e32 v68, 3, v4
	v_mad_i64_i32 v[2:3], s[0:1], v94, s54, v[0:1]
	v_ashrrev_i32_e32 v67, 31, v66
	v_mad_i64_i32 v[0:1], s[0:1], v95, s54, v[0:1]
	v_ashrrev_i32_e32 v69, 31, v68
	v_lshl_add_u64 v[2:3], v[66:67], 1, v[2:3]
	v_lshl_add_u64 v[0:1], v[68:69], 1, v[0:1]
	v_and_b32_e32 v99, 63, v78
	global_load_dwordx4 v[36:39], v[2:3], off
	global_load_dwordx4 v[32:35], v[0:1], off
	v_or_b32_e32 v2, s66, v99
	v_mov_b64_e32 v[0:1], s[36:37]
	v_mad_i64_i32 v[0:1], s[0:1], v2, s49, v[0:1]
	s_mul_i32 s0, s2, 0x180
	v_ashrrev_i32_e32 v2, 3, v54
	s_ashr_i32 s1, s0, 31
	v_and_b32_e32 v72, -8, v2
	v_ashrrev_i32_e32 v2, 3, v55
	v_lshl_add_u64 v[0:1], s[0:1], 1, v[0:1]
	v_ashrrev_i32_e32 v73, 31, v72
	v_and_b32_e32 v70, -8, v2
	v_lshl_add_u64 v[62:63], v[72:73], 1, v[0:1]
	v_ashrrev_i32_e32 v71, 31, v70
	v_lshl_add_u64 v[60:61], v[70:71], 1, v[0:1]
	global_load_dwordx4 v[44:47], v[62:63], off offset:3072
	global_load_dwordx4 v[40:43], v[60:61], off offset:3072
	v_ashrrev_i32_e32 v0, 6, v54
	v_and_b32_e32 v85, 1, v0
	v_ashrrev_i32_e32 v86, 7, v54
	v_and_b32_e32 v71, 31, v78
	v_cmp_lt_i32_e32 vcc, 3, v0
	v_lshlrev_b32_e32 v73, 5, v85
	v_lshlrev_b32_e32 v82, 5, v86
	s_and_saveexec_b64 s[2:3], vcc
	s_xor_b64 s[26:27], exec, s[2:3]
	v_lshlrev_b32_e32 v82, 5, v86
	v_lshlrev_b32_e32 v73, 5, v85
	v_or_b32_e32 v54, v82, v71
	s_or_saveexec_b64 s[26:27], s[26:27]
	v_bfe_u32 v83, v78, 5, 1
	s_xor_b64 exec, exec, s[26:27]
	s_cbranch_execz .LBB0_4865
	v_cmp_le_i32_e32 vcc, v86, v85
	s_and_saveexec_b64 s[2:3], vcc
	s_xor_b64 s[44:45], exec, s[2:3]
	s_cbranch_execz .LBB0_4862
	v_or_b32_e32 v0, v73, v71
	v_mul_u32_u24_e32 v0, 0x190, v0
	v_lshlrev_b32_e32 v4, 4, v83
	v_add3_u32 v55, 0, v0, v4
	v_lshlrev_b32_e32 v82, 5, v86
	ds_read_b128 v[0:3], v55 offset:54272
	v_or_b32_e32 v54, v82, v71
	v_mul_lo_u32 v5, v54, s60
	v_add3_u32 v92, s61, v5, v4
	ds_read_b128 v[4:7], v92
	ds_read_b128 v[88:91], v55 offset:54304
	ds_read_b128 v[100:103], v92 offset:32
	ds_read_b128 v[104:107], v55 offset:54336
	ds_read_b128 v[108:111], v92 offset:64
	ds_read_b128 v[194:197], v55 offset:54368
	ds_read_b128 v[198:201], v92 offset:96
	s_waitcnt lgkmcnt(6)
	v_mfma_f32_32x32x16_bf16 v[0:15], v[0:3], v[4:7], 0
	ds_read_b128 v[206:209], v55 offset:54400
	ds_read_b128 v[210:213], v92 offset:128
	s_waitcnt lgkmcnt(6)
	v_mfma_f32_32x32x16_bf16 v[0:15], v[88:91], v[100:103], v[0:15]
	ds_read_b128 v[88:91], v55 offset:54432
	ds_read_b128 v[100:103], v92 offset:160
	s_waitcnt lgkmcnt(6)
	v_mfma_f32_32x32x16_bf16 v[0:15], v[104:107], v[108:111], v[0:15]
	ds_read_b128 v[104:107], v55 offset:54464
	ds_read_b128 v[108:111], v92 offset:192
	s_waitcnt lgkmcnt(6)
	v_mfma_f32_32x32x16_bf16 v[0:15], v[194:197], v[198:201], v[0:15]
	ds_read_b128 v[194:197], v55 offset:54496
	ds_read_b128 v[198:201], v92 offset:224
	s_waitcnt lgkmcnt(6)
	v_mfma_f32_32x32x16_bf16 v[0:15], v[206:209], v[210:213], v[0:15]
	ds_read_b128 v[206:209], v55 offset:54528
	ds_read_b128 v[210:213], v92 offset:256
	s_waitcnt lgkmcnt(6)
	v_mfma_f32_32x32x16_bf16 v[0:15], v[88:91], v[100:103], v[0:15]
	ds_read_b128 v[88:91], v55 offset:54560
	ds_read_b128 v[100:103], v92 offset:288
	s_waitcnt lgkmcnt(6)
	v_mfma_f32_32x32x16_bf16 v[0:15], v[104:107], v[108:111], v[0:15]
	ds_read_b128 v[104:107], v55 offset:54592
	ds_read_b128 v[108:111], v92 offset:320
	s_waitcnt lgkmcnt(6)
	v_mfma_f32_32x32x16_bf16 v[0:15], v[194:197], v[198:201], v[0:15]
	ds_read_b128 v[194:197], v55 offset:54624
	ds_read_b128 v[198:201], v92 offset:352
	s_waitcnt lgkmcnt(6)
	v_mfma_f32_32x32x16_bf16 v[0:15], v[206:209], v[210:213], v[0:15]
	s_waitcnt lgkmcnt(4)
	v_mfma_f32_32x32x16_bf16 v[0:15], v[88:91], v[100:103], v[0:15]
	s_waitcnt lgkmcnt(2)
	v_mfma_f32_32x32x16_bf16 v[0:15], v[104:107], v[108:111], v[0:15]
	s_waitcnt lgkmcnt(0)
	v_mfma_f32_32x32x16_bf16 v[0:15], v[194:197], v[198:201], v[0:15]

.LBB0_4865:
	s_or_b64 exec, exec, s[26:27]
	v_or_b32_e32 v0, v73, v71
	v_mul_i32_i24_e32 v1, 0x190, v0
	v_lshlrev_b32_e32 v88, 4, v83
	v_mul_i32_i24_e32 v0, 0x90, v0
	v_add3_u32 v91, 0, v1, v88
	v_mul_lo_u32 v1, v54, s60
	v_add3_u32 v90, s62, v0, v88
	v_mul_lo_u32 v0, v54, s63
	v_add3_u32 v92, 0, v1, v88
	v_add3_u32 v89, s64, v0, v88
	v_mul_lo_u32 v0, v93, s60
	v_lshlrev_b32_e32 v1, 1, v64
	v_add3_u32 v96, 0, v0, v1
	v_mul_lo_u32 v0, v94, s60
	v_lshlrev_b32_e32 v1, 1, v66
	v_add3_u32 v97, 0, v0, v1
	v_mul_lo_u32 v0, v95, s60
	v_lshlrev_b32_e32 v1, 1, v68
	v_add3_u32 v98, 0, v0, v1
	v_mul_lo_u32 v0, v72, s63
	v_lshlrev_b32_e32 v1, 1, v99
	v_add3_u32 v72, s64, v0, v1
	v_mul_lo_u32 v0, v70, s63
	v_add3_u32 v70, s64, v0, v1
	v_add_u32_e32 v0, 0x80, v95
	v_mov_b64_e32 v[54:55], s[22:23]
	s_waitcnt lgkmcnt(0)
	s_barrier
	s_waitcnt vmcnt(7)
	ds_write_b128 v58, v[16:19]
	s_waitcnt vmcnt(6)
	ds_write_b128 v84, v[20:23]
	s_waitcnt vmcnt(5)
	ds_write_b128 v87, v[28:31]
	s_waitcnt vmcnt(4)
	ds_write_b128 v96, v[24:27]
	s_waitcnt vmcnt(3)
	ds_write_b128 v97, v[36:39]
	s_waitcnt vmcnt(2)
	ds_write_b128 v98, v[32:35]
	s_waitcnt vmcnt(1)
	ds_write_b16 v72, v44
	ds_write_b16_d16_hi v72, v44 offset:144
	ds_write_b16 v72, v45 offset:288
	ds_write_b16_d16_hi v72, v45 offset:432
	ds_write_b16 v72, v46 offset:576
	ds_write_b16_d16_hi v72, v46 offset:720
	ds_write_b16 v72, v47 offset:864
	ds_write_b16_d16_hi v72, v47 offset:1008
	s_waitcnt vmcnt(0)
	ds_write_b16 v70, v40
	ds_write_b16_d16_hi v70, v40 offset:144
	ds_write_b16 v70, v41 offset:288
	ds_write_b16_d16_hi v70, v41 offset:432
	ds_write_b16 v70, v42 offset:576
	ds_write_b16_d16_hi v70, v42 offset:720
	ds_write_b16 v70, v43 offset:864
	ds_write_b16_d16_hi v70, v43 offset:1008
	v_mad_i64_i32 v[0:1], s[2:3], v0, s54, v[54:55]
	v_lshlrev_b64 v[40:41], 1, v[68:69]
	v_lshl_add_u64 v[0:1], v[0:1], 0, v[40:41]
	s_waitcnt lgkmcnt(0)
	s_barrier
	global_load_dwordx4 v[16:19], v[0:1], off
	v_add_u32_e32 v0, 0x80, v94
	v_mad_i64_i32 v[0:1], s[2:3], v0, s54, v[54:55]
	v_lshlrev_b64 v[42:43], 1, v[66:67]
	v_lshl_add_u64 v[0:1], v[0:1], 0, v[42:43]
	global_load_dwordx4 v[20:23], v[0:1], off
	v_add_u32_e32 v0, 0x80, v93
	v_mad_i64_i32 v[0:1], s[2:3], v0, s54, v[54:55]
	v_lshlrev_b64 v[44:45], 1, v[64:65]
	v_lshl_add_u64 v[0:1], v[0:1], 0, v[44:45]
	global_load_dwordx4 v[24:27], v[0:1], off
	v_add_u32_e32 v0, 0x80, v81
	v_mad_i64_i32 v[0:1], s[2:3], v0, s54, v[54:55]
	v_lshlrev_b64 v[46:47], 1, v[52:53]
	v_lshl_add_u64 v[0:1], v[0:1], 0, v[46:47]
	global_load_dwordx4 v[28:31], v[0:1], off
	v_add_u32_e32 v0, 0x80, v80
	v_mad_i64_i32 v[0:1], s[2:3], v0, s54, v[54:55]
	v_lshlrev_b64 v[50:51], 1, v[50:51]
	v_lshl_add_u64 v[0:1], v[0:1], 0, v[50:51]
	global_load_dwordx4 v[32:35], v[0:1], off
	v_add_u32_e32 v0, 0x80, v79
	v_mad_i64_i32 v[0:1], s[2:3], v0, s54, v[54:55]
	v_lshlrev_b64 v[52:53], 1, v[48:49]
	v_lshl_add_u64 v[0:1], v[0:1], 0, v[52:53]
	global_load_dwordx4 v[36:39], v[0:1], off
	ds_read_b128 v[0:3], v91 offset:54272
	ds_read_b128 v[4:7], v92
	ds_read_b128 v[64:67], v91 offset:54304
	ds_read_b128 v[100:103], v92 offset:32
	ds_read_b128 v[104:107], v91 offset:54336
	ds_read_b128 v[108:111], v92 offset:64
	ds_read_b128 v[194:197], v91 offset:54368
	ds_read_b128 v[198:201], v92 offset:96
	s_waitcnt lgkmcnt(6)
	v_mfma_f32_32x32x16_bf16 v[0:15], v[0:3], v[4:7], 0
	ds_read_b128 v[206:209], v91 offset:54400
	ds_read_b128 v[210:213], v92 offset:128
	s_waitcnt lgkmcnt(6)
	v_mfma_f32_32x32x16_bf16 v[0:15], v[64:67], v[100:103], v[0:15]
	ds_read_b128 v[64:67], v91 offset:54432
	ds_read_b128 v[100:103], v92 offset:160
	s_waitcnt lgkmcnt(6)
	v_mfma_f32_32x32x16_bf16 v[0:15], v[104:107], v[108:111], v[0:15]
	ds_read_b128 v[104:107], v91 offset:54464
	ds_read_b128 v[108:111], v92 offset:192
	s_waitcnt lgkmcnt(6)
	v_mfma_f32_32x32x16_bf16 v[0:15], v[194:197], v[198:201], v[0:15]
	ds_read_b128 v[194:197], v91 offset:54496
	ds_read_b128 v[198:201], v92 offset:224
	s_waitcnt lgkmcnt(6)
	v_mfma_f32_32x32x16_bf16 v[0:15], v[206:209], v[210:213], v[0:15]
	ds_read_b128 v[206:209], v91 offset:54528
	ds_read_b128 v[210:213], v92 offset:256
	s_waitcnt lgkmcnt(6)
	v_mfma_f32_32x32x16_bf16 v[0:15], v[64:67], v[100:103], v[0:15]
	ds_read_b128 v[64:67], v91 offset:54560
	ds_read_b128 v[100:103], v92 offset:288
	s_waitcnt lgkmcnt(6)
	v_mfma_f32_32x32x16_bf16 v[0:15], v[104:107], v[108:111], v[0:15]
	ds_read_b128 v[104:107], v91 offset:54592
	ds_read_b128 v[108:111], v92 offset:320
	s_waitcnt lgkmcnt(6)
	v_mfma_f32_32x32x16_bf16 v[0:15], v[194:197], v[198:201], v[0:15]
	ds_read_b128 v[194:197], v91 offset:54624
	ds_read_b128 v[198:201], v92 offset:352
	s_waitcnt lgkmcnt(6)
	v_mfma_f32_32x32x16_bf16 v[0:15], v[206:209], v[210:213], v[0:15]
	ds_read_b128 v[206:209], v90
	s_waitcnt lgkmcnt(5)
	v_mfma_f32_32x32x16_bf16 v[0:15], v[64:67], v[100:103], v[0:15]
	ds_read_b128 v[210:213], v90 offset:32
	ds_read_b128 v[64:67], v89
	ds_read_b128 v[100:103], v89 offset:32
	s_waitcnt lgkmcnt(6)
	v_mfma_f32_32x32x16_bf16 v[0:15], v[104:107], v[108:111], v[0:15]
	ds_read_b128 v[104:107], v90 offset:64
	ds_read_b128 v[108:111], v89 offset:64
	s_waitcnt lgkmcnt(6)
	v_mfma_f32_32x32x16_bf16 v[0:15], v[194:197], v[198:201], v[0:15]
	ds_read_b128 v[194:197], v90 offset:96
	ds_read_b128 v[198:201], v89 offset:96
	s_waitcnt lgkmcnt(5)
	v_mfma_f32_32x32x16_bf16 v[0:15], v[206:209], v[64:67], v[0:15]
	s_waitcnt lgkmcnt(4)
	v_mfma_f32_32x32x16_bf16 v[0:15], v[210:213], v[100:103], v[0:15]
	s_waitcnt lgkmcnt(2)
	v_mfma_f32_32x32x16_bf16 v[0:15], v[104:107], v[108:111], v[0:15]
	s_waitcnt lgkmcnt(0)
	v_mfma_f32_32x32x16_bf16 v[0:15], v[194:197], v[198:201], v[0:15]
	global_load_dwordx4 v[64:67], v[62:63], off offset:3328
	global_load_dwordx4 v[100:103], v[60:61], off offset:3328
	s_barrier
	s_waitcnt vmcnt(2)
	ds_write_b128 v58, v[36:39]
	ds_write_b128 v84, v[32:35]
	ds_write_b128 v87, v[28:31]
	ds_write_b128 v96, v[24:27]
	ds_write_b128 v97, v[20:23]
	ds_write_b128 v98, v[16:19]
	s_waitcnt vmcnt(1)
	ds_write_b16 v72, v64
	ds_write_b16_d16_hi v72, v64 offset:144
	ds_write_b16 v72, v65 offset:288
	ds_write_b16_d16_hi v72, v65 offset:432
	ds_write_b16 v72, v66 offset:576
	ds_write_b16_d16_hi v72, v66 offset:720
	ds_write_b16 v72, v67 offset:864
	ds_write_b16_d16_hi v72, v67 offset:1008
	s_waitcnt vmcnt(0)
	ds_write_b16 v70, v100
	ds_write_b16_d16_hi v70, v100 offset:144
	ds_write_b16 v70, v101 offset:288
	ds_write_b16_d16_hi v70, v101 offset:432
	ds_write_b16 v70, v102 offset:576
	ds_write_b16_d16_hi v70, v102 offset:720
	ds_write_b16 v70, v103 offset:864
	ds_write_b16_d16_hi v70, v103 offset:1008
	v_add_u32_e32 v16, 0x100, v95
	v_mad_i64_i32 v[16:17], s[2:3], v16, s54, v[54:55]
	v_lshl_add_u64 v[16:17], v[16:17], 0, v[40:41]
	s_waitcnt lgkmcnt(0)
	s_barrier
	global_load_dwordx4 v[32:35], v[16:17], off
	v_add_u32_e32 v16, 0x100, v94
	v_mad_i64_i32 v[16:17], s[2:3], v16, s54, v[54:55]
	v_lshl_add_u64 v[16:17], v[16:17], 0, v[42:43]
	global_load_dwordx4 v[36:39], v[16:17], off
	v_add_u32_e32 v16, 0x100, v93
	v_mad_i64_i32 v[16:17], s[2:3], v16, s54, v[54:55]
	v_lshl_add_u64 v[16:17], v[16:17], 0, v[44:45]
	global_load_dwordx4 v[40:43], v[16:17], off
	v_add_u32_e32 v16, 0x100, v81
	v_mad_i64_i32 v[16:17], s[2:3], v16, s54, v[54:55]
	v_lshl_add_u64 v[16:17], v[16:17], 0, v[46:47]
	global_load_dwordx4 v[44:47], v[16:17], off
	v_add_u32_e32 v16, 0x100, v80
	v_mad_i64_i32 v[16:17], s[2:3], v16, s54, v[54:55]
	v_lshl_add_u64 v[16:17], v[16:17], 0, v[50:51]
	global_load_dwordx4 v[48:51], v[16:17], off
	v_add_u32_e32 v16, 0x100, v79
	v_mad_i64_i32 v[16:17], s[2:3], v16, s54, v[54:55]
	v_lshl_add_u64 v[16:17], v[16:17], 0, v[52:53]
	global_load_dwordx4 v[52:55], v[16:17], off
	ds_read_b128 v[16:19], v91 offset:54272
	ds_read_b128 v[20:23], v92
	ds_read_b128 v[64:67], v91 offset:54304
	ds_read_b128 v[100:103], v92 offset:32
	ds_read_b128 v[104:107], v91 offset:54336
	ds_read_b128 v[108:111], v92 offset:64
	ds_read_b128 v[194:197], v91 offset:54368
	ds_read_b128 v[198:201], v92 offset:96
	s_waitcnt lgkmcnt(6)
	v_mfma_f32_32x32x16_bf16 v[16:31], v[16:19], v[20:23], 0
	ds_read_b128 v[206:209], v91 offset:54400
	ds_read_b128 v[210:213], v92 offset:128
	s_waitcnt lgkmcnt(6)
	v_mfma_f32_32x32x16_bf16 v[16:31], v[64:67], v[100:103], v[16:31]
	ds_read_b128 v[64:67], v91 offset:54432
	ds_read_b128 v[100:103], v92 offset:160
	s_waitcnt lgkmcnt(6)
	v_mfma_f32_32x32x16_bf16 v[16:31], v[104:107], v[108:111], v[16:31]
	ds_read_b128 v[104:107], v91 offset:54464
	ds_read_b128 v[108:111], v92 offset:192
	s_waitcnt lgkmcnt(6)
	v_mfma_f32_32x32x16_bf16 v[16:31], v[194:197], v[198:201], v[16:31]
	ds_read_b128 v[194:197], v91 offset:54496
	ds_read_b128 v[198:201], v92 offset:224
	s_waitcnt lgkmcnt(6)
	v_mfma_f32_32x32x16_bf16 v[16:31], v[206:209], v[210:213], v[16:31]
	ds_read_b128 v[206:209], v91 offset:54528
	ds_read_b128 v[210:213], v92 offset:256
	s_waitcnt lgkmcnt(6)
	v_mfma_f32_32x32x16_bf16 v[16:31], v[64:67], v[100:103], v[16:31]
	ds_read_b128 v[64:67], v91 offset:54560
	ds_read_b128 v[100:103], v92 offset:288
	s_waitcnt lgkmcnt(6)
	v_mfma_f32_32x32x16_bf16 v[16:31], v[104:107], v[108:111], v[16:31]
	ds_read_b128 v[104:107], v91 offset:54592
	ds_read_b128 v[108:111], v92 offset:320
	s_waitcnt lgkmcnt(6)
	v_mfma_f32_32x32x16_bf16 v[16:31], v[194:197], v[198:201], v[16:31]
	ds_read_b128 v[194:197], v91 offset:54624
	ds_read_b128 v[198:201], v92 offset:352
	s_waitcnt lgkmcnt(6)
	v_mfma_f32_32x32x16_bf16 v[16:31], v[206:209], v[210:213], v[16:31]
	ds_read_b128 v[206:209], v90
	s_waitcnt lgkmcnt(5)
	v_mfma_f32_32x32x16_bf16 v[16:31], v[64:67], v[100:103], v[16:31]
	ds_read_b128 v[210:213], v90 offset:32
	ds_read_b128 v[64:67], v89
	ds_read_b128 v[100:103], v89 offset:32
	s_waitcnt lgkmcnt(6)
	v_mfma_f32_32x32x16_bf16 v[16:31], v[104:107], v[108:111], v[16:31]
	ds_read_b128 v[104:107], v90 offset:64
	ds_read_b128 v[108:111], v89 offset:64
	s_waitcnt lgkmcnt(6)
	v_mfma_f32_32x32x16_bf16 v[16:31], v[194:197], v[198:201], v[16:31]
	ds_read_b128 v[194:197], v90 offset:96
	ds_read_b128 v[198:201], v89 offset:96
	s_waitcnt lgkmcnt(5)
	v_mfma_f32_32x32x16_bf16 v[16:31], v[206:209], v[64:67], v[16:31]
	s_waitcnt lgkmcnt(4)
	v_mfma_f32_32x32x16_bf16 v[16:31], v[210:213], v[100:103], v[16:31]
	s_waitcnt lgkmcnt(2)
	v_mfma_f32_32x32x16_bf16 v[16:31], v[104:107], v[108:111], v[16:31]
	s_waitcnt lgkmcnt(0)
	v_mfma_f32_32x32x16_bf16 v[16:31], v[194:197], v[198:201], v[16:31]
	global_load_dwordx4 v[62:65], v[62:63], off offset:3584
	s_nop 0
	global_load_dwordx4 v[66:69], v[60:61], off offset:3584
	s_barrier
	s_waitcnt vmcnt(2)
	ds_write_b128 v58, v[52:55]
	ds_write_b128 v84, v[48:51]
	ds_write_b128 v87, v[44:47]
	ds_write_b128 v96, v[40:43]
	ds_write_b128 v97, v[36:39]
	ds_write_b128 v98, v[32:35]
	s_waitcnt vmcnt(1)
	ds_write_b16 v72, v62
	ds_write_b16_d16_hi v72, v62 offset:144
	ds_write_b16 v72, v63 offset:288
	ds_write_b16_d16_hi v72, v63 offset:432
	ds_write_b16 v72, v64 offset:576
	ds_write_b16_d16_hi v72, v64 offset:720
	ds_write_b16 v72, v65 offset:864
	ds_write_b16_d16_hi v72, v65 offset:1008
	s_waitcnt vmcnt(0)
	v_lshl_or_b32 v144, v83, 2, v73
	v_or_b32_e32 v145, s0, v71
	v_add_u32_e32 v145, v82, v145
	v_or_b32_e32 v144, s66, v144
	v_mul_lo_u32 v201, v144, s49
	v_lshlrev_b32_e32 v202, 12, v144
	v_lshl_add_u32 v201, v145, 1, v201
	v_lshl_add_u32 v202, v145, 1, v202
	v_lshlrev_b32_e32 v144, 2, v145
	global_load_dword v195, v144, s[34:35]
	global_load_dword v196, v144, s[34:35] offset:512
	global_load_dword v197, v144, s[34:35] offset:1024
	global_load_dword v198, v144, s[20:21]
	global_load_dword v199, v144, s[20:21] offset:512
	global_load_dword v200, v144, s[20:21] offset:1024
	v_add_u32_e32 v201, 0x1000, v201
	global_load_ushort v205, v201, s[36:37] offset:2048
	global_load_ushort v206, v201, s[36:37] offset:2304
	global_load_ushort v207, v201, s[36:37] offset:2560
	v_add_u32_e32 v201, 0x2a00, v201
	global_load_ushort v208, v201, s[36:37] offset:2048
	global_load_ushort v209, v201, s[36:37] offset:2304
	global_load_ushort v210, v201, s[36:37] offset:2560
	v_add_u32_e32 v201, 0x2a00, v201
	global_load_ushort v211, v201, s[36:37] offset:2048
	global_load_ushort v212, v201, s[36:37] offset:2304
	global_load_ushort v213, v201, s[36:37] offset:2560
	v_add_u32_e32 v201, 0x2a00, v201
	global_load_ushort v214, v201, s[36:37] offset:2048
	global_load_ushort v215, v201, s[36:37] offset:2304
	global_load_ushort v216, v201, s[36:37] offset:2560
	v_add_u32_e32 v201, 0xd200, v201
	global_load_ushort v217, v201, s[36:37] offset:2048
	global_load_ushort v218, v201, s[36:37] offset:2304
	global_load_ushort v219, v201, s[36:37] offset:2560
	v_add_u32_e32 v201, 0x2a00, v201
	global_load_ushort v220, v201, s[36:37] offset:2048
	global_load_ushort v221, v201, s[36:37] offset:2304
	global_load_ushort v222, v201, s[36:37] offset:2560
	v_add_u32_e32 v201, 0x2a00, v201
	global_load_ushort v223, v201, s[36:37] offset:2048
	global_load_ushort v224, v201, s[36:37] offset:2304
	global_load_ushort v225, v201, s[36:37] offset:2560
	v_add_u32_e32 v201, 0x2a00, v201
	global_load_ushort v226, v201, s[36:37] offset:2048
	global_load_ushort v227, v201, s[36:37] offset:2304
	global_load_ushort v228, v201, s[36:37] offset:2560
	v_add_u32_e32 v201, 0xd200, v201
	global_load_ushort v229, v201, s[36:37] offset:2048
	global_load_ushort v230, v201, s[36:37] offset:2304
	global_load_ushort v231, v201, s[36:37] offset:2560
	v_add_u32_e32 v201, 0x2a00, v201
	global_load_ushort v232, v201, s[36:37] offset:2048
	global_load_ushort v233, v201, s[36:37] offset:2304
	global_load_ushort v234, v201, s[36:37] offset:2560
	v_add_u32_e32 v201, 0x2a00, v201
	global_load_ushort v235, v201, s[36:37] offset:2048
	global_load_ushort v236, v201, s[36:37] offset:2304
	global_load_ushort v237, v201, s[36:37] offset:2560
	v_add_u32_e32 v201, 0x2a00, v201
	global_load_ushort v238, v201, s[36:37] offset:2048
	global_load_ushort v239, v201, s[36:37] offset:2304
	global_load_ushort v240, v201, s[36:37] offset:2560
	v_add_u32_e32 v201, 0xd200, v201
	global_load_ushort v241, v201, s[36:37] offset:2048
	global_load_ushort v242, v201, s[36:37] offset:2304
	global_load_ushort v243, v201, s[36:37] offset:2560
	v_add_u32_e32 v201, 0x2a00, v201
	global_load_ushort v244, v201, s[36:37] offset:2048
	global_load_ushort v245, v201, s[36:37] offset:2304
	global_load_ushort v246, v201, s[36:37] offset:2560
	v_add_u32_e32 v201, 0x2a00, v201
	global_load_ushort v247, v201, s[36:37] offset:2048
	global_load_ushort v248, v201, s[36:37] offset:2304
	global_load_ushort v249, v201, s[36:37] offset:2560
	v_add_u32_e32 v201, 0x2a00, v201
	global_load_ushort v250, v201, s[36:37] offset:2048
	global_load_ushort v251, v201, s[36:37] offset:2304
	global_load_ushort v194, v201, s[36:37] offset:2560
	ds_write_b16 v70, v66
	ds_write_b16_d16_hi v70, v66 offset:144
	ds_write_b16 v70, v67 offset:288
	ds_write_b16_d16_hi v70, v67 offset:432
	ds_write_b16 v70, v68 offset:576
	ds_write_b16_d16_hi v70, v68 offset:720
	ds_write_b16 v70, v69 offset:864
	ds_write_b16_d16_hi v70, v69 offset:1008
	s_waitcnt lgkmcnt(0)
	s_barrier
	ds_read_b128 v[32:35], v91 offset:54272
	ds_read_b128 v[36:39], v92
	ds_read_b128 v[48:51], v91 offset:54304
	ds_read_b128 v[52:55], v92 offset:32
	ds_read_b128 v[60:63], v91 offset:54336
	ds_read_b128 v[64:67], v92 offset:64
	s_waitcnt lgkmcnt(4)
	v_mfma_f32_32x32x16_bf16 v[32:47], v[32:35], v[36:39], 0
	s_waitcnt lgkmcnt(2)
	v_mfma_f32_32x32x16_bf16 v[32:47], v[48:51], v[52:55], v[32:47]
	ds_read_b128 v[48:51], v91 offset:54368
	ds_read_b128 v[52:55], v92 offset:96
	s_waitcnt lgkmcnt(2)
	v_mfma_f32_32x32x16_bf16 v[32:47], v[60:63], v[64:67], v[32:47]
	ds_read_b128 v[60:63], v91 offset:54400
	ds_read_b128 v[64:67], v92 offset:128
	s_waitcnt lgkmcnt(2)
	v_mfma_f32_32x32x16_bf16 v[32:47], v[48:51], v[52:55], v[32:47]
	ds_read_b128 v[48:51], v91 offset:54432
	ds_read_b128 v[52:55], v92 offset:160
	s_waitcnt lgkmcnt(2)
	v_mfma_f32_32x32x16_bf16 v[32:47], v[60:63], v[64:67], v[32:47]
	ds_read_b128 v[60:63], v91 offset:54464
	ds_read_b128 v[64:67], v92 offset:192
	s_waitcnt lgkmcnt(2)
	v_mfma_f32_32x32x16_bf16 v[32:47], v[48:51], v[52:55], v[32:47]
	ds_read_b128 v[48:51], v91 offset:54496
	ds_read_b128 v[52:55], v92 offset:224
	s_waitcnt lgkmcnt(2)
	v_mfma_f32_32x32x16_bf16 v[32:47], v[60:63], v[64:67], v[32:47]
	ds_read_b128 v[60:63], v91 offset:54528
	ds_read_b128 v[64:67], v92 offset:256
	s_waitcnt lgkmcnt(2)
	v_mfma_f32_32x32x16_bf16 v[32:47], v[48:51], v[52:55], v[32:47]
	ds_read_b128 v[48:51], v91 offset:54560
	ds_read_b128 v[52:55], v92 offset:288
	s_waitcnt lgkmcnt(2)
	v_mfma_f32_32x32x16_bf16 v[32:47], v[60:63], v[64:67], v[32:47]
	ds_read_b128 v[60:63], v91 offset:54592
	ds_read_b128 v[64:67], v92 offset:320
	s_waitcnt lgkmcnt(2)
	v_mfma_f32_32x32x16_bf16 v[32:47], v[48:51], v[52:55], v[32:47]
	ds_read_b128 v[48:51], v91 offset:54624
	ds_read_b128 v[52:55], v92 offset:352
	s_waitcnt lgkmcnt(2)
	v_mfma_f32_32x32x16_bf16 v[32:47], v[60:63], v[64:67], v[32:47]
	ds_read_b128 v[60:63], v90
	ds_read_b128 v[64:67], v90 offset:32
	s_waitcnt lgkmcnt(2)
	v_mfma_f32_32x32x16_bf16 v[32:47], v[48:51], v[52:55], v[32:47]
	ds_read_b128 v[48:51], v89
	ds_read_b128 v[52:55], v89 offset:32
	s_waitcnt lgkmcnt(1)
	v_mfma_f32_32x32x16_bf16 v[32:47], v[60:63], v[48:51], v[32:47]
	ds_read_b128 v[60:63], v90 offset:64
	ds_read_b128 v[48:51], v89 offset:64
	s_waitcnt lgkmcnt(2)
	v_mfma_f32_32x32x16_bf16 v[32:47], v[64:67], v[52:55], v[32:47]
	s_waitcnt lgkmcnt(0)
	v_mfma_f32_32x32x16_bf16 v[32:47], v[60:63], v[48:51], v[32:47]
	ds_read_b128 v[48:51], v90 offset:96
	ds_read_b128 v[52:55], v89 offset:96
	s_waitcnt lgkmcnt(0)
	s_barrier
	v_mfma_f32_32x32x16_bf16 v[32:47], v[48:51], v[52:55], v[32:47]
	v_xor_b32_e32 v69, 16, v204
	v_lshlrev_b32_e32 v49, 7, v85
	v_lshlrev_b32_e32 v69, 2, v69
	v_add3_u32 v49, v88, v86, v49
	v_lshl_add_u32 v70, v49, 2, 0
	v_add_u32_e32 v70, 0x20800, v70
	v_mul_f32_e32 v48, v16, v16
	v_mul_f32_e32 v49, v17, v17
	v_mul_f32_e32 v50, v18, v18
	v_mul_f32_e32 v51, v19, v19
	v_mul_f32_e32 v52, v20, v20
	v_mul_f32_e32 v53, v21, v21
	v_mul_f32_e32 v54, v22, v22
	v_mul_f32_e32 v55, v23, v23
	v_fmac_f32_e32 v48, v0, v0
	v_fmac_f32_e32 v49, v1, v1
	v_fmac_f32_e32 v50, v2, v2
	v_fmac_f32_e32 v51, v3, v3
	v_fmac_f32_e32 v52, v4, v4
	v_fmac_f32_e32 v53, v5, v5
	v_fmac_f32_e32 v54, v6, v6
	v_fmac_f32_e32 v55, v7, v7
	v_fmac_f32_e32 v48, v32, v32
	v_fmac_f32_e32 v49, v33, v33
	v_fmac_f32_e32 v50, v34, v34
	v_fmac_f32_e32 v51, v35, v35
	v_fmac_f32_e32 v52, v36, v36
	v_fmac_f32_e32 v53, v37, v37
	v_fmac_f32_e32 v54, v38, v38
	v_fmac_f32_e32 v55, v39, v39
	v_add_f32_dpp v48, v48, v48 quad_perm:[1,0,3,2] row_mask:0xf bank_mask:0xf
	v_add_f32_dpp v49, v49, v49 quad_perm:[1,0,3,2] row_mask:0xf bank_mask:0xf
	v_add_f32_dpp v50, v50, v50 quad_perm:[1,0,3,2] row_mask:0xf bank_mask:0xf
	v_add_f32_dpp v51, v51, v51 quad_perm:[1,0,3,2] row_mask:0xf bank_mask:0xf
	v_add_f32_dpp v52, v52, v52 quad_perm:[1,0,3,2] row_mask:0xf bank_mask:0xf
	v_add_f32_dpp v53, v53, v53 quad_perm:[1,0,3,2] row_mask:0xf bank_mask:0xf
	v_add_f32_dpp v54, v54, v54 quad_perm:[1,0,3,2] row_mask:0xf bank_mask:0xf
	v_add_f32_dpp v55, v55, v55 quad_perm:[1,0,3,2] row_mask:0xf bank_mask:0xf
	v_add_f32_dpp v48, v48, v48 quad_perm:[2,3,0,1] row_mask:0xf bank_mask:0xf
	v_add_f32_dpp v49, v49, v49 quad_perm:[2,3,0,1] row_mask:0xf bank_mask:0xf
	v_add_f32_dpp v50, v50, v50 quad_perm:[2,3,0,1] row_mask:0xf bank_mask:0xf
	v_add_f32_dpp v51, v51, v51 quad_perm:[2,3,0,1] row_mask:0xf bank_mask:0xf
	v_add_f32_dpp v52, v52, v52 quad_perm:[2,3,0,1] row_mask:0xf bank_mask:0xf
	v_add_f32_dpp v53, v53, v53 quad_perm:[2,3,0,1] row_mask:0xf bank_mask:0xf
	v_add_f32_dpp v54, v54, v54 quad_perm:[2,3,0,1] row_mask:0xf bank_mask:0xf
	v_add_f32_dpp v55, v55, v55 quad_perm:[2,3,0,1] row_mask:0xf bank_mask:0xf
	v_add_f32_dpp v48, v48, v48 row_ror:4 row_mask:0xf bank_mask:0xf
	v_add_f32_dpp v49, v49, v49 row_ror:4 row_mask:0xf bank_mask:0xf
	v_add_f32_dpp v50, v50, v50 row_ror:4 row_mask:0xf bank_mask:0xf
	v_add_f32_dpp v51, v51, v51 row_ror:4 row_mask:0xf bank_mask:0xf
	v_add_f32_dpp v52, v52, v52 row_ror:4 row_mask:0xf bank_mask:0xf
	v_add_f32_dpp v53, v53, v53 row_ror:4 row_mask:0xf bank_mask:0xf
	v_add_f32_dpp v54, v54, v54 row_ror:4 row_mask:0xf bank_mask:0xf
	v_add_f32_dpp v55, v55, v55 row_ror:4 row_mask:0xf bank_mask:0xf
	v_add_f32_dpp v48, v48, v48 row_ror:8 row_mask:0xf bank_mask:0xf
	v_add_f32_dpp v49, v49, v49 row_ror:8 row_mask:0xf bank_mask:0xf
	v_add_f32_dpp v50, v50, v50 row_ror:8 row_mask:0xf bank_mask:0xf
	v_add_f32_dpp v51, v51, v51 row_ror:8 row_mask:0xf bank_mask:0xf
	v_add_f32_dpp v52, v52, v52 row_ror:8 row_mask:0xf bank_mask:0xf
	v_add_f32_dpp v53, v53, v53 row_ror:8 row_mask:0xf bank_mask:0xf
	v_add_f32_dpp v54, v54, v54 row_ror:8 row_mask:0xf bank_mask:0xf
	v_add_f32_dpp v55, v55, v55 row_ror:8 row_mask:0xf bank_mask:0xf
	ds_bpermute_b32 v60, v69, v48
	ds_bpermute_b32 v61, v69, v49
	ds_bpermute_b32 v62, v69, v50
	ds_bpermute_b32 v63, v69, v51
	ds_bpermute_b32 v64, v69, v52
	ds_bpermute_b32 v65, v69, v53
	ds_bpermute_b32 v66, v69, v54
	ds_bpermute_b32 v67, v69, v55
	s_waitcnt lgkmcnt(0)
	v_cmp_eq_u32_e32 vcc, 0, v71
	s_and_saveexec_b64 s[22:23], vcc
	v_add_f32_e32 v60, v48, v60
	ds_write_b32 v70, v60
	v_add_f32_e32 v61, v49, v61
	ds_write_b32 v70, v61 offset:16
	v_add_f32_e32 v62, v50, v62
	ds_write_b32 v70, v62 offset:32
	v_add_f32_e32 v63, v51, v63
	ds_write_b32 v70, v63 offset:48
	v_add_f32_e32 v64, v52, v64
	ds_write_b32 v70, v64 offset:128
	v_add_f32_e32 v65, v53, v65
	ds_write_b32 v70, v65 offset:144
	v_add_f32_e32 v66, v54, v66
	ds_write_b32 v70, v66 offset:160
	v_add_f32_e32 v67, v55, v67
	ds_write_b32 v70, v67 offset:176
	s_or_b64 exec, exec, s[22:23]
	v_mul_f32_e32 v48, v24, v24
	v_mul_f32_e32 v49, v25, v25
	v_mul_f32_e32 v50, v26, v26
	v_mul_f32_e32 v51, v27, v27
	v_mul_f32_e32 v52, v28, v28
	v_mul_f32_e32 v53, v29, v29
	v_mul_f32_e32 v54, v30, v30
	v_mul_f32_e32 v55, v31, v31
	v_fmac_f32_e32 v48, v8, v8
	v_fmac_f32_e32 v49, v9, v9
	v_fmac_f32_e32 v50, v10, v10
	v_fmac_f32_e32 v51, v11, v11
	v_fmac_f32_e32 v52, v12, v12
	v_fmac_f32_e32 v53, v13, v13
	v_fmac_f32_e32 v54, v14, v14
	v_fmac_f32_e32 v55, v15, v15
	v_fmac_f32_e32 v48, v40, v40
	v_fmac_f32_e32 v49, v41, v41
	v_fmac_f32_e32 v50, v42, v42
	v_fmac_f32_e32 v51, v43, v43
	v_fmac_f32_e32 v52, v44, v44
	v_fmac_f32_e32 v53, v45, v45
	v_fmac_f32_e32 v54, v46, v46
	v_fmac_f32_e32 v55, v47, v47
	v_add_f32_dpp v48, v48, v48 quad_perm:[1,0,3,2] row_mask:0xf bank_mask:0xf
	v_add_f32_dpp v49, v49, v49 quad_perm:[1,0,3,2] row_mask:0xf bank_mask:0xf
	v_add_f32_dpp v50, v50, v50 quad_perm:[1,0,3,2] row_mask:0xf bank_mask:0xf
	v_add_f32_dpp v51, v51, v51 quad_perm:[1,0,3,2] row_mask:0xf bank_mask:0xf
	v_add_f32_dpp v52, v52, v52 quad_perm:[1,0,3,2] row_mask:0xf bank_mask:0xf
	v_add_f32_dpp v53, v53, v53 quad_perm:[1,0,3,2] row_mask:0xf bank_mask:0xf
	v_add_f32_dpp v54, v54, v54 quad_perm:[1,0,3,2] row_mask:0xf bank_mask:0xf
	v_add_f32_dpp v55, v55, v55 quad_perm:[1,0,3,2] row_mask:0xf bank_mask:0xf
	v_add_f32_dpp v48, v48, v48 quad_perm:[2,3,0,1] row_mask:0xf bank_mask:0xf
	v_add_f32_dpp v49, v49, v49 quad_perm:[2,3,0,1] row_mask:0xf bank_mask:0xf
	v_add_f32_dpp v50, v50, v50 quad_perm:[2,3,0,1] row_mask:0xf bank_mask:0xf
	v_add_f32_dpp v51, v51, v51 quad_perm:[2,3,0,1] row_mask:0xf bank_mask:0xf
	v_add_f32_dpp v52, v52, v52 quad_perm:[2,3,0,1] row_mask:0xf bank_mask:0xf
	v_add_f32_dpp v53, v53, v53 quad_perm:[2,3,0,1] row_mask:0xf bank_mask:0xf
	v_add_f32_dpp v54, v54, v54 quad_perm:[2,3,0,1] row_mask:0xf bank_mask:0xf
	v_add_f32_dpp v55, v55, v55 quad_perm:[2,3,0,1] row_mask:0xf bank_mask:0xf
	v_add_f32_dpp v48, v48, v48 row_ror:4 row_mask:0xf bank_mask:0xf
	v_add_f32_dpp v49, v49, v49 row_ror:4 row_mask:0xf bank_mask:0xf
	v_add_f32_dpp v50, v50, v50 row_ror:4 row_mask:0xf bank_mask:0xf
	v_add_f32_dpp v51, v51, v51 row_ror:4 row_mask:0xf bank_mask:0xf
	v_add_f32_dpp v52, v52, v52 row_ror:4 row_mask:0xf bank_mask:0xf
	v_add_f32_dpp v53, v53, v53 row_ror:4 row_mask:0xf bank_mask:0xf
	v_add_f32_dpp v54, v54, v54 row_ror:4 row_mask:0xf bank_mask:0xf
	v_add_f32_dpp v55, v55, v55 row_ror:4 row_mask:0xf bank_mask:0xf
	v_add_f32_dpp v48, v48, v48 row_ror:8 row_mask:0xf bank_mask:0xf
	v_add_f32_dpp v49, v49, v49 row_ror:8 row_mask:0xf bank_mask:0xf
	v_add_f32_dpp v50, v50, v50 row_ror:8 row_mask:0xf bank_mask:0xf
	v_add_f32_dpp v51, v51, v51 row_ror:8 row_mask:0xf bank_mask:0xf
	v_add_f32_dpp v52, v52, v52 row_ror:8 row_mask:0xf bank_mask:0xf
	v_add_f32_dpp v53, v53, v53 row_ror:8 row_mask:0xf bank_mask:0xf
	v_add_f32_dpp v54, v54, v54 row_ror:8 row_mask:0xf bank_mask:0xf
	v_add_f32_dpp v55, v55, v55 row_ror:8 row_mask:0xf bank_mask:0xf
	ds_bpermute_b32 v60, v69, v48
	ds_bpermute_b32 v61, v69, v49
	ds_bpermute_b32 v62, v69, v50
	ds_bpermute_b32 v63, v69, v51
	ds_bpermute_b32 v64, v69, v52
	ds_bpermute_b32 v65, v69, v53
	ds_bpermute_b32 v66, v69, v54
	ds_bpermute_b32 v67, v69, v55
	s_waitcnt lgkmcnt(0)
	v_cmp_eq_u32_e32 vcc, 0, v71
	s_and_saveexec_b64 s[22:23], vcc
	v_add_f32_e32 v60, v48, v60
	ds_write_b32 v70, v60 offset:256
	v_add_f32_e32 v61, v49, v61
	ds_write_b32 v70, v61 offset:272
	v_add_f32_e32 v62, v50, v62
	ds_write_b32 v70, v62 offset:288
	v_add_f32_e32 v63, v51, v63
	ds_write_b32 v70, v63 offset:304
	v_add_f32_e32 v64, v52, v64
	ds_write_b32 v70, v64 offset:384
	v_add_f32_e32 v65, v53, v65
	ds_write_b32 v70, v65 offset:400
	v_add_f32_e32 v66, v54, v66
	ds_write_b32 v70, v66 offset:416
	v_add_f32_e32 v67, v55, v67
	ds_write_b32 v70, v67 offset:432
	s_or_b64 exec, exec, s[22:23]
	v_lshl_or_b32 v62, v83, 2, v73
	v_or_b32_e32 v48, s0, v71
	v_add_u32_e32 v52, v82, v48
	v_or_b32_e32 v54, s66, v62
	v_mov_b64_e32 v[48:49], s[36:37]
	v_mad_i64_i32 v[48:49], s[0:1], v54, s49, v[48:49]
	v_ashrrev_i32_e32 v53, 31, v52
	v_lshl_add_u64 v[60:61], v[52:53], 1, v[48:49]
	v_add_co_u32_e32 v48, vcc, s50, v60
	s_waitcnt lgkmcnt(0)
	s_nop 0
	v_addc_co_u32_e32 v49, vcc, 0, v61, vcc
	s_barrier
	s_mov_b32 s98, 0x55555555
	s_mov_b32 s99, 0x55555555
	v_lshl_add_u32 v203, v62, 4, 0
	v_add_u32_e32 v203, 0x20800, v203
	ds_read_b128 v[64:67], v203
	s_waitcnt lgkmcnt(0)
	v_add_f32_e32 v68, v64, v65
	v_add_f32_e32 v69, v66, v67
	ds_read_b128 v[64:67], v203 offset:16
	v_add_f32_e32 v68, v68, v69
	v_fmamk_f32 v68, v68, 0x3b2aaaab, v76
	v_mul_f32_e32 v69, 0x4b800000, v68
	v_cmp_gt_f32_e32 vcc, s56, v68
	s_nop 1
	v_cndmask_b32_e32 v68, v68, v69, vcc
	v_rsq_f32_e32 v68, v68
	s_nop 0
	v_mul_f32_e32 v69, 0x45800000, v68
	v_cndmask_b32_e32 v63, v68, v69, vcc
	s_waitcnt vmcnt(47)
	v_lshlrev_b32_e32 v205, 16, v205
	v_add_f32_e32 v205, v195, v205
	v_mul_f32_e32 v68, 0xbfb8aa3b, v205
	v_exp_f32_e32 v68, v68
	v_mul_f32_e32 v0, v0, v63
	v_add_f32_e32 v68, 1.0, v68
	v_div_scale_f32 v69, s[0:1], v68, v68, v205
	v_div_scale_f32 v71, vcc, v205, v68, v205
	v_rcp_f32_e32 v70, v69
	v_mul_f32_e32 v0, v198, v0
	v_fma_f32 v50, -v69, v70, 1.0
	v_fmac_f32_e32 v70, v50, v70
	v_mul_f32_e32 v50, v71, v70
	v_fma_f32 v51, -v69, v50, v71
	v_fmac_f32_e32 v50, v51, v70
	v_fma_f32 v69, -v69, v50, v71
	v_div_fmas_f32 v69, v69, v70, v50
	v_div_fixup_f32 v205, v69, v68, v205
	v_mul_f32_e32 v0, v205, v0
	s_waitcnt vmcnt(46)
	v_lshlrev_b32_e32 v206, 16, v206
	v_add_f32_e32 v206, v196, v206
	v_mul_f32_e32 v68, 0xbfb8aa3b, v206
	v_exp_f32_e32 v68, v68
	v_mul_f32_e32 v16, v16, v63
	v_add_f32_e32 v68, 1.0, v68
	v_div_scale_f32 v69, s[0:1], v68, v68, v206
	v_div_scale_f32 v71, vcc, v206, v68, v206
	v_rcp_f32_e32 v70, v69
	v_mul_f32_e32 v16, v199, v16
	v_fma_f32 v50, -v69, v70, 1.0
	v_fmac_f32_e32 v70, v50, v70
	v_mul_f32_e32 v50, v71, v70
	v_fma_f32 v51, -v69, v50, v71
	v_fmac_f32_e32 v50, v51, v70
	v_fma_f32 v69, -v69, v50, v71
	v_div_fmas_f32 v69, v69, v70, v50
	v_div_fixup_f32 v206, v69, v68, v206
	v_mul_f32_e32 v16, v206, v16
	s_waitcnt vmcnt(45)
	v_lshlrev_b32_e32 v207, 16, v207
	v_add_f32_e32 v207, v197, v207
	v_mul_f32_e32 v68, 0xbfb8aa3b, v207
	v_exp_f32_e32 v68, v68
	v_mul_f32_e32 v32, v32, v63
	v_add_f32_e32 v68, 1.0, v68
	v_div_scale_f32 v69, s[0:1], v68, v68, v207
	v_div_scale_f32 v71, vcc, v207, v68, v207
	v_rcp_f32_e32 v70, v69
	v_mul_f32_e32 v32, v200, v32
	v_fma_f32 v50, -v69, v70, 1.0
	v_fmac_f32_e32 v70, v50, v70
	v_mul_f32_e32 v50, v71, v70
	v_fma_f32 v51, -v69, v50, v71
	v_fmac_f32_e32 v50, v51, v70
	v_fma_f32 v69, -v69, v50, v71
	v_div_fmas_f32 v69, v69, v70, v50
	v_div_fixup_f32 v207, v69, v68, v207
	v_mul_f32_e32 v32, v207, v32
	s_nop 1
	v_mov_b32_dpp v68, v0 quad_perm:[1,0,3,2] row_mask:0xf bank_mask:0xf
	v_mov_b32_dpp v69, v16 quad_perm:[1,0,3,2] row_mask:0xf bank_mask:0xf
	v_mov_b32_dpp v70, v32 quad_perm:[1,0,3,2] row_mask:0xf bank_mask:0xf
	s_nop 0
	v_cvt_pk_bf16_f32 v0, v0, v68
	v_cvt_pk_bf16_f32 v16, v16, v69
	v_cvt_pk_bf16_f32 v32, v32, v70
	s_mov_b64 exec, s[98:99]
	global_store_dword v202, v0, s[38:39]
	global_store_dword v202, v16, s[38:39] offset:256
	global_store_dword v202, v32, s[38:39] offset:512
	s_mov_b64 exec, -1
	v_add_u32_e32 v202, 0x1000, v202
	s_waitcnt lgkmcnt(0)
	v_add_f32_e32 v68, v64, v65
	v_add_f32_e32 v69, v66, v67
	ds_read_b128 v[64:67], v203 offset:32
	v_add_f32_e32 v68, v68, v69
	v_fmamk_f32 v68, v68, 0x3b2aaaab, v76
	v_mul_f32_e32 v69, 0x4b800000, v68
	v_cmp_gt_f32_e32 vcc, s56, v68
	s_nop 1
	v_cndmask_b32_e32 v68, v68, v69, vcc
	v_rsq_f32_e32 v68, v68
	s_nop 0
	v_mul_f32_e32 v69, 0x45800000, v68
	v_cndmask_b32_e32 v63, v68, v69, vcc
	s_waitcnt vmcnt(47)
	v_lshlrev_b32_e32 v208, 16, v208
	v_add_f32_e32 v208, v195, v208
	v_mul_f32_e32 v68, 0xbfb8aa3b, v208
	v_exp_f32_e32 v68, v68
	v_mul_f32_e32 v1, v1, v63
	v_add_f32_e32 v68, 1.0, v68
	v_div_scale_f32 v69, s[0:1], v68, v68, v208
	v_div_scale_f32 v71, vcc, v208, v68, v208
	v_rcp_f32_e32 v70, v69
	v_mul_f32_e32 v1, v198, v1
	v_fma_f32 v50, -v69, v70, 1.0
	v_fmac_f32_e32 v70, v50, v70
	v_mul_f32_e32 v50, v71, v70
	v_fma_f32 v51, -v69, v50, v71
	v_fmac_f32_e32 v50, v51, v70
	v_fma_f32 v69, -v69, v50, v71
	v_div_fmas_f32 v69, v69, v70, v50
	v_div_fixup_f32 v208, v69, v68, v208
	v_mul_f32_e32 v1, v208, v1
	s_waitcnt vmcnt(46)
	v_lshlrev_b32_e32 v209, 16, v209
	v_add_f32_e32 v209, v196, v209
	v_mul_f32_e32 v68, 0xbfb8aa3b, v209
	v_exp_f32_e32 v68, v68
	v_mul_f32_e32 v17, v17, v63
	v_add_f32_e32 v68, 1.0, v68
	v_div_scale_f32 v69, s[0:1], v68, v68, v209
	v_div_scale_f32 v71, vcc, v209, v68, v209
	v_rcp_f32_e32 v70, v69
	v_mul_f32_e32 v17, v199, v17
	v_fma_f32 v50, -v69, v70, 1.0
	v_fmac_f32_e32 v70, v50, v70
	v_mul_f32_e32 v50, v71, v70
	v_fma_f32 v51, -v69, v50, v71
	v_fmac_f32_e32 v50, v51, v70
	v_fma_f32 v69, -v69, v50, v71
	v_div_fmas_f32 v69, v69, v70, v50
	v_div_fixup_f32 v209, v69, v68, v209
	v_mul_f32_e32 v17, v209, v17
	s_waitcnt vmcnt(45)
	v_lshlrev_b32_e32 v210, 16, v210
	v_add_f32_e32 v210, v197, v210
	v_mul_f32_e32 v68, 0xbfb8aa3b, v210
	v_exp_f32_e32 v68, v68
	v_mul_f32_e32 v33, v33, v63
	v_add_f32_e32 v68, 1.0, v68
	v_div_scale_f32 v69, s[0:1], v68, v68, v210
	v_div_scale_f32 v71, vcc, v210, v68, v210
	v_rcp_f32_e32 v70, v69
	v_mul_f32_e32 v33, v200, v33
	v_fma_f32 v50, -v69, v70, 1.0
	v_fmac_f32_e32 v70, v50, v70
	v_mul_f32_e32 v50, v71, v70
	v_fma_f32 v51, -v69, v50, v71
	v_fmac_f32_e32 v50, v51, v70
	v_fma_f32 v69, -v69, v50, v71
	v_div_fmas_f32 v69, v69, v70, v50
	v_div_fixup_f32 v210, v69, v68, v210
	v_mul_f32_e32 v33, v210, v33
	s_nop 1
	v_mov_b32_dpp v68, v1 quad_perm:[1,0,3,2] row_mask:0xf bank_mask:0xf
	v_mov_b32_dpp v69, v17 quad_perm:[1,0,3,2] row_mask:0xf bank_mask:0xf
	v_mov_b32_dpp v70, v33 quad_perm:[1,0,3,2] row_mask:0xf bank_mask:0xf
	s_nop 0
	v_cvt_pk_bf16_f32 v1, v1, v68
	v_cvt_pk_bf16_f32 v17, v17, v69
	v_cvt_pk_bf16_f32 v33, v33, v70
	s_mov_b64 exec, s[98:99]
	global_store_dword v202, v1, s[38:39]
	global_store_dword v202, v17, s[38:39] offset:256
	global_store_dword v202, v33, s[38:39] offset:512
	s_mov_b64 exec, -1
	v_add_u32_e32 v202, 0x1000, v202
	s_waitcnt lgkmcnt(0)
	v_add_f32_e32 v68, v64, v65
	v_add_f32_e32 v69, v66, v67
	ds_read_b128 v[64:67], v203 offset:48
	v_add_f32_e32 v68, v68, v69
	v_fmamk_f32 v68, v68, 0x3b2aaaab, v76
	v_mul_f32_e32 v69, 0x4b800000, v68
	v_cmp_gt_f32_e32 vcc, s56, v68
	s_nop 1
	v_cndmask_b32_e32 v68, v68, v69, vcc
	v_rsq_f32_e32 v68, v68
	s_nop 0
	v_mul_f32_e32 v69, 0x45800000, v68
	v_cndmask_b32_e32 v63, v68, v69, vcc
	s_waitcnt vmcnt(47)
	v_lshlrev_b32_e32 v211, 16, v211
	v_add_f32_e32 v211, v195, v211
	v_mul_f32_e32 v68, 0xbfb8aa3b, v211
	v_exp_f32_e32 v68, v68
	v_mul_f32_e32 v2, v2, v63
	v_add_f32_e32 v68, 1.0, v68
	v_div_scale_f32 v69, s[0:1], v68, v68, v211
	v_div_scale_f32 v71, vcc, v211, v68, v211
	v_rcp_f32_e32 v70, v69
	v_mul_f32_e32 v2, v198, v2
	v_fma_f32 v50, -v69, v70, 1.0
	v_fmac_f32_e32 v70, v50, v70
	v_mul_f32_e32 v50, v71, v70
	v_fma_f32 v51, -v69, v50, v71
	v_fmac_f32_e32 v50, v51, v70
	v_fma_f32 v69, -v69, v50, v71
	v_div_fmas_f32 v69, v69, v70, v50
	v_div_fixup_f32 v211, v69, v68, v211
	v_mul_f32_e32 v2, v211, v2
	s_waitcnt vmcnt(46)
	v_lshlrev_b32_e32 v212, 16, v212
	v_add_f32_e32 v212, v196, v212
	v_mul_f32_e32 v68, 0xbfb8aa3b, v212
	v_exp_f32_e32 v68, v68
	v_mul_f32_e32 v18, v18, v63
	v_add_f32_e32 v68, 1.0, v68
	v_div_scale_f32 v69, s[0:1], v68, v68, v212
	v_div_scale_f32 v71, vcc, v212, v68, v212
	v_rcp_f32_e32 v70, v69
	v_mul_f32_e32 v18, v199, v18
	v_fma_f32 v50, -v69, v70, 1.0
	v_fmac_f32_e32 v70, v50, v70
	v_mul_f32_e32 v50, v71, v70
	v_fma_f32 v51, -v69, v50, v71
	v_fmac_f32_e32 v50, v51, v70
	v_fma_f32 v69, -v69, v50, v71
	v_div_fmas_f32 v69, v69, v70, v50
	v_div_fixup_f32 v212, v69, v68, v212
	v_mul_f32_e32 v18, v212, v18
	s_waitcnt vmcnt(45)
	v_lshlrev_b32_e32 v213, 16, v213
	v_add_f32_e32 v213, v197, v213
	v_mul_f32_e32 v68, 0xbfb8aa3b, v213
	v_exp_f32_e32 v68, v68
	v_mul_f32_e32 v34, v34, v63
	v_add_f32_e32 v68, 1.0, v68
	v_div_scale_f32 v69, s[0:1], v68, v68, v213
	v_div_scale_f32 v71, vcc, v213, v68, v213
	v_rcp_f32_e32 v70, v69
	v_mul_f32_e32 v34, v200, v34
	v_fma_f32 v50, -v69, v70, 1.0
	v_fmac_f32_e32 v70, v50, v70
	v_mul_f32_e32 v50, v71, v70
	v_fma_f32 v51, -v69, v50, v71
	v_fmac_f32_e32 v50, v51, v70
	v_fma_f32 v69, -v69, v50, v71
	v_div_fmas_f32 v69, v69, v70, v50
	v_div_fixup_f32 v213, v69, v68, v213
	v_mul_f32_e32 v34, v213, v34
	s_nop 1
	v_mov_b32_dpp v68, v2 quad_perm:[1,0,3,2] row_mask:0xf bank_mask:0xf
	v_mov_b32_dpp v69, v18 quad_perm:[1,0,3,2] row_mask:0xf bank_mask:0xf
	v_mov_b32_dpp v70, v34 quad_perm:[1,0,3,2] row_mask:0xf bank_mask:0xf
	s_nop 0
	v_cvt_pk_bf16_f32 v2, v2, v68
	v_cvt_pk_bf16_f32 v18, v18, v69
	v_cvt_pk_bf16_f32 v34, v34, v70
	s_mov_b64 exec, s[98:99]
	global_store_dword v202, v2, s[38:39]
	global_store_dword v202, v18, s[38:39] offset:256
	global_store_dword v202, v34, s[38:39] offset:512
	s_mov_b64 exec, -1
	v_add_u32_e32 v202, 0x1000, v202
	s_waitcnt lgkmcnt(0)
	v_add_f32_e32 v68, v64, v65
	v_add_f32_e32 v69, v66, v67
	ds_read_b128 v[64:67], v203 offset:128
	v_add_f32_e32 v68, v68, v69
	v_fmamk_f32 v68, v68, 0x3b2aaaab, v76
	v_mul_f32_e32 v69, 0x4b800000, v68
	v_cmp_gt_f32_e32 vcc, s56, v68
	s_nop 1
	v_cndmask_b32_e32 v68, v68, v69, vcc
	v_rsq_f32_e32 v68, v68
	s_nop 0
	v_mul_f32_e32 v69, 0x45800000, v68
	v_cndmask_b32_e32 v63, v68, v69, vcc
	s_waitcnt vmcnt(47)
	v_lshlrev_b32_e32 v214, 16, v214
	v_add_f32_e32 v214, v195, v214
	v_mul_f32_e32 v68, 0xbfb8aa3b, v214
	v_exp_f32_e32 v68, v68
	v_mul_f32_e32 v3, v3, v63
	v_add_f32_e32 v68, 1.0, v68
	v_div_scale_f32 v69, s[0:1], v68, v68, v214
	v_div_scale_f32 v71, vcc, v214, v68, v214
	v_rcp_f32_e32 v70, v69
	v_mul_f32_e32 v3, v198, v3
	v_fma_f32 v50, -v69, v70, 1.0
	v_fmac_f32_e32 v70, v50, v70
	v_mul_f32_e32 v50, v71, v70
	v_fma_f32 v51, -v69, v50, v71
	v_fmac_f32_e32 v50, v51, v70
	v_fma_f32 v69, -v69, v50, v71
	v_div_fmas_f32 v69, v69, v70, v50
	v_div_fixup_f32 v214, v69, v68, v214
	v_mul_f32_e32 v3, v214, v3
	s_waitcnt vmcnt(46)
	v_lshlrev_b32_e32 v215, 16, v215
	v_add_f32_e32 v215, v196, v215
	v_mul_f32_e32 v68, 0xbfb8aa3b, v215
	v_exp_f32_e32 v68, v68
	v_mul_f32_e32 v19, v19, v63
	v_add_f32_e32 v68, 1.0, v68
	v_div_scale_f32 v69, s[0:1], v68, v68, v215
	v_div_scale_f32 v71, vcc, v215, v68, v215
	v_rcp_f32_e32 v70, v69
	v_mul_f32_e32 v19, v199, v19
	v_fma_f32 v50, -v69, v70, 1.0
	v_fmac_f32_e32 v70, v50, v70
	v_mul_f32_e32 v50, v71, v70
	v_fma_f32 v51, -v69, v50, v71
	v_fmac_f32_e32 v50, v51, v70
	v_fma_f32 v69, -v69, v50, v71
	v_div_fmas_f32 v69, v69, v70, v50
	v_div_fixup_f32 v215, v69, v68, v215
	v_mul_f32_e32 v19, v215, v19
	s_waitcnt vmcnt(45)
	v_lshlrev_b32_e32 v216, 16, v216
	v_add_f32_e32 v216, v197, v216
	v_mul_f32_e32 v68, 0xbfb8aa3b, v216
	v_exp_f32_e32 v68, v68
	v_mul_f32_e32 v35, v35, v63
	v_add_f32_e32 v68, 1.0, v68
	v_div_scale_f32 v69, s[0:1], v68, v68, v216
	v_div_scale_f32 v71, vcc, v216, v68, v216
	v_rcp_f32_e32 v70, v69
	v_mul_f32_e32 v35, v200, v35
	v_fma_f32 v50, -v69, v70, 1.0
	v_fmac_f32_e32 v70, v50, v70
	v_mul_f32_e32 v50, v71, v70
	v_fma_f32 v51, -v69, v50, v71
	v_fmac_f32_e32 v50, v51, v70
	v_fma_f32 v69, -v69, v50, v71
	v_div_fmas_f32 v69, v69, v70, v50
	v_div_fixup_f32 v216, v69, v68, v216
	v_mul_f32_e32 v35, v216, v35
	s_nop 1
	v_mov_b32_dpp v68, v3 quad_perm:[1,0,3,2] row_mask:0xf bank_mask:0xf
	v_mov_b32_dpp v69, v19 quad_perm:[1,0,3,2] row_mask:0xf bank_mask:0xf
	v_mov_b32_dpp v70, v35 quad_perm:[1,0,3,2] row_mask:0xf bank_mask:0xf
	s_nop 0
	v_cvt_pk_bf16_f32 v3, v3, v68
	v_cvt_pk_bf16_f32 v19, v19, v69
	v_cvt_pk_bf16_f32 v35, v35, v70
	s_mov_b64 exec, s[98:99]
	global_store_dword v202, v3, s[38:39]
	global_store_dword v202, v19, s[38:39] offset:256
	global_store_dword v202, v35, s[38:39] offset:512
	s_mov_b64 exec, -1
	v_add_u32_e32 v202, 0x5000, v202
	s_waitcnt lgkmcnt(0)
	v_add_f32_e32 v68, v64, v65
	v_add_f32_e32 v69, v66, v67
	ds_read_b128 v[64:67], v203 offset:144
	v_add_f32_e32 v68, v68, v69
	v_fmamk_f32 v68, v68, 0x3b2aaaab, v76
	v_mul_f32_e32 v69, 0x4b800000, v68
	v_cmp_gt_f32_e32 vcc, s56, v68
	s_nop 1
	v_cndmask_b32_e32 v68, v68, v69, vcc
	v_rsq_f32_e32 v68, v68
	s_nop 0
	v_mul_f32_e32 v69, 0x45800000, v68
	v_cndmask_b32_e32 v63, v68, v69, vcc
	s_waitcnt vmcnt(47)
	v_lshlrev_b32_e32 v217, 16, v217
	v_add_f32_e32 v217, v195, v217
	v_mul_f32_e32 v68, 0xbfb8aa3b, v217
	v_exp_f32_e32 v68, v68
	v_mul_f32_e32 v4, v4, v63
	v_add_f32_e32 v68, 1.0, v68
	v_div_scale_f32 v69, s[0:1], v68, v68, v217
	v_div_scale_f32 v71, vcc, v217, v68, v217
	v_rcp_f32_e32 v70, v69
	v_mul_f32_e32 v4, v198, v4
	v_fma_f32 v50, -v69, v70, 1.0
	v_fmac_f32_e32 v70, v50, v70
	v_mul_f32_e32 v50, v71, v70
	v_fma_f32 v51, -v69, v50, v71
	v_fmac_f32_e32 v50, v51, v70
	v_fma_f32 v69, -v69, v50, v71
	v_div_fmas_f32 v69, v69, v70, v50
	v_div_fixup_f32 v217, v69, v68, v217
	v_mul_f32_e32 v4, v217, v4
	s_waitcnt vmcnt(46)
	v_lshlrev_b32_e32 v218, 16, v218
	v_add_f32_e32 v218, v196, v218
	v_mul_f32_e32 v68, 0xbfb8aa3b, v218
	v_exp_f32_e32 v68, v68
	v_mul_f32_e32 v20, v20, v63
	v_add_f32_e32 v68, 1.0, v68
	v_div_scale_f32 v69, s[0:1], v68, v68, v218
	v_div_scale_f32 v71, vcc, v218, v68, v218
	v_rcp_f32_e32 v70, v69
	v_mul_f32_e32 v20, v199, v20
	v_fma_f32 v50, -v69, v70, 1.0
	v_fmac_f32_e32 v70, v50, v70
	v_mul_f32_e32 v50, v71, v70
	v_fma_f32 v51, -v69, v50, v71
	v_fmac_f32_e32 v50, v51, v70
	v_fma_f32 v69, -v69, v50, v71
	v_div_fmas_f32 v69, v69, v70, v50
	v_div_fixup_f32 v218, v69, v68, v218
	v_mul_f32_e32 v20, v218, v20
	s_waitcnt vmcnt(45)
	v_lshlrev_b32_e32 v219, 16, v219
	v_add_f32_e32 v219, v197, v219
	v_mul_f32_e32 v68, 0xbfb8aa3b, v219
	v_exp_f32_e32 v68, v68
	v_mul_f32_e32 v36, v36, v63
	v_add_f32_e32 v68, 1.0, v68
	v_div_scale_f32 v69, s[0:1], v68, v68, v219
	v_div_scale_f32 v71, vcc, v219, v68, v219
	v_rcp_f32_e32 v70, v69
	v_mul_f32_e32 v36, v200, v36
	v_fma_f32 v50, -v69, v70, 1.0
	v_fmac_f32_e32 v70, v50, v70
	v_mul_f32_e32 v50, v71, v70
	v_fma_f32 v51, -v69, v50, v71
	v_fmac_f32_e32 v50, v51, v70
	v_fma_f32 v69, -v69, v50, v71
	v_div_fmas_f32 v69, v69, v70, v50
	v_div_fixup_f32 v219, v69, v68, v219
	v_mul_f32_e32 v36, v219, v36
	s_nop 1
	v_mov_b32_dpp v68, v4 quad_perm:[1,0,3,2] row_mask:0xf bank_mask:0xf
	v_mov_b32_dpp v69, v20 quad_perm:[1,0,3,2] row_mask:0xf bank_mask:0xf
	v_mov_b32_dpp v70, v36 quad_perm:[1,0,3,2] row_mask:0xf bank_mask:0xf
	s_nop 0
	v_cvt_pk_bf16_f32 v4, v4, v68
	v_cvt_pk_bf16_f32 v20, v20, v69
	v_cvt_pk_bf16_f32 v36, v36, v70
	s_mov_b64 exec, s[98:99]
	global_store_dword v202, v4, s[38:39]
	global_store_dword v202, v20, s[38:39] offset:256
	global_store_dword v202, v36, s[38:39] offset:512
	s_mov_b64 exec, -1
	v_add_u32_e32 v202, 0x1000, v202
	s_waitcnt lgkmcnt(0)
	v_add_f32_e32 v68, v64, v65
	v_add_f32_e32 v69, v66, v67
	ds_read_b128 v[64:67], v203 offset:160
	v_add_f32_e32 v68, v68, v69
	v_fmamk_f32 v68, v68, 0x3b2aaaab, v76
	v_mul_f32_e32 v69, 0x4b800000, v68
	v_cmp_gt_f32_e32 vcc, s56, v68
	s_nop 1
	v_cndmask_b32_e32 v68, v68, v69, vcc
	v_rsq_f32_e32 v68, v68
	s_nop 0
	v_mul_f32_e32 v69, 0x45800000, v68
	v_cndmask_b32_e32 v63, v68, v69, vcc
	s_waitcnt vmcnt(47)
	v_lshlrev_b32_e32 v220, 16, v220
	v_add_f32_e32 v220, v195, v220
	v_mul_f32_e32 v68, 0xbfb8aa3b, v220
	v_exp_f32_e32 v68, v68
	v_mul_f32_e32 v5, v5, v63
	v_add_f32_e32 v68, 1.0, v68
	v_div_scale_f32 v69, s[0:1], v68, v68, v220
	v_div_scale_f32 v71, vcc, v220, v68, v220
	v_rcp_f32_e32 v70, v69
	v_mul_f32_e32 v5, v198, v5
	v_fma_f32 v50, -v69, v70, 1.0
	v_fmac_f32_e32 v70, v50, v70
	v_mul_f32_e32 v50, v71, v70
	v_fma_f32 v51, -v69, v50, v71
	v_fmac_f32_e32 v50, v51, v70
	v_fma_f32 v69, -v69, v50, v71
	v_div_fmas_f32 v69, v69, v70, v50
	v_div_fixup_f32 v220, v69, v68, v220
	v_mul_f32_e32 v5, v220, v5
	s_waitcnt vmcnt(46)
	v_lshlrev_b32_e32 v221, 16, v221
	v_add_f32_e32 v221, v196, v221
	v_mul_f32_e32 v68, 0xbfb8aa3b, v221
	v_exp_f32_e32 v68, v68
	v_mul_f32_e32 v21, v21, v63
	v_add_f32_e32 v68, 1.0, v68
	v_div_scale_f32 v69, s[0:1], v68, v68, v221
	v_div_scale_f32 v71, vcc, v221, v68, v221
	v_rcp_f32_e32 v70, v69
	v_mul_f32_e32 v21, v199, v21
	v_fma_f32 v50, -v69, v70, 1.0
	v_fmac_f32_e32 v70, v50, v70
	v_mul_f32_e32 v50, v71, v70
	v_fma_f32 v51, -v69, v50, v71
	v_fmac_f32_e32 v50, v51, v70
	v_fma_f32 v69, -v69, v50, v71
	v_div_fmas_f32 v69, v69, v70, v50
	v_div_fixup_f32 v221, v69, v68, v221
	v_mul_f32_e32 v21, v221, v21
	s_waitcnt vmcnt(45)
	v_lshlrev_b32_e32 v222, 16, v222
	v_add_f32_e32 v222, v197, v222
	v_mul_f32_e32 v68, 0xbfb8aa3b, v222
	v_exp_f32_e32 v68, v68
	v_mul_f32_e32 v37, v37, v63
	v_add_f32_e32 v68, 1.0, v68
	v_div_scale_f32 v69, s[0:1], v68, v68, v222
	v_div_scale_f32 v71, vcc, v222, v68, v222
	v_rcp_f32_e32 v70, v69
	v_mul_f32_e32 v37, v200, v37
	v_fma_f32 v50, -v69, v70, 1.0
	v_fmac_f32_e32 v70, v50, v70
	v_mul_f32_e32 v50, v71, v70
	v_fma_f32 v51, -v69, v50, v71
	v_fmac_f32_e32 v50, v51, v70
	v_fma_f32 v69, -v69, v50, v71
	v_div_fmas_f32 v69, v69, v70, v50
	v_div_fixup_f32 v222, v69, v68, v222
	v_mul_f32_e32 v37, v222, v37
	s_nop 1
	v_mov_b32_dpp v68, v5 quad_perm:[1,0,3,2] row_mask:0xf bank_mask:0xf
	v_mov_b32_dpp v69, v21 quad_perm:[1,0,3,2] row_mask:0xf bank_mask:0xf
	v_mov_b32_dpp v70, v37 quad_perm:[1,0,3,2] row_mask:0xf bank_mask:0xf
	s_nop 0
	v_cvt_pk_bf16_f32 v5, v5, v68
	v_cvt_pk_bf16_f32 v21, v21, v69
	v_cvt_pk_bf16_f32 v37, v37, v70
	s_mov_b64 exec, s[98:99]
	global_store_dword v202, v5, s[38:39]
	global_store_dword v202, v21, s[38:39] offset:256
	global_store_dword v202, v37, s[38:39] offset:512
	s_mov_b64 exec, -1
	v_add_u32_e32 v202, 0x1000, v202
	s_waitcnt lgkmcnt(0)
	v_add_f32_e32 v68, v64, v65
	v_add_f32_e32 v69, v66, v67
	ds_read_b128 v[64:67], v203 offset:176
	v_add_f32_e32 v68, v68, v69
	v_fmamk_f32 v68, v68, 0x3b2aaaab, v76
	v_mul_f32_e32 v69, 0x4b800000, v68
	v_cmp_gt_f32_e32 vcc, s56, v68
	s_nop 1
	v_cndmask_b32_e32 v68, v68, v69, vcc
	v_rsq_f32_e32 v68, v68
	s_nop 0
	v_mul_f32_e32 v69, 0x45800000, v68
	v_cndmask_b32_e32 v63, v68, v69, vcc
	s_waitcnt vmcnt(47)
	v_lshlrev_b32_e32 v223, 16, v223
	v_add_f32_e32 v223, v195, v223
	v_mul_f32_e32 v68, 0xbfb8aa3b, v223
	v_exp_f32_e32 v68, v68
	v_mul_f32_e32 v6, v6, v63
	v_add_f32_e32 v68, 1.0, v68
	v_div_scale_f32 v69, s[0:1], v68, v68, v223
	v_div_scale_f32 v71, vcc, v223, v68, v223
	v_rcp_f32_e32 v70, v69
	v_mul_f32_e32 v6, v198, v6
	v_fma_f32 v50, -v69, v70, 1.0
	v_fmac_f32_e32 v70, v50, v70
	v_mul_f32_e32 v50, v71, v70
	v_fma_f32 v51, -v69, v50, v71
	v_fmac_f32_e32 v50, v51, v70
	v_fma_f32 v69, -v69, v50, v71
	v_div_fmas_f32 v69, v69, v70, v50
	v_div_fixup_f32 v223, v69, v68, v223
	v_mul_f32_e32 v6, v223, v6
	s_waitcnt vmcnt(46)
	v_lshlrev_b32_e32 v224, 16, v224
	v_add_f32_e32 v224, v196, v224
	v_mul_f32_e32 v68, 0xbfb8aa3b, v224
	v_exp_f32_e32 v68, v68
	v_mul_f32_e32 v22, v22, v63
	v_add_f32_e32 v68, 1.0, v68
	v_div_scale_f32 v69, s[0:1], v68, v68, v224
	v_div_scale_f32 v71, vcc, v224, v68, v224
	v_rcp_f32_e32 v70, v69
	v_mul_f32_e32 v22, v199, v22
	v_fma_f32 v50, -v69, v70, 1.0
	v_fmac_f32_e32 v70, v50, v70
	v_mul_f32_e32 v50, v71, v70
	v_fma_f32 v51, -v69, v50, v71
	v_fmac_f32_e32 v50, v51, v70
	v_fma_f32 v69, -v69, v50, v71
	v_div_fmas_f32 v69, v69, v70, v50
	v_div_fixup_f32 v224, v69, v68, v224
	v_mul_f32_e32 v22, v224, v22
	s_waitcnt vmcnt(45)
	v_lshlrev_b32_e32 v225, 16, v225
	v_add_f32_e32 v225, v197, v225
	v_mul_f32_e32 v68, 0xbfb8aa3b, v225
	v_exp_f32_e32 v68, v68
	v_mul_f32_e32 v38, v38, v63
	v_add_f32_e32 v68, 1.0, v68
	v_div_scale_f32 v69, s[0:1], v68, v68, v225
	v_div_scale_f32 v71, vcc, v225, v68, v225
	v_rcp_f32_e32 v70, v69
	v_mul_f32_e32 v38, v200, v38
	v_fma_f32 v50, -v69, v70, 1.0
	v_fmac_f32_e32 v70, v50, v70
	v_mul_f32_e32 v50, v71, v70
	v_fma_f32 v51, -v69, v50, v71
	v_fmac_f32_e32 v50, v51, v70
	v_fma_f32 v69, -v69, v50, v71
	v_div_fmas_f32 v69, v69, v70, v50
	v_div_fixup_f32 v225, v69, v68, v225
	v_mul_f32_e32 v38, v225, v38
	s_nop 1
	v_mov_b32_dpp v68, v6 quad_perm:[1,0,3,2] row_mask:0xf bank_mask:0xf
	v_mov_b32_dpp v69, v22 quad_perm:[1,0,3,2] row_mask:0xf bank_mask:0xf
	v_mov_b32_dpp v70, v38 quad_perm:[1,0,3,2] row_mask:0xf bank_mask:0xf
	s_nop 0
	v_cvt_pk_bf16_f32 v6, v6, v68
	v_cvt_pk_bf16_f32 v22, v22, v69
	v_cvt_pk_bf16_f32 v38, v38, v70
	s_mov_b64 exec, s[98:99]
	global_store_dword v202, v6, s[38:39]
	global_store_dword v202, v22, s[38:39] offset:256
	global_store_dword v202, v38, s[38:39] offset:512
	s_mov_b64 exec, -1
	v_add_u32_e32 v202, 0x1000, v202
	s_waitcnt lgkmcnt(0)
	v_add_f32_e32 v68, v64, v65
	v_add_f32_e32 v69, v66, v67
	ds_read_b128 v[64:67], v203 offset:256
	v_add_f32_e32 v68, v68, v69
	v_fmamk_f32 v68, v68, 0x3b2aaaab, v76
	v_mul_f32_e32 v69, 0x4b800000, v68
	v_cmp_gt_f32_e32 vcc, s56, v68
	s_nop 1
	v_cndmask_b32_e32 v68, v68, v69, vcc
	v_rsq_f32_e32 v68, v68
	s_nop 0
	v_mul_f32_e32 v69, 0x45800000, v68
	v_cndmask_b32_e32 v63, v68, v69, vcc
	s_waitcnt vmcnt(47)
	v_lshlrev_b32_e32 v226, 16, v226
	v_add_f32_e32 v226, v195, v226
	v_mul_f32_e32 v68, 0xbfb8aa3b, v226
	v_exp_f32_e32 v68, v68
	v_mul_f32_e32 v7, v7, v63
	v_add_f32_e32 v68, 1.0, v68
	v_div_scale_f32 v69, s[0:1], v68, v68, v226
	v_div_scale_f32 v71, vcc, v226, v68, v226
	v_rcp_f32_e32 v70, v69
	v_mul_f32_e32 v7, v198, v7
	v_fma_f32 v50, -v69, v70, 1.0
	v_fmac_f32_e32 v70, v50, v70
	v_mul_f32_e32 v50, v71, v70
	v_fma_f32 v51, -v69, v50, v71
	v_fmac_f32_e32 v50, v51, v70
	v_fma_f32 v69, -v69, v50, v71
	v_div_fmas_f32 v69, v69, v70, v50
	v_div_fixup_f32 v226, v69, v68, v226
	v_mul_f32_e32 v7, v226, v7
	s_waitcnt vmcnt(46)
	v_lshlrev_b32_e32 v227, 16, v227
	v_add_f32_e32 v227, v196, v227
	v_mul_f32_e32 v68, 0xbfb8aa3b, v227
	v_exp_f32_e32 v68, v68
	v_mul_f32_e32 v23, v23, v63
	v_add_f32_e32 v68, 1.0, v68
	v_div_scale_f32 v69, s[0:1], v68, v68, v227
	v_div_scale_f32 v71, vcc, v227, v68, v227
	v_rcp_f32_e32 v70, v69
	v_mul_f32_e32 v23, v199, v23
	v_fma_f32 v50, -v69, v70, 1.0
	v_fmac_f32_e32 v70, v50, v70
	v_mul_f32_e32 v50, v71, v70
	v_fma_f32 v51, -v69, v50, v71
	v_fmac_f32_e32 v50, v51, v70
	v_fma_f32 v69, -v69, v50, v71
	v_div_fmas_f32 v69, v69, v70, v50
	v_div_fixup_f32 v227, v69, v68, v227
	v_mul_f32_e32 v23, v227, v23
	s_waitcnt vmcnt(45)
	v_lshlrev_b32_e32 v228, 16, v228
	v_add_f32_e32 v228, v197, v228
	v_mul_f32_e32 v68, 0xbfb8aa3b, v228
	v_exp_f32_e32 v68, v68
	v_mul_f32_e32 v39, v39, v63
	v_add_f32_e32 v68, 1.0, v68
	v_div_scale_f32 v69, s[0:1], v68, v68, v228
	v_div_scale_f32 v71, vcc, v228, v68, v228
	v_rcp_f32_e32 v70, v69
	v_mul_f32_e32 v39, v200, v39
	v_fma_f32 v50, -v69, v70, 1.0
	v_fmac_f32_e32 v70, v50, v70
	v_mul_f32_e32 v50, v71, v70
	v_fma_f32 v51, -v69, v50, v71
	v_fmac_f32_e32 v50, v51, v70
	v_fma_f32 v69, -v69, v50, v71
	v_div_fmas_f32 v69, v69, v70, v50
	v_div_fixup_f32 v228, v69, v68, v228
	v_mul_f32_e32 v39, v228, v39
	s_nop 1
	v_mov_b32_dpp v68, v7 quad_perm:[1,0,3,2] row_mask:0xf bank_mask:0xf
	v_mov_b32_dpp v69, v23 quad_perm:[1,0,3,2] row_mask:0xf bank_mask:0xf
	v_mov_b32_dpp v70, v39 quad_perm:[1,0,3,2] row_mask:0xf bank_mask:0xf
	s_nop 0
	v_cvt_pk_bf16_f32 v7, v7, v68
	v_cvt_pk_bf16_f32 v23, v23, v69
	v_cvt_pk_bf16_f32 v39, v39, v70
	s_mov_b64 exec, s[98:99]
	global_store_dword v202, v7, s[38:39]
	global_store_dword v202, v23, s[38:39] offset:256
	global_store_dword v202, v39, s[38:39] offset:512
	s_mov_b64 exec, -1
	v_add_u32_e32 v202, 0x5000, v202
	s_waitcnt lgkmcnt(0)
	v_add_f32_e32 v68, v64, v65
	v_add_f32_e32 v69, v66, v67
	ds_read_b128 v[64:67], v203 offset:272
	v_add_f32_e32 v68, v68, v69
	v_fmamk_f32 v68, v68, 0x3b2aaaab, v76
	v_mul_f32_e32 v69, 0x4b800000, v68
	v_cmp_gt_f32_e32 vcc, s56, v68
	s_nop 1
	v_cndmask_b32_e32 v68, v68, v69, vcc
	v_rsq_f32_e32 v68, v68
	s_nop 0
	v_mul_f32_e32 v69, 0x45800000, v68
	v_cndmask_b32_e32 v63, v68, v69, vcc
	s_waitcnt vmcnt(47)
	v_lshlrev_b32_e32 v229, 16, v229
	v_add_f32_e32 v229, v195, v229
	v_mul_f32_e32 v68, 0xbfb8aa3b, v229
	v_exp_f32_e32 v68, v68
	v_mul_f32_e32 v8, v8, v63
	v_add_f32_e32 v68, 1.0, v68
	v_div_scale_f32 v69, s[0:1], v68, v68, v229
	v_div_scale_f32 v71, vcc, v229, v68, v229
	v_rcp_f32_e32 v70, v69
	v_mul_f32_e32 v8, v198, v8
	v_fma_f32 v50, -v69, v70, 1.0
	v_fmac_f32_e32 v70, v50, v70
	v_mul_f32_e32 v50, v71, v70
	v_fma_f32 v51, -v69, v50, v71
	v_fmac_f32_e32 v50, v51, v70
	v_fma_f32 v69, -v69, v50, v71
	v_div_fmas_f32 v69, v69, v70, v50
	v_div_fixup_f32 v229, v69, v68, v229
	v_mul_f32_e32 v8, v229, v8
	s_waitcnt vmcnt(46)
	v_lshlrev_b32_e32 v230, 16, v230
	v_add_f32_e32 v230, v196, v230
	v_mul_f32_e32 v68, 0xbfb8aa3b, v230
	v_exp_f32_e32 v68, v68
	v_mul_f32_e32 v24, v24, v63
	v_add_f32_e32 v68, 1.0, v68
	v_div_scale_f32 v69, s[0:1], v68, v68, v230
	v_div_scale_f32 v71, vcc, v230, v68, v230
	v_rcp_f32_e32 v70, v69
	v_mul_f32_e32 v24, v199, v24
	v_fma_f32 v50, -v69, v70, 1.0
	v_fmac_f32_e32 v70, v50, v70
	v_mul_f32_e32 v50, v71, v70
	v_fma_f32 v51, -v69, v50, v71
	v_fmac_f32_e32 v50, v51, v70
	v_fma_f32 v69, -v69, v50, v71
	v_div_fmas_f32 v69, v69, v70, v50
	v_div_fixup_f32 v230, v69, v68, v230
	v_mul_f32_e32 v24, v230, v24
	s_waitcnt vmcnt(45)
	v_lshlrev_b32_e32 v231, 16, v231
	v_add_f32_e32 v231, v197, v231
	v_mul_f32_e32 v68, 0xbfb8aa3b, v231
	v_exp_f32_e32 v68, v68
	v_mul_f32_e32 v40, v40, v63
	v_add_f32_e32 v68, 1.0, v68
	v_div_scale_f32 v69, s[0:1], v68, v68, v231
	v_div_scale_f32 v71, vcc, v231, v68, v231
	v_rcp_f32_e32 v70, v69
	v_mul_f32_e32 v40, v200, v40
	v_fma_f32 v50, -v69, v70, 1.0
	v_fmac_f32_e32 v70, v50, v70
	v_mul_f32_e32 v50, v71, v70
	v_fma_f32 v51, -v69, v50, v71
	v_fmac_f32_e32 v50, v51, v70
	v_fma_f32 v69, -v69, v50, v71
	v_div_fmas_f32 v69, v69, v70, v50
	v_div_fixup_f32 v231, v69, v68, v231
	v_mul_f32_e32 v40, v231, v40
	s_nop 1
	v_mov_b32_dpp v68, v8 quad_perm:[1,0,3,2] row_mask:0xf bank_mask:0xf
	v_mov_b32_dpp v69, v24 quad_perm:[1,0,3,2] row_mask:0xf bank_mask:0xf
	v_mov_b32_dpp v70, v40 quad_perm:[1,0,3,2] row_mask:0xf bank_mask:0xf
	s_nop 0
	v_cvt_pk_bf16_f32 v8, v8, v68
	v_cvt_pk_bf16_f32 v24, v24, v69
	v_cvt_pk_bf16_f32 v40, v40, v70
	s_mov_b64 exec, s[98:99]
	global_store_dword v202, v8, s[38:39]
	global_store_dword v202, v24, s[38:39] offset:256
	global_store_dword v202, v40, s[38:39] offset:512
	s_mov_b64 exec, -1
	v_add_u32_e32 v202, 0x1000, v202
	s_waitcnt lgkmcnt(0)
	v_add_f32_e32 v68, v64, v65
	v_add_f32_e32 v69, v66, v67
	ds_read_b128 v[64:67], v203 offset:288
	v_add_f32_e32 v68, v68, v69
	v_fmamk_f32 v68, v68, 0x3b2aaaab, v76
	v_mul_f32_e32 v69, 0x4b800000, v68
	v_cmp_gt_f32_e32 vcc, s56, v68
	s_nop 1
	v_cndmask_b32_e32 v68, v68, v69, vcc
	v_rsq_f32_e32 v68, v68
	s_nop 0
	v_mul_f32_e32 v69, 0x45800000, v68
	v_cndmask_b32_e32 v63, v68, v69, vcc
	s_waitcnt vmcnt(47)
	v_lshlrev_b32_e32 v232, 16, v232
	v_add_f32_e32 v232, v195, v232
	v_mul_f32_e32 v68, 0xbfb8aa3b, v232
	v_exp_f32_e32 v68, v68
	v_mul_f32_e32 v9, v9, v63
	v_add_f32_e32 v68, 1.0, v68
	v_div_scale_f32 v69, s[0:1], v68, v68, v232
	v_div_scale_f32 v71, vcc, v232, v68, v232
	v_rcp_f32_e32 v70, v69
	v_mul_f32_e32 v9, v198, v9
	v_fma_f32 v50, -v69, v70, 1.0
	v_fmac_f32_e32 v70, v50, v70
	v_mul_f32_e32 v50, v71, v70
	v_fma_f32 v51, -v69, v50, v71
	v_fmac_f32_e32 v50, v51, v70
	v_fma_f32 v69, -v69, v50, v71
	v_div_fmas_f32 v69, v69, v70, v50
	v_div_fixup_f32 v232, v69, v68, v232
	v_mul_f32_e32 v9, v232, v9
	s_waitcnt vmcnt(46)
	v_lshlrev_b32_e32 v233, 16, v233
	v_add_f32_e32 v233, v196, v233
	v_mul_f32_e32 v68, 0xbfb8aa3b, v233
	v_exp_f32_e32 v68, v68
	v_mul_f32_e32 v25, v25, v63
	v_add_f32_e32 v68, 1.0, v68
	v_div_scale_f32 v69, s[0:1], v68, v68, v233
	v_div_scale_f32 v71, vcc, v233, v68, v233
	v_rcp_f32_e32 v70, v69
	v_mul_f32_e32 v25, v199, v25
	v_fma_f32 v50, -v69, v70, 1.0
	v_fmac_f32_e32 v70, v50, v70
	v_mul_f32_e32 v50, v71, v70
	v_fma_f32 v51, -v69, v50, v71
	v_fmac_f32_e32 v50, v51, v70
	v_fma_f32 v69, -v69, v50, v71
	v_div_fmas_f32 v69, v69, v70, v50
	v_div_fixup_f32 v233, v69, v68, v233
	v_mul_f32_e32 v25, v233, v25
	s_waitcnt vmcnt(45)
	v_lshlrev_b32_e32 v234, 16, v234
	v_add_f32_e32 v234, v197, v234
	v_mul_f32_e32 v68, 0xbfb8aa3b, v234
	v_exp_f32_e32 v68, v68
	v_mul_f32_e32 v41, v41, v63
	v_add_f32_e32 v68, 1.0, v68
	v_div_scale_f32 v69, s[0:1], v68, v68, v234
	v_div_scale_f32 v71, vcc, v234, v68, v234
	v_rcp_f32_e32 v70, v69
	v_mul_f32_e32 v41, v200, v41
	v_fma_f32 v50, -v69, v70, 1.0
	v_fmac_f32_e32 v70, v50, v70
	v_mul_f32_e32 v50, v71, v70
	v_fma_f32 v51, -v69, v50, v71
	v_fmac_f32_e32 v50, v51, v70
	v_fma_f32 v69, -v69, v50, v71
	v_div_fmas_f32 v69, v69, v70, v50
	v_div_fixup_f32 v234, v69, v68, v234
	v_mul_f32_e32 v41, v234, v41
	s_nop 1
	v_mov_b32_dpp v68, v9 quad_perm:[1,0,3,2] row_mask:0xf bank_mask:0xf
	v_mov_b32_dpp v69, v25 quad_perm:[1,0,3,2] row_mask:0xf bank_mask:0xf
	v_mov_b32_dpp v70, v41 quad_perm:[1,0,3,2] row_mask:0xf bank_mask:0xf
	s_nop 0
	v_cvt_pk_bf16_f32 v9, v9, v68
	v_cvt_pk_bf16_f32 v25, v25, v69
	v_cvt_pk_bf16_f32 v41, v41, v70
	s_mov_b64 exec, s[98:99]
	global_store_dword v202, v9, s[38:39]
	global_store_dword v202, v25, s[38:39] offset:256
	global_store_dword v202, v41, s[38:39] offset:512
	s_mov_b64 exec, -1
	v_add_u32_e32 v202, 0x1000, v202
	s_waitcnt lgkmcnt(0)
	v_add_f32_e32 v68, v64, v65
	v_add_f32_e32 v69, v66, v67
	ds_read_b128 v[64:67], v203 offset:304
	v_add_f32_e32 v68, v68, v69
	v_fmamk_f32 v68, v68, 0x3b2aaaab, v76
	v_mul_f32_e32 v69, 0x4b800000, v68
	v_cmp_gt_f32_e32 vcc, s56, v68
	s_nop 1
	v_cndmask_b32_e32 v68, v68, v69, vcc
	v_rsq_f32_e32 v68, v68
	s_nop 0
	v_mul_f32_e32 v69, 0x45800000, v68
	v_cndmask_b32_e32 v63, v68, v69, vcc
	s_waitcnt vmcnt(47)
	v_lshlrev_b32_e32 v235, 16, v235
	v_add_f32_e32 v235, v195, v235
	v_mul_f32_e32 v68, 0xbfb8aa3b, v235
	v_exp_f32_e32 v68, v68
	v_mul_f32_e32 v10, v10, v63
	v_add_f32_e32 v68, 1.0, v68
	v_div_scale_f32 v69, s[0:1], v68, v68, v235
	v_div_scale_f32 v71, vcc, v235, v68, v235
	v_rcp_f32_e32 v70, v69
	v_mul_f32_e32 v10, v198, v10
	v_fma_f32 v50, -v69, v70, 1.0
	v_fmac_f32_e32 v70, v50, v70
	v_mul_f32_e32 v50, v71, v70
	v_fma_f32 v51, -v69, v50, v71
	v_fmac_f32_e32 v50, v51, v70
	v_fma_f32 v69, -v69, v50, v71
	v_div_fmas_f32 v69, v69, v70, v50
	v_div_fixup_f32 v235, v69, v68, v235
	v_mul_f32_e32 v10, v235, v10
	s_waitcnt vmcnt(46)
	v_lshlrev_b32_e32 v236, 16, v236
	v_add_f32_e32 v236, v196, v236
	v_mul_f32_e32 v68, 0xbfb8aa3b, v236
	v_exp_f32_e32 v68, v68
	v_mul_f32_e32 v26, v26, v63
	v_add_f32_e32 v68, 1.0, v68
	v_div_scale_f32 v69, s[0:1], v68, v68, v236
	v_div_scale_f32 v71, vcc, v236, v68, v236
	v_rcp_f32_e32 v70, v69
	v_mul_f32_e32 v26, v199, v26
	v_fma_f32 v50, -v69, v70, 1.0
	v_fmac_f32_e32 v70, v50, v70
	v_mul_f32_e32 v50, v71, v70
	v_fma_f32 v51, -v69, v50, v71
	v_fmac_f32_e32 v50, v51, v70
	v_fma_f32 v69, -v69, v50, v71
	v_div_fmas_f32 v69, v69, v70, v50
	v_div_fixup_f32 v236, v69, v68, v236
	v_mul_f32_e32 v26, v236, v26
	s_waitcnt vmcnt(45)
	v_lshlrev_b32_e32 v237, 16, v237
	v_add_f32_e32 v237, v197, v237
	v_mul_f32_e32 v68, 0xbfb8aa3b, v237
	v_exp_f32_e32 v68, v68
	v_mul_f32_e32 v42, v42, v63
	v_add_f32_e32 v68, 1.0, v68
	v_div_scale_f32 v69, s[0:1], v68, v68, v237
	v_div_scale_f32 v71, vcc, v237, v68, v237
	v_rcp_f32_e32 v70, v69
	v_mul_f32_e32 v42, v200, v42
	v_fma_f32 v50, -v69, v70, 1.0
	v_fmac_f32_e32 v70, v50, v70
	v_mul_f32_e32 v50, v71, v70
	v_fma_f32 v51, -v69, v50, v71
	v_fmac_f32_e32 v50, v51, v70
	v_fma_f32 v69, -v69, v50, v71
	v_div_fmas_f32 v69, v69, v70, v50
	v_div_fixup_f32 v237, v69, v68, v237
	v_mul_f32_e32 v42, v237, v42
	s_nop 1
	v_mov_b32_dpp v68, v10 quad_perm:[1,0,3,2] row_mask:0xf bank_mask:0xf
	v_mov_b32_dpp v69, v26 quad_perm:[1,0,3,2] row_mask:0xf bank_mask:0xf
	v_mov_b32_dpp v70, v42 quad_perm:[1,0,3,2] row_mask:0xf bank_mask:0xf
	s_nop 0
	v_cvt_pk_bf16_f32 v10, v10, v68
	v_cvt_pk_bf16_f32 v26, v26, v69
	v_cvt_pk_bf16_f32 v42, v42, v70
	s_mov_b64 exec, s[98:99]
	global_store_dword v202, v10, s[38:39]
	global_store_dword v202, v26, s[38:39] offset:256
	global_store_dword v202, v42, s[38:39] offset:512
	s_mov_b64 exec, -1
	v_add_u32_e32 v202, 0x1000, v202
	s_waitcnt lgkmcnt(0)
	v_add_f32_e32 v68, v64, v65
	v_add_f32_e32 v69, v66, v67
	ds_read_b128 v[64:67], v203 offset:384
	v_add_f32_e32 v68, v68, v69
	v_fmamk_f32 v68, v68, 0x3b2aaaab, v76
	v_mul_f32_e32 v69, 0x4b800000, v68
	v_cmp_gt_f32_e32 vcc, s56, v68
	s_nop 1
	v_cndmask_b32_e32 v68, v68, v69, vcc
	v_rsq_f32_e32 v68, v68
	s_nop 0
	v_mul_f32_e32 v69, 0x45800000, v68
	v_cndmask_b32_e32 v63, v68, v69, vcc
	s_waitcnt vmcnt(47)
	v_lshlrev_b32_e32 v238, 16, v238
	v_add_f32_e32 v238, v195, v238
	v_mul_f32_e32 v68, 0xbfb8aa3b, v238
	v_exp_f32_e32 v68, v68
	v_mul_f32_e32 v11, v11, v63
	v_add_f32_e32 v68, 1.0, v68
	v_div_scale_f32 v69, s[0:1], v68, v68, v238
	v_div_scale_f32 v71, vcc, v238, v68, v238
	v_rcp_f32_e32 v70, v69
	v_mul_f32_e32 v11, v198, v11
	v_fma_f32 v50, -v69, v70, 1.0
	v_fmac_f32_e32 v70, v50, v70
	v_mul_f32_e32 v50, v71, v70
	v_fma_f32 v51, -v69, v50, v71
	v_fmac_f32_e32 v50, v51, v70
	v_fma_f32 v69, -v69, v50, v71
	v_div_fmas_f32 v69, v69, v70, v50
	v_div_fixup_f32 v238, v69, v68, v238
	v_mul_f32_e32 v11, v238, v11
	s_waitcnt vmcnt(46)
	v_lshlrev_b32_e32 v239, 16, v239
	v_add_f32_e32 v239, v196, v239
	v_mul_f32_e32 v68, 0xbfb8aa3b, v239
	v_exp_f32_e32 v68, v68
	v_mul_f32_e32 v27, v27, v63
	v_add_f32_e32 v68, 1.0, v68
	v_div_scale_f32 v69, s[0:1], v68, v68, v239
	v_div_scale_f32 v71, vcc, v239, v68, v239
	v_rcp_f32_e32 v70, v69
	v_mul_f32_e32 v27, v199, v27
	v_fma_f32 v50, -v69, v70, 1.0
	v_fmac_f32_e32 v70, v50, v70
	v_mul_f32_e32 v50, v71, v70
	v_fma_f32 v51, -v69, v50, v71
	v_fmac_f32_e32 v50, v51, v70
	v_fma_f32 v69, -v69, v50, v71
	v_div_fmas_f32 v69, v69, v70, v50
	v_div_fixup_f32 v239, v69, v68, v239
	v_mul_f32_e32 v27, v239, v27
	s_waitcnt vmcnt(45)
	v_lshlrev_b32_e32 v240, 16, v240
	v_add_f32_e32 v240, v197, v240
	v_mul_f32_e32 v68, 0xbfb8aa3b, v240
	v_exp_f32_e32 v68, v68
	v_mul_f32_e32 v43, v43, v63
	v_add_f32_e32 v68, 1.0, v68
	v_div_scale_f32 v69, s[0:1], v68, v68, v240
	v_div_scale_f32 v71, vcc, v240, v68, v240
	v_rcp_f32_e32 v70, v69
	v_mul_f32_e32 v43, v200, v43
	v_fma_f32 v50, -v69, v70, 1.0
	v_fmac_f32_e32 v70, v50, v70
	v_mul_f32_e32 v50, v71, v70
	v_fma_f32 v51, -v69, v50, v71
	v_fmac_f32_e32 v50, v51, v70
	v_fma_f32 v69, -v69, v50, v71
	v_div_fmas_f32 v69, v69, v70, v50
	v_div_fixup_f32 v240, v69, v68, v240
	v_mul_f32_e32 v43, v240, v43
	s_nop 1
	v_mov_b32_dpp v68, v11 quad_perm:[1,0,3,2] row_mask:0xf bank_mask:0xf
	v_mov_b32_dpp v69, v27 quad_perm:[1,0,3,2] row_mask:0xf bank_mask:0xf
	v_mov_b32_dpp v70, v43 quad_perm:[1,0,3,2] row_mask:0xf bank_mask:0xf
	s_nop 0
	v_cvt_pk_bf16_f32 v11, v11, v68
	v_cvt_pk_bf16_f32 v27, v27, v69
	v_cvt_pk_bf16_f32 v43, v43, v70
	s_mov_b64 exec, s[98:99]
	global_store_dword v202, v11, s[38:39]
	global_store_dword v202, v27, s[38:39] offset:256
	global_store_dword v202, v43, s[38:39] offset:512
	s_mov_b64 exec, -1
	v_add_u32_e32 v202, 0x5000, v202
	s_waitcnt lgkmcnt(0)
	v_add_f32_e32 v68, v64, v65
	v_add_f32_e32 v69, v66, v67
	ds_read_b128 v[64:67], v203 offset:400
	v_add_f32_e32 v68, v68, v69
	v_fmamk_f32 v68, v68, 0x3b2aaaab, v76
	v_mul_f32_e32 v69, 0x4b800000, v68
	v_cmp_gt_f32_e32 vcc, s56, v68
	s_nop 1
	v_cndmask_b32_e32 v68, v68, v69, vcc
	v_rsq_f32_e32 v68, v68
	s_nop 0
	v_mul_f32_e32 v69, 0x45800000, v68
	v_cndmask_b32_e32 v63, v68, v69, vcc
	s_waitcnt vmcnt(47)
	v_lshlrev_b32_e32 v241, 16, v241
	v_add_f32_e32 v241, v195, v241
	v_mul_f32_e32 v68, 0xbfb8aa3b, v241
	v_exp_f32_e32 v68, v68
	v_mul_f32_e32 v12, v12, v63
	v_add_f32_e32 v68, 1.0, v68
	v_div_scale_f32 v69, s[0:1], v68, v68, v241
	v_div_scale_f32 v71, vcc, v241, v68, v241
	v_rcp_f32_e32 v70, v69
	v_mul_f32_e32 v12, v198, v12
	v_fma_f32 v50, -v69, v70, 1.0
	v_fmac_f32_e32 v70, v50, v70
	v_mul_f32_e32 v50, v71, v70
	v_fma_f32 v51, -v69, v50, v71
	v_fmac_f32_e32 v50, v51, v70
	v_fma_f32 v69, -v69, v50, v71
	v_div_fmas_f32 v69, v69, v70, v50
	v_div_fixup_f32 v241, v69, v68, v241
	v_mul_f32_e32 v12, v241, v12
	s_waitcnt vmcnt(46)
	v_lshlrev_b32_e32 v242, 16, v242
	v_add_f32_e32 v242, v196, v242
	v_mul_f32_e32 v68, 0xbfb8aa3b, v242
	v_exp_f32_e32 v68, v68
	v_mul_f32_e32 v28, v28, v63
	v_add_f32_e32 v68, 1.0, v68
	v_div_scale_f32 v69, s[0:1], v68, v68, v242
	v_div_scale_f32 v71, vcc, v242, v68, v242
	v_rcp_f32_e32 v70, v69
	v_mul_f32_e32 v28, v199, v28
	v_fma_f32 v50, -v69, v70, 1.0
	v_fmac_f32_e32 v70, v50, v70
	v_mul_f32_e32 v50, v71, v70
	v_fma_f32 v51, -v69, v50, v71
	v_fmac_f32_e32 v50, v51, v70
	v_fma_f32 v69, -v69, v50, v71
	v_div_fmas_f32 v69, v69, v70, v50
	v_div_fixup_f32 v242, v69, v68, v242
	v_mul_f32_e32 v28, v242, v28
	s_waitcnt vmcnt(45)
	v_lshlrev_b32_e32 v243, 16, v243
	v_add_f32_e32 v243, v197, v243
	v_mul_f32_e32 v68, 0xbfb8aa3b, v243
	v_exp_f32_e32 v68, v68
	v_mul_f32_e32 v44, v44, v63
	v_add_f32_e32 v68, 1.0, v68
	v_div_scale_f32 v69, s[0:1], v68, v68, v243
	v_div_scale_f32 v71, vcc, v243, v68, v243
	v_rcp_f32_e32 v70, v69
	v_mul_f32_e32 v44, v200, v44
	v_fma_f32 v50, -v69, v70, 1.0
	v_fmac_f32_e32 v70, v50, v70
	v_mul_f32_e32 v50, v71, v70
	v_fma_f32 v51, -v69, v50, v71
	v_fmac_f32_e32 v50, v51, v70
	v_fma_f32 v69, -v69, v50, v71
	v_div_fmas_f32 v69, v69, v70, v50
	v_div_fixup_f32 v243, v69, v68, v243
	v_mul_f32_e32 v44, v243, v44
	s_nop 1
	v_mov_b32_dpp v68, v12 quad_perm:[1,0,3,2] row_mask:0xf bank_mask:0xf
	v_mov_b32_dpp v69, v28 quad_perm:[1,0,3,2] row_mask:0xf bank_mask:0xf
	v_mov_b32_dpp v70, v44 quad_perm:[1,0,3,2] row_mask:0xf bank_mask:0xf
	s_nop 0
	v_cvt_pk_bf16_f32 v12, v12, v68
	v_cvt_pk_bf16_f32 v28, v28, v69
	v_cvt_pk_bf16_f32 v44, v44, v70
	s_mov_b64 exec, s[98:99]
	global_store_dword v202, v12, s[38:39]
	global_store_dword v202, v28, s[38:39] offset:256
	global_store_dword v202, v44, s[38:39] offset:512
	s_mov_b64 exec, -1
	v_add_u32_e32 v202, 0x1000, v202
	s_waitcnt lgkmcnt(0)
	v_add_f32_e32 v68, v64, v65
	v_add_f32_e32 v69, v66, v67
	ds_read_b128 v[64:67], v203 offset:416
	v_add_f32_e32 v68, v68, v69
	v_fmamk_f32 v68, v68, 0x3b2aaaab, v76
	v_mul_f32_e32 v69, 0x4b800000, v68
	v_cmp_gt_f32_e32 vcc, s56, v68
	s_nop 1
	v_cndmask_b32_e32 v68, v68, v69, vcc
	v_rsq_f32_e32 v68, v68
	s_nop 0
	v_mul_f32_e32 v69, 0x45800000, v68
	v_cndmask_b32_e32 v63, v68, v69, vcc
	s_waitcnt vmcnt(47)
	v_lshlrev_b32_e32 v244, 16, v244
	v_add_f32_e32 v244, v195, v244
	v_mul_f32_e32 v68, 0xbfb8aa3b, v244
	v_exp_f32_e32 v68, v68
	v_mul_f32_e32 v13, v13, v63
	v_add_f32_e32 v68, 1.0, v68
	v_div_scale_f32 v69, s[0:1], v68, v68, v244
	v_div_scale_f32 v71, vcc, v244, v68, v244
	v_rcp_f32_e32 v70, v69
	v_mul_f32_e32 v13, v198, v13
	v_fma_f32 v50, -v69, v70, 1.0
	v_fmac_f32_e32 v70, v50, v70
	v_mul_f32_e32 v50, v71, v70
	v_fma_f32 v51, -v69, v50, v71
	v_fmac_f32_e32 v50, v51, v70
	v_fma_f32 v69, -v69, v50, v71
	v_div_fmas_f32 v69, v69, v70, v50
	v_div_fixup_f32 v244, v69, v68, v244
	v_mul_f32_e32 v13, v244, v13
	s_waitcnt vmcnt(46)
	v_lshlrev_b32_e32 v245, 16, v245
	v_add_f32_e32 v245, v196, v245
	v_mul_f32_e32 v68, 0xbfb8aa3b, v245
	v_exp_f32_e32 v68, v68
	v_mul_f32_e32 v29, v29, v63
	v_add_f32_e32 v68, 1.0, v68
	v_div_scale_f32 v69, s[0:1], v68, v68, v245
	v_div_scale_f32 v71, vcc, v245, v68, v245
	v_rcp_f32_e32 v70, v69
	v_mul_f32_e32 v29, v199, v29
	v_fma_f32 v50, -v69, v70, 1.0
	v_fmac_f32_e32 v70, v50, v70
	v_mul_f32_e32 v50, v71, v70
	v_fma_f32 v51, -v69, v50, v71
	v_fmac_f32_e32 v50, v51, v70
	v_fma_f32 v69, -v69, v50, v71
	v_div_fmas_f32 v69, v69, v70, v50
	v_div_fixup_f32 v245, v69, v68, v245
	v_mul_f32_e32 v29, v245, v29
	s_waitcnt vmcnt(45)
	v_lshlrev_b32_e32 v246, 16, v246
	v_add_f32_e32 v246, v197, v246
	v_mul_f32_e32 v68, 0xbfb8aa3b, v246
	v_exp_f32_e32 v68, v68
	v_mul_f32_e32 v45, v45, v63
	v_add_f32_e32 v68, 1.0, v68
	v_div_scale_f32 v69, s[0:1], v68, v68, v246
	v_div_scale_f32 v71, vcc, v246, v68, v246
	v_rcp_f32_e32 v70, v69
	v_mul_f32_e32 v45, v200, v45
	v_fma_f32 v50, -v69, v70, 1.0
	v_fmac_f32_e32 v70, v50, v70
	v_mul_f32_e32 v50, v71, v70
	v_fma_f32 v51, -v69, v50, v71
	v_fmac_f32_e32 v50, v51, v70
	v_fma_f32 v69, -v69, v50, v71
	v_div_fmas_f32 v69, v69, v70, v50
	v_div_fixup_f32 v246, v69, v68, v246
	v_mul_f32_e32 v45, v246, v45
	s_nop 1
	v_mov_b32_dpp v68, v13 quad_perm:[1,0,3,2] row_mask:0xf bank_mask:0xf
	v_mov_b32_dpp v69, v29 quad_perm:[1,0,3,2] row_mask:0xf bank_mask:0xf
	v_mov_b32_dpp v70, v45 quad_perm:[1,0,3,2] row_mask:0xf bank_mask:0xf
	s_nop 0
	v_cvt_pk_bf16_f32 v13, v13, v68
	v_cvt_pk_bf16_f32 v29, v29, v69
	v_cvt_pk_bf16_f32 v45, v45, v70
	s_mov_b64 exec, s[98:99]
	global_store_dword v202, v13, s[38:39]
	global_store_dword v202, v29, s[38:39] offset:256
	global_store_dword v202, v45, s[38:39] offset:512
	s_mov_b64 exec, -1
	v_add_u32_e32 v202, 0x1000, v202
	s_waitcnt lgkmcnt(0)
	v_add_f32_e32 v68, v64, v65
	v_add_f32_e32 v69, v66, v67
	ds_read_b128 v[64:67], v203 offset:432
	v_add_f32_e32 v68, v68, v69
	v_fmamk_f32 v68, v68, 0x3b2aaaab, v76
	v_mul_f32_e32 v69, 0x4b800000, v68
	v_cmp_gt_f32_e32 vcc, s56, v68
	s_nop 1
	v_cndmask_b32_e32 v68, v68, v69, vcc
	v_rsq_f32_e32 v68, v68
	s_nop 0
	v_mul_f32_e32 v69, 0x45800000, v68
	v_cndmask_b32_e32 v63, v68, v69, vcc
	s_waitcnt vmcnt(47)
	v_lshlrev_b32_e32 v247, 16, v247
	v_add_f32_e32 v247, v195, v247
	v_mul_f32_e32 v68, 0xbfb8aa3b, v247
	v_exp_f32_e32 v68, v68
	v_mul_f32_e32 v14, v14, v63
	v_add_f32_e32 v68, 1.0, v68
	v_div_scale_f32 v69, s[0:1], v68, v68, v247
	v_div_scale_f32 v71, vcc, v247, v68, v247
	v_rcp_f32_e32 v70, v69
	v_mul_f32_e32 v14, v198, v14
	v_fma_f32 v50, -v69, v70, 1.0
	v_fmac_f32_e32 v70, v50, v70
	v_mul_f32_e32 v50, v71, v70
	v_fma_f32 v51, -v69, v50, v71
	v_fmac_f32_e32 v50, v51, v70
	v_fma_f32 v69, -v69, v50, v71
	v_div_fmas_f32 v69, v69, v70, v50
	v_div_fixup_f32 v247, v69, v68, v247
	v_mul_f32_e32 v14, v247, v14
	s_waitcnt vmcnt(46)
	v_lshlrev_b32_e32 v248, 16, v248
	v_add_f32_e32 v248, v196, v248
	v_mul_f32_e32 v68, 0xbfb8aa3b, v248
	v_exp_f32_e32 v68, v68
	v_mul_f32_e32 v30, v30, v63
	v_add_f32_e32 v68, 1.0, v68
	v_div_scale_f32 v69, s[0:1], v68, v68, v248
	v_div_scale_f32 v71, vcc, v248, v68, v248
	v_rcp_f32_e32 v70, v69
	v_mul_f32_e32 v30, v199, v30
	v_fma_f32 v50, -v69, v70, 1.0
	v_fmac_f32_e32 v70, v50, v70
	v_mul_f32_e32 v50, v71, v70
	v_fma_f32 v51, -v69, v50, v71
	v_fmac_f32_e32 v50, v51, v70
	v_fma_f32 v69, -v69, v50, v71
	v_div_fmas_f32 v69, v69, v70, v50
	v_div_fixup_f32 v248, v69, v68, v248
	v_mul_f32_e32 v30, v248, v30
	s_waitcnt vmcnt(45)
	v_lshlrev_b32_e32 v249, 16, v249
	v_add_f32_e32 v249, v197, v249
	v_mul_f32_e32 v68, 0xbfb8aa3b, v249
	v_exp_f32_e32 v68, v68
	v_mul_f32_e32 v46, v46, v63
	v_add_f32_e32 v68, 1.0, v68
	v_div_scale_f32 v69, s[0:1], v68, v68, v249
	v_div_scale_f32 v71, vcc, v249, v68, v249
	v_rcp_f32_e32 v70, v69
	v_mul_f32_e32 v46, v200, v46
	v_fma_f32 v50, -v69, v70, 1.0
	v_fmac_f32_e32 v70, v50, v70
	v_mul_f32_e32 v50, v71, v70
	v_fma_f32 v51, -v69, v50, v71
	v_fmac_f32_e32 v50, v51, v70
	v_fma_f32 v69, -v69, v50, v71
	v_div_fmas_f32 v69, v69, v70, v50
	v_div_fixup_f32 v249, v69, v68, v249
	v_mul_f32_e32 v46, v249, v46
	s_nop 1
	v_mov_b32_dpp v68, v14 quad_perm:[1,0,3,2] row_mask:0xf bank_mask:0xf
	v_mov_b32_dpp v69, v30 quad_perm:[1,0,3,2] row_mask:0xf bank_mask:0xf
	v_mov_b32_dpp v70, v46 quad_perm:[1,0,3,2] row_mask:0xf bank_mask:0xf
	s_nop 0
	v_cvt_pk_bf16_f32 v14, v14, v68
	v_cvt_pk_bf16_f32 v30, v30, v69
	v_cvt_pk_bf16_f32 v46, v46, v70
	s_mov_b64 exec, s[98:99]
	global_store_dword v202, v14, s[38:39]
	global_store_dword v202, v30, s[38:39] offset:256
	global_store_dword v202, v46, s[38:39] offset:512
	s_mov_b64 exec, -1
	v_add_u32_e32 v202, 0x1000, v202
	s_waitcnt lgkmcnt(0)
	v_add_f32_e32 v68, v64, v65
	v_add_f32_e32 v69, v66, v67
	v_add_f32_e32 v68, v68, v69
	v_fmamk_f32 v68, v68, 0x3b2aaaab, v76
	v_mul_f32_e32 v69, 0x4b800000, v68
	v_cmp_gt_f32_e32 vcc, s56, v68
	s_nop 1
	v_cndmask_b32_e32 v68, v68, v69, vcc
	v_rsq_f32_e32 v68, v68
	s_nop 0
	v_mul_f32_e32 v69, 0x45800000, v68
	v_cndmask_b32_e32 v63, v68, v69, vcc
	s_waitcnt vmcnt(47)
	v_lshlrev_b32_e32 v250, 16, v250
	v_add_f32_e32 v250, v195, v250
	v_mul_f32_e32 v68, 0xbfb8aa3b, v250
	v_exp_f32_e32 v68, v68
	v_mul_f32_e32 v15, v15, v63
	v_add_f32_e32 v68, 1.0, v68
	v_div_scale_f32 v69, s[0:1], v68, v68, v250
	v_div_scale_f32 v71, vcc, v250, v68, v250
	v_rcp_f32_e32 v70, v69
	v_mul_f32_e32 v15, v198, v15
	v_fma_f32 v50, -v69, v70, 1.0
	v_fmac_f32_e32 v70, v50, v70
	v_mul_f32_e32 v50, v71, v70
	v_fma_f32 v51, -v69, v50, v71
	v_fmac_f32_e32 v50, v51, v70
	v_fma_f32 v69, -v69, v50, v71
	v_div_fmas_f32 v69, v69, v70, v50
	v_div_fixup_f32 v250, v69, v68, v250
	v_mul_f32_e32 v15, v250, v15
	s_waitcnt vmcnt(46)
	v_lshlrev_b32_e32 v251, 16, v251
	v_add_f32_e32 v251, v196, v251
	v_mul_f32_e32 v68, 0xbfb8aa3b, v251
	v_exp_f32_e32 v68, v68
	v_mul_f32_e32 v31, v31, v63
	v_add_f32_e32 v68, 1.0, v68
	v_div_scale_f32 v69, s[0:1], v68, v68, v251
	v_div_scale_f32 v71, vcc, v251, v68, v251
	v_rcp_f32_e32 v70, v69
	v_mul_f32_e32 v31, v199, v31
	v_fma_f32 v50, -v69, v70, 1.0
	v_fmac_f32_e32 v70, v50, v70
	v_mul_f32_e32 v50, v71, v70
	v_fma_f32 v51, -v69, v50, v71
	v_fmac_f32_e32 v50, v51, v70
	v_fma_f32 v69, -v69, v50, v71
	v_div_fmas_f32 v69, v69, v70, v50
	v_div_fixup_f32 v251, v69, v68, v251
	v_mul_f32_e32 v31, v251, v31
	s_waitcnt vmcnt(45)
	v_lshlrev_b32_e32 v194, 16, v194
	v_add_f32_e32 v194, v197, v194
	v_mul_f32_e32 v68, 0xbfb8aa3b, v194
	v_exp_f32_e32 v68, v68
	v_mul_f32_e32 v47, v47, v63
	v_add_f32_e32 v68, 1.0, v68
	v_div_scale_f32 v69, s[0:1], v68, v68, v194
	v_div_scale_f32 v71, vcc, v194, v68, v194
	v_rcp_f32_e32 v70, v69
	v_mul_f32_e32 v47, v200, v47
	v_fma_f32 v50, -v69, v70, 1.0
	v_fmac_f32_e32 v70, v50, v70
	v_mul_f32_e32 v50, v71, v70
	v_fma_f32 v51, -v69, v50, v71
	v_fmac_f32_e32 v50, v51, v70
	v_fma_f32 v69, -v69, v50, v71
	v_div_fmas_f32 v69, v69, v70, v50
	v_div_fixup_f32 v194, v69, v68, v194
	v_mul_f32_e32 v47, v194, v47
	s_nop 1
	v_mov_b32_dpp v68, v15 quad_perm:[1,0,3,2] row_mask:0xf bank_mask:0xf
	v_mov_b32_dpp v69, v31 quad_perm:[1,0,3,2] row_mask:0xf bank_mask:0xf
	v_mov_b32_dpp v70, v47 quad_perm:[1,0,3,2] row_mask:0xf bank_mask:0xf
	s_nop 0
	v_cvt_pk_bf16_f32 v15, v15, v68
	v_cvt_pk_bf16_f32 v31, v31, v69
	v_cvt_pk_bf16_f32 v47, v47, v70
	s_mov_b64 exec, s[98:99]
	global_store_dword v202, v15, s[38:39]
	global_store_dword v202, v31, s[38:39] offset:256
	global_store_dword v202, v47, s[38:39] offset:512
	s_mov_b64 exec, -1
	s_branch .LBB0_4791

.LBB0_5096:
	s_andn2_b64 vcc, exec, s[22:23]
	s_cbranch_vccnz .LBB0_5087
	ds_read_b128 v[2:5], v235 offset:32768
	ds_read_b128 v[98:101], v229
	ds_read_b128 v[102:105], v229 offset:32
	ds_read_b128 v[106:109], v229 offset:64
	ds_read_b128 v[110:113], v229 offset:96
	ds_read_b128 v[82:85], v229 offset:128
	ds_read_b128 v[6:9], v235 offset:40960
	ds_read_b128 v[86:89], v229 offset:160
	ds_read_b128 v[90:93], v229 offset:192
	ds_read_b128 v[94:97], v229 offset:224
	s_add_i32 s20, s26, 63
	s_waitcnt lgkmcnt(5)
	v_mfma_f32_32x32x16_bf16 v[98:113], v[2:5], v[114:117], v[98:113]
	ds_read_b128 v[2:5], v236 offset:32768
	s_cmp_le_i32 s20, s27
	s_waitcnt lgkmcnt(1)
	v_mfma_f32_32x32x16_bf16 v[82:97], v[6:9], v[114:117], v[82:97]
	s_waitcnt lgkmcnt(0)
	v_mfma_f32_32x32x16_bf16 v[98:113], v[2:5], v[118:121], v[98:113]
	ds_read_b128 v[2:5], v236 offset:40960
	ds_read_b128 v[6:9], v237 offset:32768
	ds_read_b128 v[10:13], v237 offset:40960
	ds_read_b128 v[240:243], v238 offset:32768
	s_waitcnt lgkmcnt(3)
	v_mfma_f32_32x32x16_bf16 v[82:97], v[2:5], v[118:121], v[82:97]
	ds_read_b128 v[2:5], v238 offset:40960
	s_waitcnt lgkmcnt(3)
	v_mfma_f32_32x32x16_bf16 v[98:113], v[6:9], v[122:125], v[98:113]
	ds_read_b128 v[6:9], v235 offset:32896
	s_waitcnt lgkmcnt(3)
	v_mfma_f32_32x32x16_bf16 v[82:97], v[10:13], v[122:125], v[82:97]
	ds_read_b128 v[10:13], v235 offset:41088
	s_waitcnt lgkmcnt(3)
	v_mfma_f32_32x32x16_bf16 v[98:113], v[240:243], v[126:129], v[98:113]
	ds_read_b128 v[240:243], v236 offset:32896
	s_waitcnt lgkmcnt(3)
	v_mfma_f32_32x32x16_bf16 v[82:97], v[2:5], v[126:129], v[82:97]
	ds_read_b128 v[2:5], v236 offset:41088
	s_waitcnt lgkmcnt(3)
	v_mfma_f32_32x32x16_bf16 v[98:113], v[6:9], v[130:133], v[98:113]
	ds_read_b128 v[6:9], v237 offset:32896
	s_waitcnt lgkmcnt(3)
	v_mfma_f32_32x32x16_bf16 v[82:97], v[10:13], v[130:133], v[82:97]
	ds_read_b128 v[10:13], v237 offset:41088
	s_waitcnt lgkmcnt(3)
	v_mfma_f32_32x32x16_bf16 v[98:113], v[240:243], v[134:137], v[98:113]
	ds_read_b128 v[240:243], v238 offset:32896
	s_waitcnt lgkmcnt(3)
	v_mfma_f32_32x32x16_bf16 v[82:97], v[2:5], v[134:137], v[82:97]
	ds_read_b128 v[2:5], v238 offset:41088
	s_waitcnt lgkmcnt(3)
	v_mfma_f32_32x32x16_bf16 v[98:113], v[6:9], v[138:141], v[98:113]
	s_waitcnt lgkmcnt(2)
	v_mfma_f32_32x32x16_bf16 v[82:97], v[10:13], v[138:141], v[82:97]
	s_waitcnt lgkmcnt(1)
	v_mfma_f32_32x32x16_bf16 v[98:113], v[240:243], v[142:145], v[98:113]
	s_waitcnt lgkmcnt(0)
	v_mfma_f32_32x32x16_bf16 v[82:97], v[2:5], v[142:145], v[82:97]
	s_cbranch_scc1 .LBB0_5099
	v_add_u32_e32 v0, 0x4000003b, v230
	v_cmp_gt_u32_e32 vcc, 2.0, v0
	v_add_u32_e32 v0, 27, v230
	s_nop 4
	v_cndmask_b32_e32 v98, v205, v98, vcc
	v_cmp_lt_u32_e32 vcc, s84, v0
	v_add_u32_e32 v0, 58, v230
	s_nop 0
	v_cndmask_b32_e32 v82, v205, v82, vcc
	v_cmp_lt_u32_e32 vcc, s84, v0
	v_add_u32_e32 v0, 26, v230
	s_nop 0
	v_cndmask_b32_e32 v99, v205, v99, vcc
	v_cmp_lt_u32_e32 vcc, s84, v0
	v_add_u32_e32 v0, 57, v230
	s_nop 0
	v_cndmask_b32_e32 v83, v205, v83, vcc
	v_cmp_lt_u32_e32 vcc, s84, v0
	v_add_u32_e32 v0, 25, v230
	s_nop 0
	v_cndmask_b32_e32 v100, v205, v100, vcc
	v_cmp_lt_u32_e32 vcc, s84, v0
	v_add_u32_e32 v0, 56, v230
	s_nop 0
	v_cndmask_b32_e32 v84, v205, v84, vcc
	v_cmp_lt_u32_e32 vcc, s84, v0
	v_add_u32_e32 v0, 24, v230
	s_nop 0
	v_cndmask_b32_e32 v101, v205, v101, vcc
	v_cmp_lt_u32_e32 vcc, s84, v0
	v_add_u32_e32 v0, 51, v230
	s_nop 0
	v_cndmask_b32_e32 v85, v205, v85, vcc
	v_cmp_lt_u32_e32 vcc, s84, v0
	v_add_u32_e32 v0, 19, v230
	s_nop 0
	v_cndmask_b32_e32 v102, v205, v102, vcc
	v_cmp_lt_u32_e32 vcc, s84, v0
	v_add_u32_e32 v0, 50, v230
	s_nop 0
	v_cndmask_b32_e32 v86, v205, v86, vcc
	v_cmp_lt_u32_e32 vcc, s84, v0
	v_add_u32_e32 v0, 18, v230
	s_nop 0
	v_cndmask_b32_e32 v103, v205, v103, vcc
	v_cmp_lt_u32_e32 vcc, s84, v0
	v_add_u32_e32 v0, 49, v230
	s_nop 0
	v_cndmask_b32_e32 v87, v205, v87, vcc
	v_cmp_lt_u32_e32 vcc, s84, v0
	v_add_u32_e32 v0, 17, v230
	s_nop 0
	v_cndmask_b32_e32 v104, v205, v104, vcc
	v_cmp_lt_u32_e32 vcc, s84, v0
	v_add_u32_e32 v0, 48, v230
	s_nop 0
	v_cndmask_b32_e32 v88, v205, v88, vcc
	v_cmp_lt_u32_e32 vcc, s84, v0
	v_add_u32_e32 v0, 16, v230
	s_nop 0
	v_cndmask_b32_e32 v105, v205, v105, vcc
	v_cmp_lt_u32_e32 vcc, s84, v0
	v_add_u32_e32 v0, 43, v230
	s_nop 0
	v_cndmask_b32_e32 v89, v205, v89, vcc
	v_cmp_lt_u32_e32 vcc, s84, v0
	v_add_u32_e32 v0, 11, v230
	s_nop 0
	v_cndmask_b32_e32 v106, v205, v106, vcc
	v_cmp_lt_u32_e32 vcc, s84, v0
	v_add_u32_e32 v0, 42, v230
	s_nop 0
	v_cndmask_b32_e32 v90, v205, v90, vcc
	v_cmp_lt_u32_e32 vcc, s84, v0
	v_add_u32_e32 v0, 10, v230
	s_nop 0
	v_cndmask_b32_e32 v107, v205, v107, vcc
	v_cmp_lt_u32_e32 vcc, s84, v0
	v_add_u32_e32 v0, 41, v230
	s_nop 0
	v_cndmask_b32_e32 v91, v205, v91, vcc
	v_cmp_lt_u32_e32 vcc, s84, v0
	v_add_u32_e32 v0, 9, v230
	s_nop 0
	v_cndmask_b32_e32 v108, v205, v108, vcc
	v_cmp_lt_u32_e32 vcc, s84, v0
	v_add_u32_e32 v0, 40, v230
	s_nop 0
	v_cndmask_b32_e32 v92, v205, v92, vcc
	v_cmp_lt_u32_e32 vcc, s84, v0
	v_add_u32_e32 v0, 8, v230
	s_nop 0
	v_cndmask_b32_e32 v109, v205, v109, vcc
	v_cmp_lt_u32_e32 vcc, s84, v0
	v_add_u32_e32 v0, 35, v230
	s_nop 0
	v_cndmask_b32_e32 v93, v205, v93, vcc
	v_cmp_lt_u32_e32 vcc, s84, v0
	v_add_u32_e32 v0, 3, v230
	s_nop 0
	v_cndmask_b32_e32 v110, v205, v110, vcc
	v_cmp_lt_u32_e32 vcc, s84, v0
	v_add_u32_e32 v0, 34, v230
	s_nop 0
	v_cndmask_b32_e32 v94, v205, v94, vcc
	v_cmp_lt_u32_e32 vcc, s84, v0
	v_add_u32_e32 v0, 2, v230
	s_nop 0
	v_cndmask_b32_e32 v111, v205, v111, vcc
	v_cmp_lt_u32_e32 vcc, s84, v0
	v_add_u32_e32 v0, 33, v230
	s_nop 0
	v_cndmask_b32_e32 v95, v205, v95, vcc
	v_cmp_lt_u32_e32 vcc, s84, v0
	v_add_u32_e32 v0, 1, v230
	s_nop 0
	v_cndmask_b32_e32 v112, v205, v112, vcc
	v_cmp_lt_u32_e32 vcc, s84, v0
	v_add_u32_e32 v0, 32, v230
	s_nop 0
	v_cndmask_b32_e32 v96, v205, v96, vcc
	v_cmp_lt_u32_e32 vcc, s84, v0
	s_nop 1
	v_cndmask_b32_e32 v113, v205, v113, vcc
	v_cmp_lt_u32_e32 vcc, s84, v230
	s_nop 1
	v_cndmask_b32_e32 v97, v205, v97, vcc

.LBB0_5416:
	s_ashr_i32 s23, s39, 1
	s_and_b32 s74, s23, 0xffffffe0
	s_cmpk_lt_i32 s74, 0x100
	s_cselect_b64 s[20:21], -1, 0
	s_lshl_b32 s40, s6, 15
	s_add_i32 s27, s40, 0
	v_bfe_u32 v49, v210, 5, 1
	s_add_i32 s27, s27, 0x10800
	v_and_b32_e32 v211, 31, v210
	v_lshl_add_u32 v221, v49, 4, s27
	s_cmpk_gt_i32 s74, 0xff
	v_lshlrev_b32_e32 v198, 4, v49
	s_cbranch_scc1 .LBB0_5418
	v_lshlrev_b32_e32 v11, 4, v211
	v_lshlrev_b32_e32 v10, 8, v211
	v_bitop3_b32 v2, v198, v11, s5 bitop3:0x78
	v_add3_u32 v12, 0, v2, v10
	v_lshl_add_u32 v1, s38, 2, v221
	ds_read_b128 v[2:5], v12 offset:32768
	ds_read_b128 v[32:35], v1
	ds_read_b128 v[36:39], v1 offset:32
	ds_read_b128 v[40:43], v1 offset:64
	ds_read_b128 v[44:47], v1 offset:96
	ds_read_b128 v[16:19], v1 offset:128
	ds_read_b128 v[6:9], v12 offset:40960
	ds_read_b128 v[20:23], v1 offset:160
	ds_read_b128 v[24:27], v1 offset:192
	ds_read_b128 v[28:31], v1 offset:224
	v_and_b32_e32 v1, 0x70, v11
	s_waitcnt vmcnt(7) lgkmcnt(5)
	v_mfma_f32_32x32x16_bf16 v[32:47], v[2:5], v[172:175], v[32:47]
	v_bitop3_b32 v2, v198, v1, 32 bitop3:0x36
	v_add3_u32 v11, 0, v2, v10
	ds_read_b128 v[2:5], v11 offset:32768
	s_waitcnt lgkmcnt(1)
	v_mfma_f32_32x32x16_bf16 v[16:31], v[6:9], v[172:175], v[16:31]
	v_bitop3_b32 v6, v198, v1, 64 bitop3:0x36
	v_add3_u32 v6, 0, v6, v10
	v_bitop3_b32 v1, v198, v1, s94 bitop3:0x36
	v_add3_u32 v1, 0, v1, v10
	s_waitcnt vmcnt(6) lgkmcnt(0)
	v_mfma_f32_32x32x16_bf16 v[32:47], v[2:5], v[168:171], v[32:47]
	ds_read_b128 v[2:5], v11 offset:40960
	ds_read_b128 v[50:53], v6 offset:32768
	ds_read_b128 v[54:57], v6 offset:40960
	ds_read_b128 v[58:61], v1 offset:32768
	s_waitcnt lgkmcnt(3)
	v_mfma_f32_32x32x16_bf16 v[16:31], v[2:5], v[168:171], v[16:31]
	ds_read_b128 v[2:5], v1 offset:40960
	s_waitcnt vmcnt(5) lgkmcnt(3)
	v_mfma_f32_32x32x16_bf16 v[32:47], v[50:53], v[164:167], v[32:47]
	ds_read_b128 v[50:53], v12 offset:32896
	s_waitcnt lgkmcnt(3)
	v_mfma_f32_32x32x16_bf16 v[16:31], v[54:57], v[164:167], v[16:31]
	ds_read_b128 v[54:57], v12 offset:41088
	s_waitcnt vmcnt(4) lgkmcnt(3)
	v_mfma_f32_32x32x16_bf16 v[32:47], v[58:61], v[160:163], v[32:47]
	ds_read_b128 v[58:61], v11 offset:32896
	s_waitcnt lgkmcnt(3)
	v_mfma_f32_32x32x16_bf16 v[16:31], v[2:5], v[160:163], v[16:31]
	ds_read_b128 v[2:5], v11 offset:41088
	s_waitcnt vmcnt(3) lgkmcnt(3)
	v_mfma_f32_32x32x16_bf16 v[32:47], v[50:53], v[156:159], v[32:47]
	ds_read_b128 v[50:53], v6 offset:32896
	s_waitcnt lgkmcnt(3)
	v_mfma_f32_32x32x16_bf16 v[16:31], v[54:57], v[156:159], v[16:31]
	ds_read_b128 v[54:57], v6 offset:41088
	s_waitcnt vmcnt(2) lgkmcnt(3)
	v_mfma_f32_32x32x16_bf16 v[32:47], v[58:61], v[152:155], v[32:47]
	ds_read_b128 v[58:61], v1 offset:32896
	s_waitcnt lgkmcnt(3)
	v_mfma_f32_32x32x16_bf16 v[16:31], v[2:5], v[152:155], v[16:31]
	ds_read_b128 v[2:5], v1 offset:41088
	s_waitcnt vmcnt(1) lgkmcnt(3)
	v_mfma_f32_32x32x16_bf16 v[32:47], v[50:53], v[148:151], v[32:47]
	s_waitcnt lgkmcnt(2)
	v_mfma_f32_32x32x16_bf16 v[16:31], v[54:57], v[148:151], v[16:31]
	s_waitcnt vmcnt(0) lgkmcnt(1)
	v_mfma_f32_32x32x16_bf16 v[32:47], v[58:61], v[144:147], v[32:47]
	s_waitcnt lgkmcnt(0)
	v_mfma_f32_32x32x16_bf16 v[16:31], v[2:5], v[144:147], v[16:31]
	s_branch .LBB0_5419

.LBB0_5453:
	s_bitcmp0_b32 s28, 0
	s_cselect_b64 s[0:1], -1, 0
	v_cndmask_b32_e64 v1, 0, 1, s[20:21]
	s_and_b64 vcc, exec, s[0:1]
	v_cmp_ne_u32_e64 s[36:37], 1, v1
	s_cbranch_vccz .LBB0_5458
	s_and_b64 vcc, exec, s[36:37]
	s_cbranch_vccnz .LBB0_5456
	v_lshl_add_u32 v1, s22, 8, v221
	v_add_u32_e32 v2, 0xffffff00, v1
	v_add_u32_e32 v6, 0xffffff40, v1
	v_subrev_u32_e32 v13, 64, v1
	v_add_u32_e32 v3, 0xffffff80, v1
	ds_read_b128 v[80:83], v2
	ds_read_b128 v[96:99], v3
	ds_read_b128 v[88:91], v6
	ds_read_b128 v[104:107], v13
	v_add_u32_e32 v6, 0xffffff60, v1
	v_add_u32_e32 v2, 0xffffff20, v1
	v_lshlrev_b32_e32 v11, 4, v211
	ds_read_b128 v[92:95], v6
	v_add_u32_e32 v6, 0xffffffa0, v1
	v_subrev_u32_e32 v1, 32, v1
	ds_read_b128 v[84:87], v2
	ds_read_b128 v[108:111], v1
	v_lshlrev_b32_e32 v10, 8, v211
	v_bitop3_b32 v2, v198, v11, s5 bitop3:0x78
	v_add3_u32 v12, 0, v2, v10
	ds_read_b128 v[2:5], v12 offset:49152
	v_and_b32_e32 v1, 0x70, v11
	s_waitcnt vmcnt(7) lgkmcnt(0)
	v_mfma_f32_32x32x16_bf16 v[80:95], v[2:5], v[172:175], v[80:95]
	v_bitop3_b32 v2, v198, v1, 32 bitop3:0x36
	v_add3_u32 v11, 0, v2, v10
	ds_read_b128 v[100:103], v6
	ds_read_b128 v[2:5], v11 offset:49152
	ds_read_b128 v[6:9], v12 offset:57344
	s_waitcnt vmcnt(6) lgkmcnt(1)
	v_mfma_f32_32x32x16_bf16 v[80:95], v[2:5], v[168:171], v[80:95]
	ds_read_b128 v[2:5], v11 offset:57344
	s_waitcnt lgkmcnt(1)
	v_mfma_f32_32x32x16_bf16 v[96:111], v[6:9], v[172:175], v[96:111]
	v_bitop3_b32 v6, v198, v1, 64 bitop3:0x36
	v_add3_u32 v6, 0, v6, v10
	v_bitop3_b32 v1, v198, v1, s94 bitop3:0x36
	v_add3_u32 v1, 0, v1, v10
	s_waitcnt lgkmcnt(0)
	v_mfma_f32_32x32x16_bf16 v[96:111], v[2:5], v[168:171], v[96:111]
	ds_read_b128 v[2:5], v6 offset:49152
	ds_read_b128 v[112:115], v6 offset:57344
	ds_read_b128 v[116:119], v1 offset:49152
	ds_read_b128 v[120:123], v1 offset:57344
	s_waitcnt vmcnt(5) lgkmcnt(3)
	v_mfma_f32_32x32x16_bf16 v[80:95], v[2:5], v[164:167], v[80:95]
	ds_read_b128 v[2:5], v12 offset:49280
	s_waitcnt lgkmcnt(3)
	v_mfma_f32_32x32x16_bf16 v[96:111], v[112:115], v[164:167], v[96:111]
	ds_read_b128 v[112:115], v12 offset:57472
	s_waitcnt vmcnt(4) lgkmcnt(3)
	v_mfma_f32_32x32x16_bf16 v[80:95], v[116:119], v[160:163], v[80:95]
	ds_read_b128 v[116:119], v11 offset:49280
	s_waitcnt lgkmcnt(3)
	v_mfma_f32_32x32x16_bf16 v[96:111], v[120:123], v[160:163], v[96:111]
	ds_read_b128 v[120:123], v11 offset:57472
	s_waitcnt vmcnt(3) lgkmcnt(3)
	v_mfma_f32_32x32x16_bf16 v[80:95], v[2:5], v[156:159], v[80:95]
	ds_read_b128 v[2:5], v6 offset:49280
	s_waitcnt lgkmcnt(3)
	v_mfma_f32_32x32x16_bf16 v[96:111], v[112:115], v[156:159], v[96:111]
	ds_read_b128 v[112:115], v6 offset:57472
	s_waitcnt vmcnt(2) lgkmcnt(3)
	v_mfma_f32_32x32x16_bf16 v[80:95], v[116:119], v[152:155], v[80:95]
	ds_read_b128 v[116:119], v1 offset:49280
	s_waitcnt lgkmcnt(3)
	v_mfma_f32_32x32x16_bf16 v[96:111], v[120:123], v[152:155], v[96:111]
	ds_read_b128 v[120:123], v1 offset:57472
	s_waitcnt vmcnt(1) lgkmcnt(3)
	v_mfma_f32_32x32x16_bf16 v[80:95], v[2:5], v[148:151], v[80:95]
	s_waitcnt lgkmcnt(2)
	v_mfma_f32_32x32x16_bf16 v[96:111], v[112:115], v[148:151], v[96:111]
	s_waitcnt vmcnt(0) lgkmcnt(1)
	v_mfma_f32_32x32x16_bf16 v[80:95], v[116:119], v[144:147], v[80:95]
	s_waitcnt lgkmcnt(0)
	v_mfma_f32_32x32x16_bf16 v[96:111], v[120:123], v[144:147], v[96:111]
	s_branch .LBB0_5457

.LBB0_6742:
	s_andn2_b64 vcc, exec, s[20:21]
	s_cbranch_vccnz .LBB0_6733
	ds_read_b128 v[2:5], v236 offset:32768
	ds_read_b128 v[98:101], v230
	ds_read_b128 v[102:105], v230 offset:32
	ds_read_b128 v[106:109], v230 offset:64
	ds_read_b128 v[110:113], v230 offset:96
	ds_read_b128 v[82:85], v230 offset:128
	ds_read_b128 v[6:9], v236 offset:40960
	ds_read_b128 v[86:89], v230 offset:160
	ds_read_b128 v[90:93], v230 offset:192
	ds_read_b128 v[94:97], v230 offset:224
	s_add_i32 s26, s10, 63
	s_waitcnt lgkmcnt(5)
	v_mfma_f32_32x32x16_bf16 v[98:113], v[2:5], v[114:117], v[98:113]
	ds_read_b128 v[2:5], v237 offset:32768
	s_cmp_le_i32 s26, s11
	s_waitcnt lgkmcnt(1)
	v_mfma_f32_32x32x16_bf16 v[82:97], v[6:9], v[114:117], v[82:97]
	s_waitcnt lgkmcnt(0)
	v_mfma_f32_32x32x16_bf16 v[98:113], v[2:5], v[118:121], v[98:113]
	ds_read_b128 v[2:5], v237 offset:40960
	ds_read_b128 v[6:9], v238 offset:32768
	ds_read_b128 v[10:13], v238 offset:40960
	ds_read_b128 v[240:243], v239 offset:32768
	s_waitcnt lgkmcnt(3)
	v_mfma_f32_32x32x16_bf16 v[82:97], v[2:5], v[118:121], v[82:97]
	ds_read_b128 v[2:5], v239 offset:40960
	s_waitcnt lgkmcnt(3)
	v_mfma_f32_32x32x16_bf16 v[98:113], v[6:9], v[122:125], v[98:113]
	ds_read_b128 v[6:9], v236 offset:32896
	s_waitcnt lgkmcnt(3)
	v_mfma_f32_32x32x16_bf16 v[82:97], v[10:13], v[122:125], v[82:97]
	ds_read_b128 v[10:13], v236 offset:41088
	s_waitcnt lgkmcnt(3)
	v_mfma_f32_32x32x16_bf16 v[98:113], v[240:243], v[126:129], v[98:113]
	ds_read_b128 v[240:243], v237 offset:32896
	s_waitcnt lgkmcnt(3)
	v_mfma_f32_32x32x16_bf16 v[82:97], v[2:5], v[126:129], v[82:97]
	ds_read_b128 v[2:5], v237 offset:41088
	s_waitcnt lgkmcnt(3)
	v_mfma_f32_32x32x16_bf16 v[98:113], v[6:9], v[130:133], v[98:113]
	ds_read_b128 v[6:9], v238 offset:32896
	s_waitcnt lgkmcnt(3)
	v_mfma_f32_32x32x16_bf16 v[82:97], v[10:13], v[130:133], v[82:97]
	ds_read_b128 v[10:13], v238 offset:41088
	s_waitcnt lgkmcnt(3)
	v_mfma_f32_32x32x16_bf16 v[98:113], v[240:243], v[134:137], v[98:113]
	ds_read_b128 v[240:243], v239 offset:32896
	s_waitcnt lgkmcnt(3)
	v_mfma_f32_32x32x16_bf16 v[82:97], v[2:5], v[134:137], v[82:97]
	ds_read_b128 v[2:5], v239 offset:41088
	s_waitcnt lgkmcnt(3)
	v_mfma_f32_32x32x16_bf16 v[98:113], v[6:9], v[138:141], v[98:113]
	s_waitcnt lgkmcnt(2)
	v_mfma_f32_32x32x16_bf16 v[82:97], v[10:13], v[138:141], v[82:97]
	s_waitcnt lgkmcnt(1)
	v_mfma_f32_32x32x16_bf16 v[98:113], v[240:243], v[142:145], v[98:113]
	s_waitcnt lgkmcnt(0)
	v_mfma_f32_32x32x16_bf16 v[82:97], v[2:5], v[142:145], v[82:97]
	s_cbranch_scc1 .LBB0_6745
	v_add_u32_e32 v0, 0x4000003b, v231
	v_cmp_gt_u32_e32 vcc, 2.0, v0
	v_add_u32_e32 v0, 27, v231
	s_nop 4
	v_cndmask_b32_e32 v98, v206, v98, vcc
	v_cmp_lt_u32_e32 vcc, s7, v0
	v_add_u32_e32 v0, 58, v231
	s_nop 0
	v_cndmask_b32_e32 v82, v206, v82, vcc
	v_cmp_lt_u32_e32 vcc, s7, v0
	v_add_u32_e32 v0, 26, v231
	s_nop 0
	v_cndmask_b32_e32 v99, v206, v99, vcc
	v_cmp_lt_u32_e32 vcc, s7, v0
	v_add_u32_e32 v0, 57, v231
	s_nop 0
	v_cndmask_b32_e32 v83, v206, v83, vcc
	v_cmp_lt_u32_e32 vcc, s7, v0
	v_add_u32_e32 v0, 25, v231
	s_nop 0
	v_cndmask_b32_e32 v100, v206, v100, vcc
	v_cmp_lt_u32_e32 vcc, s7, v0
	v_add_u32_e32 v0, 56, v231
	s_nop 0
	v_cndmask_b32_e32 v84, v206, v84, vcc
	v_cmp_lt_u32_e32 vcc, s7, v0
	v_add_u32_e32 v0, 24, v231
	s_nop 0
	v_cndmask_b32_e32 v101, v206, v101, vcc
	v_cmp_lt_u32_e32 vcc, s7, v0
	v_add_u32_e32 v0, 51, v231
	s_nop 0
	v_cndmask_b32_e32 v85, v206, v85, vcc
	v_cmp_lt_u32_e32 vcc, s7, v0
	v_add_u32_e32 v0, 19, v231
	s_nop 0
	v_cndmask_b32_e32 v102, v206, v102, vcc
	v_cmp_lt_u32_e32 vcc, s7, v0
	v_add_u32_e32 v0, 50, v231
	s_nop 0
	v_cndmask_b32_e32 v86, v206, v86, vcc
	v_cmp_lt_u32_e32 vcc, s7, v0
	v_add_u32_e32 v0, 18, v231
	s_nop 0
	v_cndmask_b32_e32 v103, v206, v103, vcc
	v_cmp_lt_u32_e32 vcc, s7, v0
	v_add_u32_e32 v0, 49, v231
	s_nop 0
	v_cndmask_b32_e32 v87, v206, v87, vcc
	v_cmp_lt_u32_e32 vcc, s7, v0
	v_add_u32_e32 v0, 17, v231
	s_nop 0
	v_cndmask_b32_e32 v104, v206, v104, vcc
	v_cmp_lt_u32_e32 vcc, s7, v0
	v_add_u32_e32 v0, 48, v231
	s_nop 0
	v_cndmask_b32_e32 v88, v206, v88, vcc
	v_cmp_lt_u32_e32 vcc, s7, v0
	v_add_u32_e32 v0, 16, v231
	s_nop 0
	v_cndmask_b32_e32 v105, v206, v105, vcc
	v_cmp_lt_u32_e32 vcc, s7, v0
	v_add_u32_e32 v0, 43, v231
	s_nop 0
	v_cndmask_b32_e32 v89, v206, v89, vcc
	v_cmp_lt_u32_e32 vcc, s7, v0
	v_add_u32_e32 v0, 11, v231
	s_nop 0
	v_cndmask_b32_e32 v106, v206, v106, vcc
	v_cmp_lt_u32_e32 vcc, s7, v0
	v_add_u32_e32 v0, 42, v231
	s_nop 0
	v_cndmask_b32_e32 v90, v206, v90, vcc
	v_cmp_lt_u32_e32 vcc, s7, v0
	v_add_u32_e32 v0, 10, v231
	s_nop 0
	v_cndmask_b32_e32 v107, v206, v107, vcc
	v_cmp_lt_u32_e32 vcc, s7, v0
	v_add_u32_e32 v0, 41, v231
	s_nop 0
	v_cndmask_b32_e32 v91, v206, v91, vcc
	v_cmp_lt_u32_e32 vcc, s7, v0
	v_add_u32_e32 v0, 9, v231
	s_nop 0
	v_cndmask_b32_e32 v108, v206, v108, vcc
	v_cmp_lt_u32_e32 vcc, s7, v0
	v_add_u32_e32 v0, 40, v231
	s_nop 0
	v_cndmask_b32_e32 v92, v206, v92, vcc
	v_cmp_lt_u32_e32 vcc, s7, v0
	v_add_u32_e32 v0, 8, v231
	s_nop 0
	v_cndmask_b32_e32 v109, v206, v109, vcc
	v_cmp_lt_u32_e32 vcc, s7, v0
	v_add_u32_e32 v0, 35, v231
	s_nop 0
	v_cndmask_b32_e32 v93, v206, v93, vcc
	v_cmp_lt_u32_e32 vcc, s7, v0
	v_add_u32_e32 v0, 3, v231
	s_nop 0
	v_cndmask_b32_e32 v110, v206, v110, vcc
	v_cmp_lt_u32_e32 vcc, s7, v0
	v_add_u32_e32 v0, 34, v231
	s_nop 0
	v_cndmask_b32_e32 v94, v206, v94, vcc
	v_cmp_lt_u32_e32 vcc, s7, v0
	v_add_u32_e32 v0, 2, v231
	s_nop 0
	v_cndmask_b32_e32 v111, v206, v111, vcc
	v_cmp_lt_u32_e32 vcc, s7, v0
	v_add_u32_e32 v0, 33, v231
	s_nop 0
	v_cndmask_b32_e32 v95, v206, v95, vcc
	v_cmp_lt_u32_e32 vcc, s7, v0
	v_add_u32_e32 v0, 1, v231
	s_nop 0
	v_cndmask_b32_e32 v112, v206, v112, vcc
	v_cmp_lt_u32_e32 vcc, s7, v0
	v_add_u32_e32 v0, 32, v231
	s_nop 0
	v_cndmask_b32_e32 v96, v206, v96, vcc
	v_cmp_lt_u32_e32 vcc, s7, v0
	s_nop 1
	v_cndmask_b32_e32 v113, v206, v113, vcc
	v_cmp_lt_u32_e32 vcc, s7, v231
	s_nop 1
	v_cndmask_b32_e32 v97, v206, v97, vcc

.LBB0_7244:
	s_ashr_i32 s20, s28, 1
	s_and_b32 s76, s20, 0xffffffe0
	s_cmp_lt_i32 s76, s85
	s_cselect_b64 s[20:21], -1, 0
	s_lshl_b32 s39, s30, 15
	s_add_i32 s26, s39, 0
	v_bfe_u32 v49, v210, 5, 1
	s_add_i32 s26, s26, 0x10800
	v_and_b32_e32 v211, 31, v210
	v_lshl_add_u32 v221, v49, 4, s26
	s_cmp_ge_i32 s76, s85
	v_lshlrev_b32_e32 v198, 4, v49
	s_cbranch_scc1 .LBB0_7246
	v_lshlrev_b32_e32 v11, 4, v211
	v_lshlrev_b32_e32 v10, 8, v211
	v_bitop3_b32 v2, v198, v11, s4 bitop3:0x78
	v_add3_u32 v12, 0, v2, v10
	v_lshl_add_u32 v1, s38, 2, v221
	ds_read_b128 v[2:5], v12 offset:32768
	ds_read_b128 v[32:35], v1
	ds_read_b128 v[36:39], v1 offset:32
	ds_read_b128 v[40:43], v1 offset:64
	ds_read_b128 v[44:47], v1 offset:96
	ds_read_b128 v[16:19], v1 offset:128
	ds_read_b128 v[6:9], v12 offset:40960
	ds_read_b128 v[20:23], v1 offset:160
	ds_read_b128 v[24:27], v1 offset:192
	ds_read_b128 v[28:31], v1 offset:224
	v_and_b32_e32 v1, 0x70, v11
	s_waitcnt vmcnt(7) lgkmcnt(5)
	v_mfma_f32_32x32x16_bf16 v[32:47], v[2:5], v[172:175], v[32:47]
	v_bitop3_b32 v2, v198, v1, 32 bitop3:0x36
	v_add3_u32 v11, 0, v2, v10
	ds_read_b128 v[2:5], v11 offset:32768
	s_waitcnt lgkmcnt(1)
	v_mfma_f32_32x32x16_bf16 v[16:31], v[6:9], v[172:175], v[16:31]
	v_bitop3_b32 v6, v198, v1, 64 bitop3:0x36
	v_add3_u32 v6, 0, v6, v10
	v_bitop3_b32 v1, v198, v1, s9 bitop3:0x36
	v_add3_u32 v1, 0, v1, v10
	s_waitcnt vmcnt(6) lgkmcnt(0)
	v_mfma_f32_32x32x16_bf16 v[32:47], v[2:5], v[168:171], v[32:47]
	ds_read_b128 v[2:5], v11 offset:40960
	ds_read_b128 v[50:53], v6 offset:32768
	ds_read_b128 v[54:57], v6 offset:40960
	ds_read_b128 v[58:61], v1 offset:32768
	s_waitcnt lgkmcnt(3)
	v_mfma_f32_32x32x16_bf16 v[16:31], v[2:5], v[168:171], v[16:31]
	ds_read_b128 v[2:5], v1 offset:40960
	s_waitcnt vmcnt(5) lgkmcnt(3)
	v_mfma_f32_32x32x16_bf16 v[32:47], v[50:53], v[164:167], v[32:47]
	ds_read_b128 v[50:53], v12 offset:32896
	s_waitcnt lgkmcnt(3)
	v_mfma_f32_32x32x16_bf16 v[16:31], v[54:57], v[164:167], v[16:31]
	ds_read_b128 v[54:57], v12 offset:41088
	s_waitcnt vmcnt(4) lgkmcnt(3)
	v_mfma_f32_32x32x16_bf16 v[32:47], v[58:61], v[160:163], v[32:47]
	ds_read_b128 v[58:61], v11 offset:32896
	s_waitcnt lgkmcnt(3)
	v_mfma_f32_32x32x16_bf16 v[16:31], v[2:5], v[160:163], v[16:31]
	ds_read_b128 v[2:5], v11 offset:41088
	s_waitcnt vmcnt(3) lgkmcnt(3)
	v_mfma_f32_32x32x16_bf16 v[32:47], v[50:53], v[156:159], v[32:47]
	ds_read_b128 v[50:53], v6 offset:32896
	s_waitcnt lgkmcnt(3)
	v_mfma_f32_32x32x16_bf16 v[16:31], v[54:57], v[156:159], v[16:31]
	ds_read_b128 v[54:57], v6 offset:41088
	s_waitcnt vmcnt(2) lgkmcnt(3)
	v_mfma_f32_32x32x16_bf16 v[32:47], v[58:61], v[152:155], v[32:47]
	ds_read_b128 v[58:61], v1 offset:32896
	s_waitcnt lgkmcnt(3)
	v_mfma_f32_32x32x16_bf16 v[16:31], v[2:5], v[152:155], v[16:31]
	ds_read_b128 v[2:5], v1 offset:41088
	s_waitcnt vmcnt(1) lgkmcnt(3)
	v_mfma_f32_32x32x16_bf16 v[32:47], v[50:53], v[148:151], v[32:47]
	s_waitcnt lgkmcnt(2)
	v_mfma_f32_32x32x16_bf16 v[16:31], v[54:57], v[148:151], v[16:31]
	s_waitcnt vmcnt(0) lgkmcnt(1)
	v_mfma_f32_32x32x16_bf16 v[32:47], v[58:61], v[144:147], v[32:47]
	s_waitcnt lgkmcnt(0)
	v_mfma_f32_32x32x16_bf16 v[16:31], v[2:5], v[144:147], v[16:31]
	s_branch .LBB0_7247

.LBB0_7281:
	s_bitcmp0_b32 s27, 0
	s_cselect_b64 s[0:1], -1, 0
	v_cndmask_b32_e64 v1, 0, 1, s[20:21]
	s_and_b64 vcc, exec, s[0:1]
	v_cmp_ne_u32_e64 s[36:37], 1, v1
	s_cbranch_vccz .LBB0_7286
	s_and_b64 vcc, exec, s[36:37]
	s_cbranch_vccnz .LBB0_7284
	v_lshl_add_u32 v1, s22, 8, v221
	v_add_u32_e32 v2, 0xffffff00, v1
	v_add_u32_e32 v6, 0xffffff40, v1
	v_subrev_u32_e32 v13, 64, v1
	v_add_u32_e32 v3, 0xffffff80, v1
	ds_read_b128 v[80:83], v2
	ds_read_b128 v[96:99], v3
	ds_read_b128 v[88:91], v6
	ds_read_b128 v[104:107], v13
	v_add_u32_e32 v6, 0xffffff60, v1
	v_add_u32_e32 v2, 0xffffff20, v1
	v_lshlrev_b32_e32 v11, 4, v211
	ds_read_b128 v[92:95], v6
	v_add_u32_e32 v6, 0xffffffa0, v1
	v_subrev_u32_e32 v1, 32, v1
	ds_read_b128 v[84:87], v2
	ds_read_b128 v[108:111], v1
	v_lshlrev_b32_e32 v10, 8, v211
	v_bitop3_b32 v2, v198, v11, s4 bitop3:0x78
	v_add3_u32 v12, 0, v2, v10
	ds_read_b128 v[2:5], v12 offset:49152
	v_and_b32_e32 v1, 0x70, v11
	s_waitcnt vmcnt(7) lgkmcnt(0)
	v_mfma_f32_32x32x16_bf16 v[80:95], v[2:5], v[172:175], v[80:95]
	v_bitop3_b32 v2, v198, v1, 32 bitop3:0x36
	v_add3_u32 v11, 0, v2, v10
	ds_read_b128 v[100:103], v6
	ds_read_b128 v[2:5], v11 offset:49152
	ds_read_b128 v[6:9], v12 offset:57344
	s_waitcnt vmcnt(6) lgkmcnt(1)
	v_mfma_f32_32x32x16_bf16 v[80:95], v[2:5], v[168:171], v[80:95]
	ds_read_b128 v[2:5], v11 offset:57344
	s_waitcnt lgkmcnt(1)
	v_mfma_f32_32x32x16_bf16 v[96:111], v[6:9], v[172:175], v[96:111]
	v_bitop3_b32 v6, v198, v1, 64 bitop3:0x36
	v_add3_u32 v6, 0, v6, v10
	v_bitop3_b32 v1, v198, v1, s9 bitop3:0x36
	v_add3_u32 v1, 0, v1, v10
	s_waitcnt lgkmcnt(0)
	v_mfma_f32_32x32x16_bf16 v[96:111], v[2:5], v[168:171], v[96:111]
	ds_read_b128 v[2:5], v6 offset:49152
	ds_read_b128 v[112:115], v6 offset:57344
	ds_read_b128 v[116:119], v1 offset:49152
	ds_read_b128 v[120:123], v1 offset:57344
	s_waitcnt vmcnt(5) lgkmcnt(3)
	v_mfma_f32_32x32x16_bf16 v[80:95], v[2:5], v[164:167], v[80:95]
	ds_read_b128 v[2:5], v12 offset:49280
	s_waitcnt lgkmcnt(3)
	v_mfma_f32_32x32x16_bf16 v[96:111], v[112:115], v[164:167], v[96:111]
	ds_read_b128 v[112:115], v12 offset:57472
	s_waitcnt vmcnt(4) lgkmcnt(3)
	v_mfma_f32_32x32x16_bf16 v[80:95], v[116:119], v[160:163], v[80:95]
	ds_read_b128 v[116:119], v11 offset:49280
	s_waitcnt lgkmcnt(3)
	v_mfma_f32_32x32x16_bf16 v[96:111], v[120:123], v[160:163], v[96:111]
	ds_read_b128 v[120:123], v11 offset:57472
	s_waitcnt vmcnt(3) lgkmcnt(3)
	v_mfma_f32_32x32x16_bf16 v[80:95], v[2:5], v[156:159], v[80:95]
	ds_read_b128 v[2:5], v6 offset:49280
	s_waitcnt lgkmcnt(3)
	v_mfma_f32_32x32x16_bf16 v[96:111], v[112:115], v[156:159], v[96:111]
	ds_read_b128 v[112:115], v6 offset:57472
	s_waitcnt vmcnt(2) lgkmcnt(3)
	v_mfma_f32_32x32x16_bf16 v[80:95], v[116:119], v[152:155], v[80:95]
	ds_read_b128 v[116:119], v1 offset:49280
	s_waitcnt lgkmcnt(3)
	v_mfma_f32_32x32x16_bf16 v[96:111], v[120:123], v[152:155], v[96:111]
	ds_read_b128 v[120:123], v1 offset:57472
	s_waitcnt vmcnt(1) lgkmcnt(3)
	v_mfma_f32_32x32x16_bf16 v[80:95], v[2:5], v[148:151], v[80:95]
	s_waitcnt lgkmcnt(2)
	v_mfma_f32_32x32x16_bf16 v[96:111], v[112:115], v[148:151], v[96:111]
	s_waitcnt vmcnt(0) lgkmcnt(1)
	v_mfma_f32_32x32x16_bf16 v[80:95], v[116:119], v[144:147], v[80:95]
	s_waitcnt lgkmcnt(0)
	v_mfma_f32_32x32x16_bf16 v[96:111], v[120:123], v[144:147], v[96:111]
	s_branch .LBB0_7285
